# v28: v27 + removed every s_setprio around the MFMA groups of the GEMM K-loops (no priority switching in GEMMs)
# speedup vs baseline: 1.0035x; 1.0008x over previous
; #define PG8_STAGE(bufoff, gbase, voff) do { _Pragma("unroll") for (int _i = 0; _i < 2; ++_i) \
;         __builtin_amdgcn_global_load_lds((const unsigned*)((const char*)(gbase) + (voff)[_i]), (PG8_LAS unsigned*)(lds + (bufoff) + ldsw + _i * 8192), 16, 0, 0); } while (0)
; #define PG8_LDA(dst, b, h) do { _Pragma("unroll") for (int m = 0; m < 4; ++m) _Pragma("unroll") for (int k = 0; k < 2; ++k) dst[m][k] = *(const PG8_LAS bf16x8*)(lds + PG8_SA(b, h) + aoff + m * 2048 + k * 1024); } while (0)
; #define PG8_LDB(dst, b, h) do { _Pragma("unroll") for (int n = 0; n < 2; ++n) _Pragma("unroll") for (int k = 0; k < 2; ++k) dst[n][k] = *(const PG8_LAS bf16x8*)(lds + PG8_SB(b, h) + boff + n * 2048 + k * 1024); } while (0)
; #define PG8_MMA(ai, bj, At, Bt) do { __builtin_amdgcn_s_setprio(1); _Pragma("unroll") for (int m = 0; m < 4; ++m) _Pragma("unroll") for (int n = 0; n < 2; ++n) _Pragma("unroll") for (int k = 0; k < 2; ++k) \
;         acc[ai][bj][m][n] = __builtin_amdgcn_mfma_f32_16x16x32_bf16(Bt[n][k], At[m][k], acc[ai][bj][m][n], 0, 0, 0); __builtin_amdgcn_s_setprio(0); } while (0)
; #define PG8_WAIT_V(n) asm volatile("s_waitcnt vmcnt(" #n ")" ::: "memory")
; #define PG8_WAIT_L(n) asm volatile("s_waitcnt lgkmcnt(" #n ")" ::: "memory")
; #define PG8_BAR __builtin_amdgcn_s_barrier()
; #define PG8_SCHED __builtin_amdgcn_sched_barrier(0)
; template <class Epi, class Sched, bool ALIGN_EPI = false, bool SP2 = false>
; __device__ __forceinline__ void gemm_phase(PG8_LAS unsigned char* lds, const Gemm g, const Sched& S, const Epi& E) {
;     ...
;             const bool last = (t == nt - 2);
;             const char* a1 = cA + (size_t)(t + 1) * kstep;
;             const char* a2 = last ? nA : cA + (size_t)(t + 2) * kstep; const char* b2 = last ? nB : cB + (size_t)(t + 2) * kstep;
;             const char* a3 = a2 + kstep; const char* b3 = b2 + kstep;
;             if (last && has_next) S.a_ready(nxt);
;             if constexpr (SP2) {
;             PG8_LDB(B0, 0, 0); PG8_LDB(B1, 0, 1); PG8_SCHED; PG8_LDA(At, 0, 0); PG8_STAGE(PG8_SA(1, 1), a1 + hstep, voffA);
;             PG8_WAIT_V(8); PG8_WAIT_L(0); PG8_BAR; PG8_MMA(0, 0, At, B0); PG8_MMA(0, 1, At, B1); PG8_BAR; PG8_SCHED;
;             PG8_LDA(At, 0, 1); PG8_STAGE(PG8_SB(0, 0), b2, voffB); PG8_STAGE(PG8_SB(0, 1), b2 + hstep, voffB); PG8_STAGE(PG8_SA(0, 0), a2, voffA);
.LBB0_168:
	s_add_i32 s18, s6, 2
	s_add_u32 s19, s0, 0x80
	s_addc_u32 s7, s1, 0
	s_add_i32 s28, 0, 0x10000
	s_cmp_eq_u32 s79, s6
	s_cselect_b32 s7, s67, s7
	s_cselect_b32 s6, s66, s19
	s_cselect_b32 s25, s27, s9
	s_cselect_b32 s24, s26, s8
	s_add_i32 s19, 0, 0x14000
	v_add_u32_e32 v154, s28, v197
	v_add_u32_e32 v170, s19, v197
	ds_read_b128 v[142:145], v154
	ds_read_b128 v[146:149], v154 offset:1024
	ds_read_b128 v[150:153], v154 offset:2048
	ds_read_b128 v[154:157], v154 offset:3072
	ds_read_b128 v[158:161], v170
	ds_read_b128 v[162:165], v170 offset:1024
	ds_read_b128 v[166:169], v170 offset:2048
	ds_read_b128 v[170:173], v170 offset:3072
	v_lshl_add_u64 v[174:175], s[0:1], 0, v[136:137]
	s_add_i32 m0, s42, 0xc000
	ds_read_b128 v[186:189], v198
	ds_read_b128 v[190:193], v198 offset:1024
	ds_read_b128 v[200:203], v198 offset:2048
	ds_read_b128 v[204:207], v198 offset:3072
	ds_read_b128 v[208:211], v198 offset:4096
	ds_read_b128 v[212:215], v198 offset:5120
	ds_read_b128 v[216:219], v198 offset:6144
	ds_read_b128 v[220:223], v198 offset:7168
	global_load_lds_dwordx4 v[174:175], off
	v_lshl_add_u64 v[174:175], s[0:1], 0, v[138:139]
	s_add_i32 m0, s42, 0xe000
	s_nop 0
	global_load_lds_dwordx4 v[174:175], off
	s_waitcnt vmcnt(8)
	s_waitcnt lgkmcnt(0)
	s_barrier
	s_waitcnt lgkmcnt(0)
	v_mfma_f32_16x16x32_bf16 v[120:123], v[142:145], v[186:189], v[120:123]
	v_mfma_f32_16x16x32_bf16 v[124:127], v[150:153], v[186:189], v[124:127]
	v_mfma_f32_16x16x32_bf16 v[112:115], v[142:145], v[200:203], v[112:115]
	v_mfma_f32_16x16x32_bf16 v[116:119], v[150:153], v[200:203], v[116:119]
	v_mfma_f32_16x16x32_bf16 v[104:107], v[142:145], v[208:211], v[104:107]
	v_mfma_f32_16x16x32_bf16 v[108:111], v[150:153], v[208:211], v[108:111]
	v_mfma_f32_16x16x32_bf16 v[96:99], v[142:145], v[216:219], v[96:99]
	v_mfma_f32_16x16x32_bf16 v[100:103], v[150:153], v[216:219], v[100:103]
	v_mfma_f32_16x16x32_bf16 v[120:123], v[146:149], v[190:193], v[120:123]
	v_mfma_f32_16x16x32_bf16 v[124:127], v[154:157], v[190:193], v[124:127]
	v_mfma_f32_16x16x32_bf16 v[112:115], v[146:149], v[204:207], v[112:115]
	v_mfma_f32_16x16x32_bf16 v[116:119], v[154:157], v[204:207], v[116:119]
	v_mfma_f32_16x16x32_bf16 v[104:107], v[146:149], v[212:215], v[104:107]
	v_mfma_f32_16x16x32_bf16 v[108:111], v[154:157], v[212:215], v[108:111]
	v_mfma_f32_16x16x32_bf16 v[96:99], v[146:149], v[220:223], v[96:99]
	v_mfma_f32_16x16x32_bf16 v[100:103], v[154:157], v[220:223], v[100:103]
	v_mfma_f32_16x16x32_bf16 v[60:63], v[158:161], v[186:189], v[60:63]
	v_mfma_f32_16x16x32_bf16 v[56:59], v[166:169], v[186:189], v[56:59]
	v_mfma_f32_16x16x32_bf16 v[52:55], v[158:161], v[200:203], v[52:55]
	v_mfma_f32_16x16x32_bf16 v[48:51], v[166:169], v[200:203], v[48:51]
	v_mfma_f32_16x16x32_bf16 v[44:47], v[158:161], v[208:211], v[44:47]
	v_mfma_f32_16x16x32_bf16 v[40:43], v[166:169], v[208:211], v[40:43]
	v_mfma_f32_16x16x32_bf16 v[36:39], v[158:161], v[216:219], v[36:39]
	v_mfma_f32_16x16x32_bf16 v[32:35], v[166:169], v[216:219], v[32:35]
	v_mfma_f32_16x16x32_bf16 v[60:63], v[162:165], v[190:193], v[60:63]
	v_mfma_f32_16x16x32_bf16 v[56:59], v[170:173], v[190:193], v[56:59]
	v_mfma_f32_16x16x32_bf16 v[52:55], v[162:165], v[204:207], v[52:55]
	v_mfma_f32_16x16x32_bf16 v[48:51], v[170:173], v[204:207], v[48:51]
	v_mfma_f32_16x16x32_bf16 v[44:47], v[162:165], v[212:215], v[44:47]
	v_mfma_f32_16x16x32_bf16 v[40:43], v[170:173], v[212:215], v[40:43]
	v_mfma_f32_16x16x32_bf16 v[36:39], v[162:165], v[220:223], v[36:39]
	v_mfma_f32_16x16x32_bf16 v[32:35], v[170:173], v[220:223], v[32:35]
	s_barrier
	s_add_i32 s28, s28, s31
	v_lshl_add_u64 v[174:175], s[24:25], 0, v[130:131]
	s_mov_b32 m0, s28
	ds_read_b128 v[186:189], v198 offset:16384
	ds_read_b128 v[190:193], v198 offset:17408
	ds_read_b128 v[200:203], v198 offset:18432
	ds_read_b128 v[204:207], v198 offset:19456
	ds_read_b128 v[208:211], v198 offset:20480
	ds_read_b128 v[212:215], v198 offset:21504
	ds_read_b128 v[216:219], v198 offset:22528
	ds_read_b128 v[220:223], v198 offset:23552
	global_load_lds_dwordx4 v[174:175], off
	s_add_i32 m0, s28, 0x2000
	v_lshl_add_u64 v[182:183], s[24:25], 0, v[134:135]
	s_add_u32 s24, s24, s14
	s_addc_u32 s25, s25, s15
	s_add_i32 s19, s19, s31
	global_load_lds_dwordx4 v[182:183], off
	v_lshl_add_u64 v[184:185], s[24:25], 0, v[130:131]
	s_mov_b32 m0, s19
	v_lshl_add_u64 v[194:195], s[24:25], 0, v[134:135]
	global_load_lds_dwordx4 v[184:185], off
	s_add_i32 m0, s19, 0x2000
	v_lshl_add_u64 v[224:225], s[6:7], 0, v[128:129]
	global_load_lds_dwordx4 v[194:195], off
	s_mov_b32 m0, s42
	v_lshl_add_u64 v[226:227], s[6:7], 0, v[132:133]
	global_load_lds_dwordx4 v[224:225], off
	s_mov_b32 m0, s43
	s_nop 0
	global_load_lds_dwordx4 v[226:227], off
	s_waitcnt vmcnt(8)
	s_waitcnt lgkmcnt(0)
	s_barrier
; #define PG8_STAGE(bufoff, gbase, voff) do { _Pragma("unroll") for (int _i = 0; _i < 2; ++_i) \
;         __builtin_amdgcn_global_load_lds((const unsigned*)((const char*)(gbase) + (voff)[_i]), (PG8_LAS unsigned*)(lds + (bufoff) + ldsw + _i * 8192), 16, 0, 0); } while (0)
; #define PG8_LDA(dst, b, h) do { _Pragma("unroll") for (int m = 0; m < 4; ++m) _Pragma("unroll") for (int k = 0; k < 2; ++k) dst[m][k] = *(const PG8_LAS bf16x8*)(lds + PG8_SA(b, h) + aoff + m * 2048 + k * 1024); } while (0)
; #define PG8_LDB(dst, b, h) do { _Pragma("unroll") for (int n = 0; n < 2; ++n) _Pragma("unroll") for (int k = 0; k < 2; ++k) dst[n][k] = *(const PG8_LAS bf16x8*)(lds + PG8_SB(b, h) + boff + n * 2048 + k * 1024); } while (0)
; #define PG8_MMA(ai, bj, At, Bt) do { __builtin_amdgcn_s_setprio(1); _Pragma("unroll") for (int m = 0; m < 4; ++m) _Pragma("unroll") for (int n = 0; n < 2; ++n) _Pragma("unroll") for (int k = 0; k < 2; ++k) \
;         acc[ai][bj][m][n] = __builtin_amdgcn_mfma_f32_16x16x32_bf16(Bt[n][k], At[m][k], acc[ai][bj][m][n], 0, 0, 0); __builtin_amdgcn_s_setprio(0); } while (0)
; #define PG8_WAIT_V(n) asm volatile("s_waitcnt vmcnt(" #n ")" ::: "memory")
; #define PG8_WAIT_L(n) asm volatile("s_waitcnt lgkmcnt(" #n ")" ::: "memory")
; #define PG8_BAR __builtin_amdgcn_s_barrier()
; #define PG8_SCHED __builtin_amdgcn_sched_barrier(0)
; template <class Epi, class Sched, bool ALIGN_EPI = false, bool SP2 = false>
; __device__ __forceinline__ void gemm_phase(PG8_LAS unsigned char* lds, const Gemm g, const Sched& S, const Epi& E) {
;     ...
;             PG8_WAIT_V(8); PG8_WAIT_L(0); PG8_BAR; PG8_MMA(1, 0, At, B0); PG8_MMA(1, 1, At, B1); PG8_BAR; PG8_SCHED;
;             PG8_LDB(B0, 1, 0); PG8_LDB(B1, 1, 1); PG8_SCHED; PG8_LDA(At, 1, 0); PG8_STAGE(PG8_SA(0, 1), a2 + hstep, voffA);
;             PG8_WAIT_V(8); PG8_WAIT_L(0); PG8_BAR; PG8_MMA(0, 0, At, B0); PG8_MMA(0, 1, At, B1); PG8_BAR; PG8_SCHED;
	s_waitcnt lgkmcnt(0)
	v_mfma_f32_16x16x32_bf16 v[88:91], v[142:145], v[186:189], v[88:91]
	v_mfma_f32_16x16x32_bf16 v[92:95], v[150:153], v[186:189], v[92:95]
	v_mfma_f32_16x16x32_bf16 v[80:83], v[142:145], v[200:203], v[80:83]
	v_mfma_f32_16x16x32_bf16 v[84:87], v[150:153], v[200:203], v[84:87]
	v_mfma_f32_16x16x32_bf16 v[72:75], v[142:145], v[208:211], v[72:75]
	v_mfma_f32_16x16x32_bf16 v[76:79], v[150:153], v[208:211], v[76:79]
	v_mfma_f32_16x16x32_bf16 v[64:67], v[142:145], v[216:219], v[64:67]
	v_mfma_f32_16x16x32_bf16 v[68:71], v[150:153], v[216:219], v[68:71]
	v_mfma_f32_16x16x32_bf16 v[88:91], v[146:149], v[190:193], v[88:91]
	v_mfma_f32_16x16x32_bf16 v[92:95], v[154:157], v[190:193], v[92:95]
	v_mfma_f32_16x16x32_bf16 v[80:83], v[146:149], v[204:207], v[80:83]
	v_mfma_f32_16x16x32_bf16 v[84:87], v[154:157], v[204:207], v[84:87]
	v_mfma_f32_16x16x32_bf16 v[72:75], v[146:149], v[212:215], v[72:75]
	v_mfma_f32_16x16x32_bf16 v[76:79], v[154:157], v[212:215], v[76:79]
	v_mfma_f32_16x16x32_bf16 v[64:67], v[146:149], v[220:223], v[64:67]
	v_mfma_f32_16x16x32_bf16 v[68:71], v[154:157], v[220:223], v[68:71]
	v_mfma_f32_16x16x32_bf16 v[28:31], v[158:161], v[186:189], v[28:31]
	v_mfma_f32_16x16x32_bf16 v[24:27], v[166:169], v[186:189], v[24:27]
	v_mfma_f32_16x16x32_bf16 v[20:23], v[158:161], v[200:203], v[20:23]
	v_mfma_f32_16x16x32_bf16 v[16:19], v[166:169], v[200:203], v[16:19]
	v_mfma_f32_16x16x32_bf16 v[12:15], v[158:161], v[208:211], v[12:15]
	v_mfma_f32_16x16x32_bf16 v[8:11], v[166:169], v[208:211], v[8:11]
	v_mfma_f32_16x16x32_bf16 v[4:7], v[158:161], v[216:219], v[4:7]
	v_mfma_f32_16x16x32_bf16 v[0:3], v[166:169], v[216:219], v[0:3]
	v_mfma_f32_16x16x32_bf16 v[28:31], v[162:165], v[190:193], v[28:31]
	v_mfma_f32_16x16x32_bf16 v[24:27], v[170:173], v[190:193], v[24:27]
	v_mfma_f32_16x16x32_bf16 v[20:23], v[162:165], v[204:207], v[20:23]
	v_mfma_f32_16x16x32_bf16 v[16:19], v[170:173], v[204:207], v[16:19]
	v_mfma_f32_16x16x32_bf16 v[12:15], v[162:165], v[212:215], v[12:15]
	v_mfma_f32_16x16x32_bf16 v[8:11], v[170:173], v[212:215], v[8:11]
	v_mfma_f32_16x16x32_bf16 v[4:7], v[162:165], v[220:223], v[4:7]
	v_mfma_f32_16x16x32_bf16 v[0:3], v[170:173], v[220:223], v[0:3]
	s_barrier
	s_add_i32 s19, 0, 0x18000
	s_add_i32 s24, 0, 0x1c000
	v_add_u32_e32 v154, s19, v197
	v_add_u32_e32 v170, s24, v197
	ds_read_b128 v[142:145], v154
	ds_read_b128 v[146:149], v154 offset:1024
	ds_read_b128 v[150:153], v154 offset:2048
	ds_read_b128 v[154:157], v154 offset:3072
	ds_read_b128 v[158:161], v170
	ds_read_b128 v[162:165], v170 offset:1024
	ds_read_b128 v[166:169], v170 offset:2048
	ds_read_b128 v[170:173], v170 offset:3072
	s_add_u32 s6, s6, s14
	s_addc_u32 s7, s7, s15
	s_mov_b32 m0, s72
	v_lshl_add_u64 v[236:237], s[6:7], 0, v[128:129]
	ds_read_b128 v[186:189], v198 offset:32768
	ds_read_b128 v[190:193], v198 offset:33792
	ds_read_b128 v[200:203], v198 offset:34816
	ds_read_b128 v[204:207], v198 offset:35840
	ds_read_b128 v[208:211], v198 offset:36864
	ds_read_b128 v[212:215], v198 offset:37888
	ds_read_b128 v[216:219], v198 offset:38912
	ds_read_b128 v[220:223], v198 offset:39936
	global_load_lds_dwordx4 v[236:237], off
	v_lshl_add_u64 v[236:237], s[6:7], 0, v[132:133]
	s_mov_b32 m0, s73
	s_nop 0
	global_load_lds_dwordx4 v[236:237], off
	s_waitcnt vmcnt(8)
	s_waitcnt lgkmcnt(0)
	s_barrier
	s_waitcnt lgkmcnt(0)
	v_mfma_f32_16x16x32_bf16 v[120:123], v[142:145], v[186:189], v[120:123]
	v_mfma_f32_16x16x32_bf16 v[124:127], v[150:153], v[186:189], v[124:127]
	v_mfma_f32_16x16x32_bf16 v[112:115], v[142:145], v[200:203], v[112:115]
	v_mfma_f32_16x16x32_bf16 v[116:119], v[150:153], v[200:203], v[116:119]
	v_mfma_f32_16x16x32_bf16 v[104:107], v[142:145], v[208:211], v[104:107]
	v_mfma_f32_16x16x32_bf16 v[108:111], v[150:153], v[208:211], v[108:111]
	v_mfma_f32_16x16x32_bf16 v[96:99], v[142:145], v[216:219], v[96:99]
	v_mfma_f32_16x16x32_bf16 v[100:103], v[150:153], v[216:219], v[100:103]
	v_mfma_f32_16x16x32_bf16 v[120:123], v[146:149], v[190:193], v[120:123]
	v_mfma_f32_16x16x32_bf16 v[124:127], v[154:157], v[190:193], v[124:127]
	v_mfma_f32_16x16x32_bf16 v[112:115], v[146:149], v[204:207], v[112:115]
	v_mfma_f32_16x16x32_bf16 v[116:119], v[154:157], v[204:207], v[116:119]
	v_mfma_f32_16x16x32_bf16 v[104:107], v[146:149], v[212:215], v[104:107]
	v_mfma_f32_16x16x32_bf16 v[108:111], v[154:157], v[212:215], v[108:111]
	v_mfma_f32_16x16x32_bf16 v[96:99], v[146:149], v[220:223], v[96:99]
	v_mfma_f32_16x16x32_bf16 v[100:103], v[154:157], v[220:223], v[100:103]
	v_mfma_f32_16x16x32_bf16 v[60:63], v[158:161], v[186:189], v[60:63]
	v_mfma_f32_16x16x32_bf16 v[56:59], v[166:169], v[186:189], v[56:59]
	v_mfma_f32_16x16x32_bf16 v[52:55], v[158:161], v[200:203], v[52:55]
	v_mfma_f32_16x16x32_bf16 v[48:51], v[166:169], v[200:203], v[48:51]
	v_mfma_f32_16x16x32_bf16 v[44:47], v[158:161], v[208:211], v[44:47]
	v_mfma_f32_16x16x32_bf16 v[40:43], v[166:169], v[208:211], v[40:43]
	v_mfma_f32_16x16x32_bf16 v[36:39], v[158:161], v[216:219], v[36:39]
	v_mfma_f32_16x16x32_bf16 v[32:35], v[166:169], v[216:219], v[32:35]
	v_mfma_f32_16x16x32_bf16 v[60:63], v[162:165], v[190:193], v[60:63]
	v_mfma_f32_16x16x32_bf16 v[56:59], v[170:173], v[190:193], v[56:59]
	v_mfma_f32_16x16x32_bf16 v[52:55], v[162:165], v[204:207], v[52:55]
	v_mfma_f32_16x16x32_bf16 v[48:51], v[170:173], v[204:207], v[48:51]
	v_mfma_f32_16x16x32_bf16 v[44:47], v[162:165], v[212:215], v[44:47]
	v_mfma_f32_16x16x32_bf16 v[40:43], v[170:173], v[212:215], v[40:43]
	v_mfma_f32_16x16x32_bf16 v[36:39], v[162:165], v[220:223], v[36:39]
	v_mfma_f32_16x16x32_bf16 v[32:35], v[170:173], v[220:223], v[32:35]
	s_barrier
; #define PG8_STAGE(bufoff, gbase, voff) do { _Pragma("unroll") for (int _i = 0; _i < 2; ++_i) \
;         __builtin_amdgcn_global_load_lds((const unsigned*)((const char*)(gbase) + (voff)[_i]), (PG8_LAS unsigned*)(lds + (bufoff) + ldsw + _i * 8192), 16, 0, 0); } while (0)
; #define PG8_LDA(dst, b, h) do { _Pragma("unroll") for (int m = 0; m < 4; ++m) _Pragma("unroll") for (int k = 0; k < 2; ++k) dst[m][k] = *(const PG8_LAS bf16x8*)(lds + PG8_SA(b, h) + aoff + m * 2048 + k * 1024); } while (0)
; #define PG8_MMA(ai, bj, At, Bt) do { __builtin_amdgcn_s_setprio(1); _Pragma("unroll") for (int m = 0; m < 4; ++m) _Pragma("unroll") for (int n = 0; n < 2; ++n) _Pragma("unroll") for (int k = 0; k < 2; ++k) \
;         acc[ai][bj][m][n] = __builtin_amdgcn_mfma_f32_16x16x32_bf16(Bt[n][k], At[m][k], acc[ai][bj][m][n], 0, 0, 0); __builtin_amdgcn_s_setprio(0); } while (0)
; #define PG8_WAIT_V(n) asm volatile("s_waitcnt vmcnt(" #n ")" ::: "memory")
; #define PG8_WAIT_L(n) asm volatile("s_waitcnt lgkmcnt(" #n ")" ::: "memory")
; #define PG8_BAR __builtin_amdgcn_s_barrier()
; #define PG8_SCHED __builtin_amdgcn_sched_barrier(0)
; template <class Epi, class Sched, bool ALIGN_EPI = false, bool SP2 = false>
; __device__ __forceinline__ void gemm_phase(PG8_LAS unsigned char* lds, const Gemm g, const Sched& S, const Epi& E) {
;     ...
;             PG8_LDA(At, 1, 1); PG8_STAGE(PG8_SB(1, 0), b3, voffB); PG8_STAGE(PG8_SB(1, 1), b3 + hstep, voffB); PG8_STAGE(PG8_SA(1, 0), a3, voffA);
;             PG8_WAIT_V(8); PG8_WAIT_L(0); PG8_BAR; PG8_MMA(1, 0, At, B0); PG8_MMA(1, 1, At, B1); PG8_BAR; PG8_SCHED;
	s_add_i32 s6, s19, s31
	v_lshl_add_u64 v[174:175], v[174:175], 0, s[44:45]
	s_mov_b32 m0, s6
	ds_read_b128 v[186:189], v198 offset:49152
	ds_read_b128 v[190:193], v198 offset:50176
	ds_read_b128 v[200:203], v198 offset:51200
	ds_read_b128 v[204:207], v198 offset:52224
	ds_read_b128 v[208:211], v198 offset:53248
	ds_read_b128 v[212:215], v198 offset:54272
	ds_read_b128 v[216:219], v198 offset:55296
	ds_read_b128 v[220:223], v198 offset:56320
	global_load_lds_dwordx4 v[174:175], off
	v_lshl_add_u64 v[174:175], v[182:183], 0, s[44:45]
	s_add_i32 m0, s6, 0x2000
	s_add_i32 s6, s24, s31
	global_load_lds_dwordx4 v[174:175], off
	v_lshl_add_u64 v[174:175], v[184:185], 0, s[44:45]
	s_mov_b32 m0, s6
	s_nop 0
	global_load_lds_dwordx4 v[174:175], off
	v_lshl_add_u64 v[174:175], v[194:195], 0, s[44:45]
	s_add_i32 m0, s6, 0x2000
	s_nop 0
	global_load_lds_dwordx4 v[174:175], off
	v_lshl_add_u64 v[174:175], v[224:225], 0, s[44:45]
	s_mov_b32 m0, s74
	s_nop 0
	global_load_lds_dwordx4 v[174:175], off
	v_lshl_add_u64 v[174:175], v[226:227], 0, s[44:45]
	s_mov_b32 m0, s75
	s_nop 0
	global_load_lds_dwordx4 v[174:175], off
	s_waitcnt vmcnt(8)
	s_waitcnt lgkmcnt(0)
	s_barrier
	s_waitcnt lgkmcnt(0)
	v_mfma_f32_16x16x32_bf16 v[88:91], v[142:145], v[186:189], v[88:91]
	v_mfma_f32_16x16x32_bf16 v[92:95], v[150:153], v[186:189], v[92:95]
	v_mfma_f32_16x16x32_bf16 v[80:83], v[142:145], v[200:203], v[80:83]
	v_mfma_f32_16x16x32_bf16 v[84:87], v[150:153], v[200:203], v[84:87]
	v_mfma_f32_16x16x32_bf16 v[72:75], v[142:145], v[208:211], v[72:75]
	v_mfma_f32_16x16x32_bf16 v[76:79], v[150:153], v[208:211], v[76:79]
	v_mfma_f32_16x16x32_bf16 v[64:67], v[142:145], v[216:219], v[64:67]
	v_mfma_f32_16x16x32_bf16 v[68:71], v[150:153], v[216:219], v[68:71]
	v_mfma_f32_16x16x32_bf16 v[88:91], v[146:149], v[190:193], v[88:91]
	v_mfma_f32_16x16x32_bf16 v[92:95], v[154:157], v[190:193], v[92:95]
	v_mfma_f32_16x16x32_bf16 v[80:83], v[146:149], v[204:207], v[80:83]
	v_mfma_f32_16x16x32_bf16 v[84:87], v[154:157], v[204:207], v[84:87]
	v_mfma_f32_16x16x32_bf16 v[72:75], v[146:149], v[212:215], v[72:75]
	v_mfma_f32_16x16x32_bf16 v[76:79], v[154:157], v[212:215], v[76:79]
	v_mfma_f32_16x16x32_bf16 v[64:67], v[146:149], v[220:223], v[64:67]
	v_mfma_f32_16x16x32_bf16 v[68:71], v[154:157], v[220:223], v[68:71]
	v_mfma_f32_16x16x32_bf16 v[28:31], v[158:161], v[186:189], v[28:31]
	v_mfma_f32_16x16x32_bf16 v[24:27], v[166:169], v[186:189], v[24:27]
	v_mfma_f32_16x16x32_bf16 v[20:23], v[158:161], v[200:203], v[20:23]
	v_mfma_f32_16x16x32_bf16 v[16:19], v[166:169], v[200:203], v[16:19]
	v_mfma_f32_16x16x32_bf16 v[12:15], v[158:161], v[208:211], v[12:15]
	v_mfma_f32_16x16x32_bf16 v[8:11], v[166:169], v[208:211], v[8:11]
	v_mfma_f32_16x16x32_bf16 v[4:7], v[158:161], v[216:219], v[4:7]
	v_mfma_f32_16x16x32_bf16 v[0:3], v[166:169], v[216:219], v[0:3]
	v_mfma_f32_16x16x32_bf16 v[28:31], v[162:165], v[190:193], v[28:31]
	v_mfma_f32_16x16x32_bf16 v[24:27], v[170:173], v[190:193], v[24:27]
	s_add_u32 s0, s0, 0x100
	v_mfma_f32_16x16x32_bf16 v[20:23], v[162:165], v[204:207], v[20:23]
	s_addc_u32 s1, s1, 0
	v_mfma_f32_16x16x32_bf16 v[16:19], v[170:173], v[204:207], v[16:19]
	s_add_u32 s8, s8, 0x100
	v_mfma_f32_16x16x32_bf16 v[12:15], v[162:165], v[212:215], v[12:15]
	s_addc_u32 s9, s9, 0
	v_mfma_f32_16x16x32_bf16 v[8:11], v[170:173], v[212:215], v[8:11]
	s_cmp_ge_i32 s18, s76
	v_mfma_f32_16x16x32_bf16 v[4:7], v[162:165], v[220:223], v[4:7]
	s_mov_b32 s6, s18
	v_mfma_f32_16x16x32_bf16 v[0:3], v[170:173], v[220:223], v[0:3]
	s_barrier
	s_cbranch_scc0 .LBB0_168

; #define PG8_STAGE(bufoff, gbase, voff) do { _Pragma("unroll") for (int _i = 0; _i < 2; ++_i) \
;         __builtin_amdgcn_global_load_lds((const unsigned*)((const char*)(gbase) + (voff)[_i]), (PG8_LAS unsigned*)(lds + (bufoff) + ldsw + _i * 8192), 16, 0, 0); } while (0)
; #define PG8_LDA(dst, b, h) do { _Pragma("unroll") for (int m = 0; m < 4; ++m) _Pragma("unroll") for (int k = 0; k < 2; ++k) dst[m][k] = *(const PG8_LAS bf16x8*)(lds + PG8_SA(b, h) + aoff + m * 2048 + k * 1024); } while (0)
; #define PG8_LDB(dst, b, h) do { _Pragma("unroll") for (int n = 0; n < 2; ++n) _Pragma("unroll") for (int k = 0; k < 2; ++k) dst[n][k] = *(const PG8_LAS bf16x8*)(lds + PG8_SB(b, h) + boff + n * 2048 + k * 1024); } while (0)
; #define PG8_MMA(ai, bj, At, Bt) do { __builtin_amdgcn_s_setprio(1); _Pragma("unroll") for (int m = 0; m < 4; ++m) _Pragma("unroll") for (int n = 0; n < 2; ++n) _Pragma("unroll") for (int k = 0; k < 2; ++k) \
;         acc[ai][bj][m][n] = __builtin_amdgcn_mfma_f32_16x16x32_bf16(Bt[n][k], At[m][k], acc[ai][bj][m][n], 0, 0, 0); __builtin_amdgcn_s_setprio(0); } while (0)
; #define PG8_WAIT_V(n) asm volatile("s_waitcnt vmcnt(" #n ")" ::: "memory")
; #define PG8_WAIT_L(n) asm volatile("s_waitcnt lgkmcnt(" #n ")" ::: "memory")
; #define PG8_BAR __builtin_amdgcn_s_barrier()
; #define PG8_SCHED __builtin_amdgcn_sched_barrier(0)
; template <class Epi, class Sched, bool ALIGN_EPI = false, bool SP2 = false>
; __device__ __forceinline__ void gemm_phase(PG8_LAS unsigned char* lds, const Gemm g, const Sched& S, const Epi& E) {
;     ...
;             const bool last = (t == nt - 2);
;             const char* a1 = cA + (size_t)(t + 1) * kstep;
;             const char* a2 = last ? nA : cA + (size_t)(t + 2) * kstep; const char* b2 = last ? nB : cB + (size_t)(t + 2) * kstep;
;             const char* a3 = a2 + kstep; const char* b3 = b2 + kstep;
;             if (last && has_next) S.a_ready(nxt);
;             if constexpr (SP2) {
;             PG8_LDB(B0, 0, 0); PG8_LDB(B1, 0, 1); PG8_SCHED; PG8_LDA(At, 0, 0); PG8_STAGE(PG8_SA(1, 1), a1 + hstep, voffA);
;             PG8_WAIT_V(8); PG8_WAIT_L(0); PG8_BAR; PG8_MMA(0, 0, At, B0); PG8_MMA(0, 1, At, B1); PG8_BAR; PG8_SCHED;
;             PG8_LDA(At, 0, 1); PG8_STAGE(PG8_SB(0, 0), b2, voffB); PG8_STAGE(PG8_SB(0, 1), b2 + hstep, voffB); PG8_STAGE(PG8_SA(0, 0), a2, voffA);
.LBB0_375:
	s_add_i32 s80, s64, 2
	s_add_u32 s28, s40, 0x80
	s_addc_u32 s38, s41, 0
	s_add_i32 s48, 0, 0x10000
	s_cmp_eq_u32 s74, s64
	s_cselect_b32 s65, s5, s38
	s_cselect_b32 s64, s4, s28
	s_cselect_b32 s39, s37, s79
	s_cselect_b32 s38, s36, s78
	s_add_i32 s28, 0, 0x14000
	v_add_u32_e32 v154, s48, v140
	v_add_u32_e32 v170, s28, v140
	ds_read_b128 v[142:145], v154
	ds_read_b128 v[146:149], v154 offset:1024
	ds_read_b128 v[150:153], v154 offset:2048
	ds_read_b128 v[154:157], v154 offset:3072
	ds_read_b128 v[158:161], v170
	ds_read_b128 v[162:165], v170 offset:1024
	ds_read_b128 v[166:169], v170 offset:2048
	ds_read_b128 v[170:173], v170 offset:3072
	v_lshl_add_u64 v[174:175], s[40:41], 0, v[134:135]
	s_add_i32 m0, s43, 0xc000
	ds_read_b128 v[182:185], v141
	ds_read_b128 v[186:189], v141 offset:1024
	ds_read_b128 v[190:193], v141 offset:2048
	ds_read_b128 v[194:197], v141 offset:3072
	ds_read_b128 v[198:201], v141 offset:4096
	ds_read_b128 v[202:205], v141 offset:5120
	ds_read_b128 v[206:209], v141 offset:6144
	ds_read_b128 v[210:213], v141 offset:7168
	global_load_lds_dwordx4 v[174:175], off
	v_lshl_add_u64 v[174:175], s[40:41], 0, v[136:137]
	s_add_i32 m0, s43, 0xe000
	s_nop 0
	global_load_lds_dwordx4 v[174:175], off
	s_waitcnt vmcnt(8)
	s_waitcnt lgkmcnt(0)
	s_barrier
	s_waitcnt lgkmcnt(0)
	v_mfma_f32_16x16x32_bf16 v[120:123], v[142:145], v[182:185], v[120:123]
	v_mfma_f32_16x16x32_bf16 v[124:127], v[150:153], v[182:185], v[124:127]
	v_mfma_f32_16x16x32_bf16 v[108:111], v[142:145], v[190:193], v[108:111]
	v_mfma_f32_16x16x32_bf16 v[104:107], v[150:153], v[190:193], v[104:107]
	v_mfma_f32_16x16x32_bf16 v[92:95], v[142:145], v[198:201], v[92:95]
	v_mfma_f32_16x16x32_bf16 v[88:91], v[150:153], v[198:201], v[88:91]
	v_mfma_f32_16x16x32_bf16 v[76:79], v[142:145], v[206:209], v[76:79]
	v_mfma_f32_16x16x32_bf16 v[72:75], v[150:153], v[206:209], v[72:75]
	v_mfma_f32_16x16x32_bf16 v[120:123], v[146:149], v[186:189], v[120:123]
	v_mfma_f32_16x16x32_bf16 v[124:127], v[154:157], v[186:189], v[124:127]
	v_mfma_f32_16x16x32_bf16 v[108:111], v[146:149], v[194:197], v[108:111]
	v_mfma_f32_16x16x32_bf16 v[104:107], v[154:157], v[194:197], v[104:107]
	v_mfma_f32_16x16x32_bf16 v[92:95], v[146:149], v[202:205], v[92:95]
	v_mfma_f32_16x16x32_bf16 v[88:91], v[154:157], v[202:205], v[88:91]
	v_mfma_f32_16x16x32_bf16 v[76:79], v[146:149], v[210:213], v[76:79]
	v_mfma_f32_16x16x32_bf16 v[72:75], v[154:157], v[210:213], v[72:75]
	v_mfma_f32_16x16x32_bf16 v[116:119], v[158:161], v[182:185], v[116:119]
	v_mfma_f32_16x16x32_bf16 v[112:115], v[166:169], v[182:185], v[112:115]
	v_mfma_f32_16x16x32_bf16 v[100:103], v[158:161], v[190:193], v[100:103]
	v_mfma_f32_16x16x32_bf16 v[96:99], v[166:169], v[190:193], v[96:99]
	v_mfma_f32_16x16x32_bf16 v[84:87], v[158:161], v[198:201], v[84:87]
	v_mfma_f32_16x16x32_bf16 v[80:83], v[166:169], v[198:201], v[80:83]
	v_mfma_f32_16x16x32_bf16 v[68:71], v[158:161], v[206:209], v[68:71]
	v_mfma_f32_16x16x32_bf16 v[64:67], v[166:169], v[206:209], v[64:67]
	v_mfma_f32_16x16x32_bf16 v[116:119], v[162:165], v[186:189], v[116:119]
	v_mfma_f32_16x16x32_bf16 v[112:115], v[170:173], v[186:189], v[112:115]
	v_mfma_f32_16x16x32_bf16 v[100:103], v[162:165], v[194:197], v[100:103]
	v_mfma_f32_16x16x32_bf16 v[96:99], v[170:173], v[194:197], v[96:99]
	v_mfma_f32_16x16x32_bf16 v[84:87], v[162:165], v[202:205], v[84:87]
	v_mfma_f32_16x16x32_bf16 v[80:83], v[170:173], v[202:205], v[80:83]
	v_mfma_f32_16x16x32_bf16 v[68:71], v[162:165], v[210:213], v[68:71]
	v_mfma_f32_16x16x32_bf16 v[64:67], v[170:173], v[210:213], v[64:67]
	s_barrier
	s_add_i32 s48, s48, s24
	v_lshl_add_u64 v[174:175], s[38:39], 0, v[176:177]
	s_mov_b32 m0, s48
	ds_read_b128 v[182:185], v141 offset:16384
	ds_read_b128 v[186:189], v141 offset:17408
	ds_read_b128 v[190:193], v141 offset:18432
	ds_read_b128 v[194:197], v141 offset:19456
	ds_read_b128 v[198:201], v141 offset:20480
	ds_read_b128 v[202:205], v141 offset:21504
	ds_read_b128 v[206:209], v141 offset:22528
	ds_read_b128 v[210:213], v141 offset:23552
	global_load_lds_dwordx4 v[174:175], off
	s_add_i32 m0, s48, 0x2000
	v_lshl_add_u64 v[214:215], s[38:39], 0, v[132:133]
	s_add_u32 s38, s38, s10
	s_addc_u32 s39, s39, s11
	s_add_i32 s28, s28, s24
	global_load_lds_dwordx4 v[214:215], off
	v_lshl_add_u64 v[216:217], s[38:39], 0, v[176:177]
	s_mov_b32 m0, s28
	v_lshl_add_u64 v[218:219], s[38:39], 0, v[132:133]
	global_load_lds_dwordx4 v[216:217], off
	s_add_i32 m0, s28, 0x2000
	v_lshl_add_u64 v[220:221], s[64:65], 0, v[128:129]
	global_load_lds_dwordx4 v[218:219], off
	s_mov_b32 m0, s43
	v_lshl_add_u64 v[222:223], s[64:65], 0, v[130:131]
	global_load_lds_dwordx4 v[220:221], off
	s_mov_b32 m0, s46
	s_nop 0
	global_load_lds_dwordx4 v[222:223], off
	s_waitcnt vmcnt(8)
	s_waitcnt lgkmcnt(0)
	s_barrier
; #define PG8_STAGE(bufoff, gbase, voff) do { _Pragma("unroll") for (int _i = 0; _i < 2; ++_i) \
;         __builtin_amdgcn_global_load_lds((const unsigned*)((const char*)(gbase) + (voff)[_i]), (PG8_LAS unsigned*)(lds + (bufoff) + ldsw + _i * 8192), 16, 0, 0); } while (0)
; #define PG8_LDA(dst, b, h) do { _Pragma("unroll") for (int m = 0; m < 4; ++m) _Pragma("unroll") for (int k = 0; k < 2; ++k) dst[m][k] = *(const PG8_LAS bf16x8*)(lds + PG8_SA(b, h) + aoff + m * 2048 + k * 1024); } while (0)
; #define PG8_LDB(dst, b, h) do { _Pragma("unroll") for (int n = 0; n < 2; ++n) _Pragma("unroll") for (int k = 0; k < 2; ++k) dst[n][k] = *(const PG8_LAS bf16x8*)(lds + PG8_SB(b, h) + boff + n * 2048 + k * 1024); } while (0)
; #define PG8_MMA(ai, bj, At, Bt) do { __builtin_amdgcn_s_setprio(1); _Pragma("unroll") for (int m = 0; m < 4; ++m) _Pragma("unroll") for (int n = 0; n < 2; ++n) _Pragma("unroll") for (int k = 0; k < 2; ++k) \
;         acc[ai][bj][m][n] = __builtin_amdgcn_mfma_f32_16x16x32_bf16(Bt[n][k], At[m][k], acc[ai][bj][m][n], 0, 0, 0); __builtin_amdgcn_s_setprio(0); } while (0)
; #define PG8_WAIT_V(n) asm volatile("s_waitcnt vmcnt(" #n ")" ::: "memory")
; #define PG8_WAIT_L(n) asm volatile("s_waitcnt lgkmcnt(" #n ")" ::: "memory")
; #define PG8_BAR __builtin_amdgcn_s_barrier()
; #define PG8_SCHED __builtin_amdgcn_sched_barrier(0)
; template <class Epi, class Sched, bool ALIGN_EPI = false, bool SP2 = false>
; __device__ __forceinline__ void gemm_phase(PG8_LAS unsigned char* lds, const Gemm g, const Sched& S, const Epi& E) {
;     ...
;             PG8_WAIT_V(8); PG8_WAIT_L(0); PG8_BAR; PG8_MMA(1, 0, At, B0); PG8_MMA(1, 1, At, B1); PG8_BAR; PG8_SCHED;
;             PG8_LDB(B0, 1, 0); PG8_LDB(B1, 1, 1); PG8_SCHED; PG8_LDA(At, 1, 0); PG8_STAGE(PG8_SA(0, 1), a2 + hstep, voffA);
;             PG8_WAIT_V(8); PG8_WAIT_L(0); PG8_BAR; PG8_MMA(0, 0, At, B0); PG8_MMA(0, 1, At, B1); PG8_BAR; PG8_SCHED;
	s_waitcnt lgkmcnt(0)
	v_mfma_f32_16x16x32_bf16 v[60:63], v[142:145], v[182:185], v[60:63]
	v_mfma_f32_16x16x32_bf16 v[56:59], v[150:153], v[182:185], v[56:59]
	v_mfma_f32_16x16x32_bf16 v[44:47], v[142:145], v[190:193], v[44:47]
	v_mfma_f32_16x16x32_bf16 v[40:43], v[150:153], v[190:193], v[40:43]
	v_mfma_f32_16x16x32_bf16 v[28:31], v[142:145], v[198:201], v[28:31]
	v_mfma_f32_16x16x32_bf16 v[24:27], v[150:153], v[198:201], v[24:27]
	v_mfma_f32_16x16x32_bf16 v[12:15], v[142:145], v[206:209], v[12:15]
	v_mfma_f32_16x16x32_bf16 v[8:11], v[150:153], v[206:209], v[8:11]
	v_mfma_f32_16x16x32_bf16 v[60:63], v[146:149], v[186:189], v[60:63]
	v_mfma_f32_16x16x32_bf16 v[56:59], v[154:157], v[186:189], v[56:59]
	v_mfma_f32_16x16x32_bf16 v[44:47], v[146:149], v[194:197], v[44:47]
	v_mfma_f32_16x16x32_bf16 v[40:43], v[154:157], v[194:197], v[40:43]
	v_mfma_f32_16x16x32_bf16 v[28:31], v[146:149], v[202:205], v[28:31]
	v_mfma_f32_16x16x32_bf16 v[24:27], v[154:157], v[202:205], v[24:27]
	v_mfma_f32_16x16x32_bf16 v[12:15], v[146:149], v[210:213], v[12:15]
	v_mfma_f32_16x16x32_bf16 v[8:11], v[154:157], v[210:213], v[8:11]
	v_mfma_f32_16x16x32_bf16 v[52:55], v[158:161], v[182:185], v[52:55]
	v_mfma_f32_16x16x32_bf16 v[48:51], v[166:169], v[182:185], v[48:51]
	v_mfma_f32_16x16x32_bf16 v[36:39], v[158:161], v[190:193], v[36:39]
	v_mfma_f32_16x16x32_bf16 v[32:35], v[166:169], v[190:193], v[32:35]
	v_mfma_f32_16x16x32_bf16 v[20:23], v[158:161], v[198:201], v[20:23]
	v_mfma_f32_16x16x32_bf16 v[16:19], v[166:169], v[198:201], v[16:19]
	v_mfma_f32_16x16x32_bf16 v[4:7], v[158:161], v[206:209], v[4:7]
	v_mfma_f32_16x16x32_bf16 v[0:3], v[166:169], v[206:209], v[0:3]
	v_mfma_f32_16x16x32_bf16 v[52:55], v[162:165], v[186:189], v[52:55]
	v_mfma_f32_16x16x32_bf16 v[48:51], v[170:173], v[186:189], v[48:51]
	v_mfma_f32_16x16x32_bf16 v[36:39], v[162:165], v[194:197], v[36:39]
	v_mfma_f32_16x16x32_bf16 v[32:35], v[170:173], v[194:197], v[32:35]
	v_mfma_f32_16x16x32_bf16 v[20:23], v[162:165], v[202:205], v[20:23]
	v_mfma_f32_16x16x32_bf16 v[16:19], v[170:173], v[202:205], v[16:19]
	v_mfma_f32_16x16x32_bf16 v[4:7], v[162:165], v[210:213], v[4:7]
	v_mfma_f32_16x16x32_bf16 v[0:3], v[170:173], v[210:213], v[0:3]
	s_barrier
	s_add_i32 s28, 0, 0x18000
	s_add_i32 s48, 0, 0x1c000
	v_add_u32_e32 v154, s28, v140
	v_add_u32_e32 v170, s48, v140
	ds_read_b128 v[142:145], v154
	ds_read_b128 v[146:149], v154 offset:1024
	ds_read_b128 v[150:153], v154 offset:2048
	ds_read_b128 v[154:157], v154 offset:3072
	ds_read_b128 v[158:161], v170
	ds_read_b128 v[162:165], v170 offset:1024
	ds_read_b128 v[166:169], v170 offset:2048
	ds_read_b128 v[170:173], v170 offset:3072
	s_add_u32 s38, s64, s10
	s_addc_u32 s39, s65, s11
	s_mov_b32 m0, s63
	v_lshl_add_u64 v[224:225], s[38:39], 0, v[128:129]
	ds_read_b128 v[182:185], v141 offset:32768
	ds_read_b128 v[186:189], v141 offset:33792
	ds_read_b128 v[190:193], v141 offset:34816
	ds_read_b128 v[194:197], v141 offset:35840
	ds_read_b128 v[198:201], v141 offset:36864
	ds_read_b128 v[202:205], v141 offset:37888
	ds_read_b128 v[206:209], v141 offset:38912
	ds_read_b128 v[210:213], v141 offset:39936
	global_load_lds_dwordx4 v[224:225], off
	v_lshl_add_u64 v[224:225], s[38:39], 0, v[130:131]
	s_mov_b32 m0, s66
	s_nop 0
	global_load_lds_dwordx4 v[224:225], off
	s_waitcnt vmcnt(8)
	s_waitcnt lgkmcnt(0)
	s_barrier
	s_waitcnt lgkmcnt(0)
	v_mfma_f32_16x16x32_bf16 v[120:123], v[142:145], v[182:185], v[120:123]
	v_mfma_f32_16x16x32_bf16 v[124:127], v[150:153], v[182:185], v[124:127]
	v_mfma_f32_16x16x32_bf16 v[108:111], v[142:145], v[190:193], v[108:111]
	v_mfma_f32_16x16x32_bf16 v[104:107], v[150:153], v[190:193], v[104:107]
	v_mfma_f32_16x16x32_bf16 v[92:95], v[142:145], v[198:201], v[92:95]
	v_mfma_f32_16x16x32_bf16 v[88:91], v[150:153], v[198:201], v[88:91]
	v_mfma_f32_16x16x32_bf16 v[76:79], v[142:145], v[206:209], v[76:79]
	v_mfma_f32_16x16x32_bf16 v[72:75], v[150:153], v[206:209], v[72:75]
	v_mfma_f32_16x16x32_bf16 v[120:123], v[146:149], v[186:189], v[120:123]
	v_mfma_f32_16x16x32_bf16 v[124:127], v[154:157], v[186:189], v[124:127]
	v_mfma_f32_16x16x32_bf16 v[108:111], v[146:149], v[194:197], v[108:111]
	v_mfma_f32_16x16x32_bf16 v[104:107], v[154:157], v[194:197], v[104:107]
	v_mfma_f32_16x16x32_bf16 v[92:95], v[146:149], v[202:205], v[92:95]
	v_mfma_f32_16x16x32_bf16 v[88:91], v[154:157], v[202:205], v[88:91]
	v_mfma_f32_16x16x32_bf16 v[76:79], v[146:149], v[210:213], v[76:79]
	v_mfma_f32_16x16x32_bf16 v[72:75], v[154:157], v[210:213], v[72:75]
	v_mfma_f32_16x16x32_bf16 v[116:119], v[158:161], v[182:185], v[116:119]
	v_mfma_f32_16x16x32_bf16 v[112:115], v[166:169], v[182:185], v[112:115]
	v_mfma_f32_16x16x32_bf16 v[100:103], v[158:161], v[190:193], v[100:103]
	v_mfma_f32_16x16x32_bf16 v[96:99], v[166:169], v[190:193], v[96:99]
	v_mfma_f32_16x16x32_bf16 v[84:87], v[158:161], v[198:201], v[84:87]
	v_mfma_f32_16x16x32_bf16 v[80:83], v[166:169], v[198:201], v[80:83]
	v_mfma_f32_16x16x32_bf16 v[68:71], v[158:161], v[206:209], v[68:71]
	v_mfma_f32_16x16x32_bf16 v[64:67], v[166:169], v[206:209], v[64:67]
	v_mfma_f32_16x16x32_bf16 v[116:119], v[162:165], v[186:189], v[116:119]
	v_mfma_f32_16x16x32_bf16 v[112:115], v[170:173], v[186:189], v[112:115]
	v_mfma_f32_16x16x32_bf16 v[100:103], v[162:165], v[194:197], v[100:103]
	v_mfma_f32_16x16x32_bf16 v[96:99], v[170:173], v[194:197], v[96:99]
	v_mfma_f32_16x16x32_bf16 v[84:87], v[162:165], v[202:205], v[84:87]
	v_mfma_f32_16x16x32_bf16 v[80:83], v[170:173], v[202:205], v[80:83]
	v_mfma_f32_16x16x32_bf16 v[68:71], v[162:165], v[210:213], v[68:71]
	v_mfma_f32_16x16x32_bf16 v[64:67], v[170:173], v[210:213], v[64:67]
	s_barrier
; #define PG8_STAGE(bufoff, gbase, voff) do { _Pragma("unroll") for (int _i = 0; _i < 2; ++_i) \
;         __builtin_amdgcn_global_load_lds((const unsigned*)((const char*)(gbase) + (voff)[_i]), (PG8_LAS unsigned*)(lds + (bufoff) + ldsw + _i * 8192), 16, 0, 0); } while (0)
; #define PG8_LDA(dst, b, h) do { _Pragma("unroll") for (int m = 0; m < 4; ++m) _Pragma("unroll") for (int k = 0; k < 2; ++k) dst[m][k] = *(const PG8_LAS bf16x8*)(lds + PG8_SA(b, h) + aoff + m * 2048 + k * 1024); } while (0)
; #define PG8_MMA(ai, bj, At, Bt) do { __builtin_amdgcn_s_setprio(1); _Pragma("unroll") for (int m = 0; m < 4; ++m) _Pragma("unroll") for (int n = 0; n < 2; ++n) _Pragma("unroll") for (int k = 0; k < 2; ++k) \
;         acc[ai][bj][m][n] = __builtin_amdgcn_mfma_f32_16x16x32_bf16(Bt[n][k], At[m][k], acc[ai][bj][m][n], 0, 0, 0); __builtin_amdgcn_s_setprio(0); } while (0)
; #define PG8_WAIT_V(n) asm volatile("s_waitcnt vmcnt(" #n ")" ::: "memory")
; #define PG8_WAIT_L(n) asm volatile("s_waitcnt lgkmcnt(" #n ")" ::: "memory")
; #define PG8_BAR __builtin_amdgcn_s_barrier()
; #define PG8_SCHED __builtin_amdgcn_sched_barrier(0)
; template <class Epi, class Sched, bool ALIGN_EPI = false, bool SP2 = false>
; __device__ __forceinline__ void gemm_phase(PG8_LAS unsigned char* lds, const Gemm g, const Sched& S, const Epi& E) {
;     ...
;             PG8_LDA(At, 1, 1); PG8_STAGE(PG8_SB(1, 0), b3, voffB); PG8_STAGE(PG8_SB(1, 1), b3 + hstep, voffB); PG8_STAGE(PG8_SA(1, 0), a3, voffA);
;             PG8_WAIT_V(8); PG8_WAIT_L(0); PG8_BAR; PG8_MMA(1, 0, At, B0); PG8_MMA(1, 1, At, B1); PG8_BAR; PG8_SCHED;
	s_add_i32 s28, s28, s24
	v_lshl_add_u64 v[174:175], v[174:175], 0, s[44:45]
	s_mov_b32 m0, s28
	ds_read_b128 v[182:185], v141 offset:49152
	ds_read_b128 v[186:189], v141 offset:50176
	ds_read_b128 v[190:193], v141 offset:51200
	ds_read_b128 v[194:197], v141 offset:52224
	ds_read_b128 v[198:201], v141 offset:53248
	ds_read_b128 v[202:205], v141 offset:54272
	ds_read_b128 v[206:209], v141 offset:55296
	ds_read_b128 v[210:213], v141 offset:56320
	global_load_lds_dwordx4 v[174:175], off
	v_lshl_add_u64 v[174:175], v[214:215], 0, s[44:45]
	s_add_i32 m0, s28, 0x2000
	s_add_i32 s28, s48, s24
	global_load_lds_dwordx4 v[174:175], off
	v_lshl_add_u64 v[174:175], v[216:217], 0, s[44:45]
	s_mov_b32 m0, s28
	s_nop 0
	global_load_lds_dwordx4 v[174:175], off
	v_lshl_add_u64 v[174:175], v[218:219], 0, s[44:45]
	s_add_i32 m0, s28, 0x2000
	s_nop 0
	global_load_lds_dwordx4 v[174:175], off
	v_lshl_add_u64 v[174:175], v[220:221], 0, s[44:45]
	s_mov_b32 m0, s72
	s_nop 0
	global_load_lds_dwordx4 v[174:175], off
	v_lshl_add_u64 v[174:175], v[222:223], 0, s[44:45]
	s_mov_b32 m0, s73
	s_nop 0
	global_load_lds_dwordx4 v[174:175], off
	s_waitcnt vmcnt(8)
	s_waitcnt lgkmcnt(0)
	s_barrier
	s_waitcnt lgkmcnt(0)
	v_mfma_f32_16x16x32_bf16 v[60:63], v[142:145], v[182:185], v[60:63]
	v_mfma_f32_16x16x32_bf16 v[56:59], v[150:153], v[182:185], v[56:59]
	v_mfma_f32_16x16x32_bf16 v[44:47], v[142:145], v[190:193], v[44:47]
	v_mfma_f32_16x16x32_bf16 v[40:43], v[150:153], v[190:193], v[40:43]
	v_mfma_f32_16x16x32_bf16 v[28:31], v[142:145], v[198:201], v[28:31]
	v_mfma_f32_16x16x32_bf16 v[24:27], v[150:153], v[198:201], v[24:27]
	v_mfma_f32_16x16x32_bf16 v[12:15], v[142:145], v[206:209], v[12:15]
	v_mfma_f32_16x16x32_bf16 v[8:11], v[150:153], v[206:209], v[8:11]
	v_mfma_f32_16x16x32_bf16 v[60:63], v[146:149], v[186:189], v[60:63]
	v_mfma_f32_16x16x32_bf16 v[56:59], v[154:157], v[186:189], v[56:59]
	v_mfma_f32_16x16x32_bf16 v[44:47], v[146:149], v[194:197], v[44:47]
	v_mfma_f32_16x16x32_bf16 v[40:43], v[154:157], v[194:197], v[40:43]
	v_mfma_f32_16x16x32_bf16 v[28:31], v[146:149], v[202:205], v[28:31]
	v_mfma_f32_16x16x32_bf16 v[24:27], v[154:157], v[202:205], v[24:27]
	v_mfma_f32_16x16x32_bf16 v[12:15], v[146:149], v[210:213], v[12:15]
	v_mfma_f32_16x16x32_bf16 v[8:11], v[154:157], v[210:213], v[8:11]
	v_mfma_f32_16x16x32_bf16 v[52:55], v[158:161], v[182:185], v[52:55]
	v_mfma_f32_16x16x32_bf16 v[48:51], v[166:169], v[182:185], v[48:51]
	v_mfma_f32_16x16x32_bf16 v[36:39], v[158:161], v[190:193], v[36:39]
	v_mfma_f32_16x16x32_bf16 v[32:35], v[166:169], v[190:193], v[32:35]
	v_mfma_f32_16x16x32_bf16 v[20:23], v[158:161], v[198:201], v[20:23]
	v_mfma_f32_16x16x32_bf16 v[16:19], v[166:169], v[198:201], v[16:19]
	v_mfma_f32_16x16x32_bf16 v[4:7], v[158:161], v[206:209], v[4:7]
	v_mfma_f32_16x16x32_bf16 v[0:3], v[166:169], v[206:209], v[0:3]
	v_mfma_f32_16x16x32_bf16 v[52:55], v[162:165], v[186:189], v[52:55]
	v_mfma_f32_16x16x32_bf16 v[48:51], v[170:173], v[186:189], v[48:51]
	s_add_u32 s40, s40, 0x100
	v_mfma_f32_16x16x32_bf16 v[36:39], v[162:165], v[194:197], v[36:39]
	s_addc_u32 s41, s41, 0
	v_mfma_f32_16x16x32_bf16 v[32:35], v[170:173], v[194:197], v[32:35]
	s_add_u32 s78, s78, 0x100
	v_mfma_f32_16x16x32_bf16 v[20:23], v[162:165], v[202:205], v[20:23]
	s_addc_u32 s79, s79, 0
	v_mfma_f32_16x16x32_bf16 v[16:19], v[170:173], v[202:205], v[16:19]
	s_cmp_ge_i32 s80, s67
	v_mfma_f32_16x16x32_bf16 v[4:7], v[162:165], v[210:213], v[4:7]
	s_mov_b32 s64, s80
	v_mfma_f32_16x16x32_bf16 v[0:3], v[170:173], v[210:213], v[0:3]
	s_barrier
	s_cbranch_scc0 .LBB0_375
	v_readlane_b32 s80, v254, 45
	v_readlane_b32 s78, v254, 43
	v_readlane_b32 s81, v254, 46
	v_readlane_b32 s82, v254, 47
	v_readlane_b32 s83, v254, 48
	v_readlane_b32 s84, v254, 49
	v_readlane_b32 s85, v254, 50
	v_readlane_b32 s86, v254, 51
	v_readlane_b32 s87, v254, 52
	v_readlane_b32 s88, v254, 53
	v_readlane_b32 s89, v254, 54
	v_readlane_b32 s92, v254, 57
	v_readlane_b32 s93, v254, 58
	v_readlane_b32 s94, v254, 59
	v_readlane_b32 s95, v254, 60
	v_readlane_b32 s79, v254, 44
	v_readlane_b32 s90, v254, 55
	v_readlane_b32 s91, v254, 56

; #define PG8_STAGE(bufoff, gbase, voff) do { _Pragma("unroll") for (int _i = 0; _i < 2; ++_i) \
;         __builtin_amdgcn_global_load_lds((const unsigned*)((const char*)(gbase) + (voff)[_i]), (PG8_LAS unsigned*)(lds + (bufoff) + ldsw + _i * 8192), 16, 0, 0); } while (0)
; #define PG8_LDA(dst, b, h) do { _Pragma("unroll") for (int m = 0; m < 4; ++m) _Pragma("unroll") for (int k = 0; k < 2; ++k) dst[m][k] = *(const PG8_LAS bf16x8*)(lds + PG8_SA(b, h) + aoff + m * 2048 + k * 1024); } while (0)
; #define PG8_LDB(dst, b, h) do { _Pragma("unroll") for (int n = 0; n < 2; ++n) _Pragma("unroll") for (int k = 0; k < 2; ++k) dst[n][k] = *(const PG8_LAS bf16x8*)(lds + PG8_SB(b, h) + boff + n * 2048 + k * 1024); } while (0)
; #define PG8_MMA(ai, bj, At, Bt) do { __builtin_amdgcn_s_setprio(1); _Pragma("unroll") for (int m = 0; m < 4; ++m) _Pragma("unroll") for (int n = 0; n < 2; ++n) _Pragma("unroll") for (int k = 0; k < 2; ++k) \
;         acc[ai][bj][m][n] = __builtin_amdgcn_mfma_f32_16x16x32_bf16(Bt[n][k], At[m][k], acc[ai][bj][m][n], 0, 0, 0); __builtin_amdgcn_s_setprio(0); } while (0)
; #define PG8_WAIT_V(n) asm volatile("s_waitcnt vmcnt(" #n ")" ::: "memory")
; #define PG8_WAIT_L(n) asm volatile("s_waitcnt lgkmcnt(" #n ")" ::: "memory")
; #define PG8_BAR __builtin_amdgcn_s_barrier()
; #define PG8_SCHED __builtin_amdgcn_sched_barrier(0)
; template <class Epi, class Sched, bool ALIGN_EPI = false, bool SP2 = false>
; __device__ __forceinline__ void gemm_phase(PG8_LAS unsigned char* lds, const Gemm g, const Sched& S, const Epi& E) {
;     ...
;             const bool last = (t == nt - 2);
;             const char* a1 = cA + (size_t)(t + 1) * kstep;
;             const char* a2 = last ? nA : cA + (size_t)(t + 2) * kstep; const char* b2 = last ? nB : cB + (size_t)(t + 2) * kstep;
;             const char* a3 = a2 + kstep; const char* b3 = b2 + kstep;
;             if (last && has_next) S.a_ready(nxt);
;             if constexpr (SP2) {
;             PG8_LDB(B0, 0, 0); PG8_LDB(B1, 0, 1); PG8_SCHED; PG8_LDA(At, 0, 0); PG8_STAGE(PG8_SA(1, 1), a1 + hstep, voffA);
;             PG8_WAIT_V(8); PG8_WAIT_L(0); PG8_BAR; PG8_MMA(0, 0, At, B0); PG8_MMA(0, 1, At, B1); PG8_BAR; PG8_SCHED;
;             PG8_LDA(At, 0, 1); PG8_STAGE(PG8_SB(0, 0), b2, voffB); PG8_STAGE(PG8_SB(0, 1), b2 + hstep, voffB); PG8_STAGE(PG8_SA(0, 0), a2, voffA);
.LBB0_406:
	s_add_i32 s81, s66, 2
	s_add_u32 s28, s64, 0x80
	s_addc_u32 s38, s65, 0
	s_add_i32 s48, 0, 0x10000
	s_cmp_eq_u32 s75, s66
	s_cselect_b32 s67, s7, s38
	s_cselect_b32 s66, s6, s28
	s_cselect_b32 s39, s41, s80
	s_cselect_b32 s38, s40, s79
	s_add_i32 s28, 0, 0x14000
	v_add_u32_e32 v154, s48, v148
	v_add_u32_e32 v170, s28, v148
	ds_read_b128 v[138:141], v154
	ds_read_b128 v[142:145], v154 offset:1024
	ds_read_b128 v[150:153], v154 offset:2048
	ds_read_b128 v[154:157], v154 offset:3072
	ds_read_b128 v[158:161], v170
	ds_read_b128 v[162:165], v170 offset:1024
	ds_read_b128 v[166:169], v170 offset:2048
	ds_read_b128 v[170:173], v170 offset:3072
	v_lshl_add_u64 v[174:175], s[64:65], 0, v[134:135]
	s_add_i32 m0, s43, 0xc000
	ds_read_b128 v[182:185], v149
	ds_read_b128 v[186:189], v149 offset:1024
	ds_read_b128 v[190:193], v149 offset:2048
	ds_read_b128 v[194:197], v149 offset:3072
	ds_read_b128 v[198:201], v149 offset:4096
	ds_read_b128 v[202:205], v149 offset:5120
	ds_read_b128 v[206:209], v149 offset:6144
	ds_read_b128 v[210:213], v149 offset:7168
	global_load_lds_dwordx4 v[174:175], off
	v_lshl_add_u64 v[174:175], s[64:65], 0, v[136:137]
	s_add_i32 m0, s43, 0xe000
	s_nop 0
	global_load_lds_dwordx4 v[174:175], off
	s_waitcnt vmcnt(8)
	s_waitcnt lgkmcnt(0)
	s_barrier
	s_waitcnt lgkmcnt(0)
	v_mfma_f32_16x16x32_bf16 v[124:127], v[138:141], v[182:185], v[124:127]
	v_mfma_f32_16x16x32_bf16 v[120:123], v[150:153], v[182:185], v[120:123]
	v_mfma_f32_16x16x32_bf16 v[116:119], v[138:141], v[190:193], v[116:119]
	v_mfma_f32_16x16x32_bf16 v[112:115], v[150:153], v[190:193], v[112:115]
	v_mfma_f32_16x16x32_bf16 v[104:107], v[138:141], v[198:201], v[104:107]
	v_mfma_f32_16x16x32_bf16 v[96:99], v[150:153], v[198:201], v[96:99]
	v_mfma_f32_16x16x32_bf16 v[88:91], v[138:141], v[206:209], v[88:91]
	v_mfma_f32_16x16x32_bf16 v[80:83], v[150:153], v[206:209], v[80:83]
	v_mfma_f32_16x16x32_bf16 v[124:127], v[142:145], v[186:189], v[124:127]
	v_mfma_f32_16x16x32_bf16 v[120:123], v[154:157], v[186:189], v[120:123]
	v_mfma_f32_16x16x32_bf16 v[116:119], v[142:145], v[194:197], v[116:119]
	v_mfma_f32_16x16x32_bf16 v[112:115], v[154:157], v[194:197], v[112:115]
	v_mfma_f32_16x16x32_bf16 v[104:107], v[142:145], v[202:205], v[104:107]
	v_mfma_f32_16x16x32_bf16 v[96:99], v[154:157], v[202:205], v[96:99]
	v_mfma_f32_16x16x32_bf16 v[88:91], v[142:145], v[210:213], v[88:91]
	v_mfma_f32_16x16x32_bf16 v[80:83], v[154:157], v[210:213], v[80:83]
	v_mfma_f32_16x16x32_bf16 v[108:111], v[158:161], v[182:185], v[108:111]
	v_mfma_f32_16x16x32_bf16 v[100:103], v[166:169], v[182:185], v[100:103]
	v_mfma_f32_16x16x32_bf16 v[92:95], v[158:161], v[190:193], v[92:95]
	v_mfma_f32_16x16x32_bf16 v[84:87], v[166:169], v[190:193], v[84:87]
	v_mfma_f32_16x16x32_bf16 v[76:79], v[158:161], v[198:201], v[76:79]
	v_mfma_f32_16x16x32_bf16 v[72:75], v[166:169], v[198:201], v[72:75]
	v_mfma_f32_16x16x32_bf16 v[68:71], v[158:161], v[206:209], v[68:71]
	v_mfma_f32_16x16x32_bf16 v[64:67], v[166:169], v[206:209], v[64:67]
	v_mfma_f32_16x16x32_bf16 v[108:111], v[162:165], v[186:189], v[108:111]
	v_mfma_f32_16x16x32_bf16 v[100:103], v[170:173], v[186:189], v[100:103]
	v_mfma_f32_16x16x32_bf16 v[92:95], v[162:165], v[194:197], v[92:95]
	v_mfma_f32_16x16x32_bf16 v[84:87], v[170:173], v[194:197], v[84:87]
	v_mfma_f32_16x16x32_bf16 v[76:79], v[162:165], v[202:205], v[76:79]
	v_mfma_f32_16x16x32_bf16 v[72:75], v[170:173], v[202:205], v[72:75]
	v_mfma_f32_16x16x32_bf16 v[68:71], v[162:165], v[210:213], v[68:71]
	v_mfma_f32_16x16x32_bf16 v[64:67], v[170:173], v[210:213], v[64:67]
	s_barrier
	s_add_i32 s48, s48, s24
	v_lshl_add_u64 v[174:175], s[38:39], 0, v[176:177]
	s_mov_b32 m0, s48
	ds_read_b128 v[182:185], v149 offset:16384
	ds_read_b128 v[186:189], v149 offset:17408
	ds_read_b128 v[190:193], v149 offset:18432
	ds_read_b128 v[194:197], v149 offset:19456
	ds_read_b128 v[198:201], v149 offset:20480
	ds_read_b128 v[202:205], v149 offset:21504
	ds_read_b128 v[206:209], v149 offset:22528
	ds_read_b128 v[210:213], v149 offset:23552
	global_load_lds_dwordx4 v[174:175], off
	s_add_i32 m0, s48, 0x2000
	v_lshl_add_u64 v[214:215], s[38:39], 0, v[132:133]
	s_add_u32 s38, s38, s10
	s_addc_u32 s39, s39, s11
	s_add_i32 s28, s28, s24
	global_load_lds_dwordx4 v[214:215], off
	v_lshl_add_u64 v[216:217], s[38:39], 0, v[176:177]
	s_mov_b32 m0, s28
	v_lshl_add_u64 v[218:219], s[38:39], 0, v[132:133]
	global_load_lds_dwordx4 v[216:217], off
	s_add_i32 m0, s28, 0x2000
	v_lshl_add_u64 v[220:221], s[66:67], 0, v[128:129]
	global_load_lds_dwordx4 v[218:219], off
	s_mov_b32 m0, s43
	v_lshl_add_u64 v[222:223], s[66:67], 0, v[130:131]
	global_load_lds_dwordx4 v[220:221], off
	s_mov_b32 m0, s46
	s_nop 0
	global_load_lds_dwordx4 v[222:223], off
	s_waitcnt vmcnt(8)
	s_waitcnt lgkmcnt(0)
	s_barrier
; #define PG8_STAGE(bufoff, gbase, voff) do { _Pragma("unroll") for (int _i = 0; _i < 2; ++_i) \
;         __builtin_amdgcn_global_load_lds((const unsigned*)((const char*)(gbase) + (voff)[_i]), (PG8_LAS unsigned*)(lds + (bufoff) + ldsw + _i * 8192), 16, 0, 0); } while (0)
; #define PG8_LDA(dst, b, h) do { _Pragma("unroll") for (int m = 0; m < 4; ++m) _Pragma("unroll") for (int k = 0; k < 2; ++k) dst[m][k] = *(const PG8_LAS bf16x8*)(lds + PG8_SA(b, h) + aoff + m * 2048 + k * 1024); } while (0)
; #define PG8_LDB(dst, b, h) do { _Pragma("unroll") for (int n = 0; n < 2; ++n) _Pragma("unroll") for (int k = 0; k < 2; ++k) dst[n][k] = *(const PG8_LAS bf16x8*)(lds + PG8_SB(b, h) + boff + n * 2048 + k * 1024); } while (0)
; #define PG8_MMA(ai, bj, At, Bt) do { __builtin_amdgcn_s_setprio(1); _Pragma("unroll") for (int m = 0; m < 4; ++m) _Pragma("unroll") for (int n = 0; n < 2; ++n) _Pragma("unroll") for (int k = 0; k < 2; ++k) \
;         acc[ai][bj][m][n] = __builtin_amdgcn_mfma_f32_16x16x32_bf16(Bt[n][k], At[m][k], acc[ai][bj][m][n], 0, 0, 0); __builtin_amdgcn_s_setprio(0); } while (0)
; #define PG8_WAIT_V(n) asm volatile("s_waitcnt vmcnt(" #n ")" ::: "memory")
; #define PG8_WAIT_L(n) asm volatile("s_waitcnt lgkmcnt(" #n ")" ::: "memory")
; #define PG8_BAR __builtin_amdgcn_s_barrier()
; #define PG8_SCHED __builtin_amdgcn_sched_barrier(0)
; template <class Epi, class Sched, bool ALIGN_EPI = false, bool SP2 = false>
; __device__ __forceinline__ void gemm_phase(PG8_LAS unsigned char* lds, const Gemm g, const Sched& S, const Epi& E) {
;     ...
;             PG8_WAIT_V(8); PG8_WAIT_L(0); PG8_BAR; PG8_MMA(1, 0, At, B0); PG8_MMA(1, 1, At, B1); PG8_BAR; PG8_SCHED;
;             PG8_LDB(B0, 1, 0); PG8_LDB(B1, 1, 1); PG8_SCHED; PG8_LDA(At, 1, 0); PG8_STAGE(PG8_SA(0, 1), a2 + hstep, voffA);
;             PG8_WAIT_V(8); PG8_WAIT_L(0); PG8_BAR; PG8_MMA(0, 0, At, B0); PG8_MMA(0, 1, At, B1); PG8_BAR; PG8_SCHED;
	s_waitcnt lgkmcnt(0)
	v_mfma_f32_16x16x32_bf16 v[60:63], v[138:141], v[182:185], v[60:63]
	v_mfma_f32_16x16x32_bf16 v[56:59], v[150:153], v[182:185], v[56:59]
	v_mfma_f32_16x16x32_bf16 v[52:55], v[138:141], v[190:193], v[52:55]
	v_mfma_f32_16x16x32_bf16 v[48:51], v[150:153], v[190:193], v[48:51]
	v_mfma_f32_16x16x32_bf16 v[40:43], v[138:141], v[198:201], v[40:43]
	v_mfma_f32_16x16x32_bf16 v[32:35], v[150:153], v[198:201], v[32:35]
	v_mfma_f32_16x16x32_bf16 v[24:27], v[138:141], v[206:209], v[24:27]
	v_mfma_f32_16x16x32_bf16 v[16:19], v[150:153], v[206:209], v[16:19]
	v_mfma_f32_16x16x32_bf16 v[60:63], v[142:145], v[186:189], v[60:63]
	v_mfma_f32_16x16x32_bf16 v[56:59], v[154:157], v[186:189], v[56:59]
	v_mfma_f32_16x16x32_bf16 v[52:55], v[142:145], v[194:197], v[52:55]
	v_mfma_f32_16x16x32_bf16 v[48:51], v[154:157], v[194:197], v[48:51]
	v_mfma_f32_16x16x32_bf16 v[40:43], v[142:145], v[202:205], v[40:43]
	v_mfma_f32_16x16x32_bf16 v[32:35], v[154:157], v[202:205], v[32:35]
	v_mfma_f32_16x16x32_bf16 v[24:27], v[142:145], v[210:213], v[24:27]
	v_mfma_f32_16x16x32_bf16 v[16:19], v[154:157], v[210:213], v[16:19]
	v_mfma_f32_16x16x32_bf16 v[44:47], v[158:161], v[182:185], v[44:47]
	v_mfma_f32_16x16x32_bf16 v[36:39], v[166:169], v[182:185], v[36:39]
	v_mfma_f32_16x16x32_bf16 v[28:31], v[158:161], v[190:193], v[28:31]
	v_mfma_f32_16x16x32_bf16 v[20:23], v[166:169], v[190:193], v[20:23]
	v_mfma_f32_16x16x32_bf16 v[12:15], v[158:161], v[198:201], v[12:15]
	v_mfma_f32_16x16x32_bf16 v[8:11], v[166:169], v[198:201], v[8:11]
	v_mfma_f32_16x16x32_bf16 v[4:7], v[158:161], v[206:209], v[4:7]
	v_mfma_f32_16x16x32_bf16 v[0:3], v[166:169], v[206:209], v[0:3]
	v_mfma_f32_16x16x32_bf16 v[44:47], v[162:165], v[186:189], v[44:47]
	v_mfma_f32_16x16x32_bf16 v[36:39], v[170:173], v[186:189], v[36:39]
	v_mfma_f32_16x16x32_bf16 v[28:31], v[162:165], v[194:197], v[28:31]
	v_mfma_f32_16x16x32_bf16 v[20:23], v[170:173], v[194:197], v[20:23]
	v_mfma_f32_16x16x32_bf16 v[12:15], v[162:165], v[202:205], v[12:15]
	v_mfma_f32_16x16x32_bf16 v[8:11], v[170:173], v[202:205], v[8:11]
	v_mfma_f32_16x16x32_bf16 v[4:7], v[162:165], v[210:213], v[4:7]
	v_mfma_f32_16x16x32_bf16 v[0:3], v[170:173], v[210:213], v[0:3]
	s_barrier
	s_add_i32 s28, 0, 0x18000
	s_add_i32 s48, 0, 0x1c000
	v_add_u32_e32 v154, s28, v148
	v_add_u32_e32 v170, s48, v148
	ds_read_b128 v[138:141], v154
	ds_read_b128 v[142:145], v154 offset:1024
	ds_read_b128 v[150:153], v154 offset:2048
	ds_read_b128 v[154:157], v154 offset:3072
	ds_read_b128 v[158:161], v170
	ds_read_b128 v[162:165], v170 offset:1024
	ds_read_b128 v[166:169], v170 offset:2048
	ds_read_b128 v[170:173], v170 offset:3072
	s_add_u32 s38, s66, s10
	s_addc_u32 s39, s67, s11
	s_mov_b32 m0, s63
	v_lshl_add_u64 v[224:225], s[38:39], 0, v[128:129]
	ds_read_b128 v[182:185], v149 offset:32768
	ds_read_b128 v[186:189], v149 offset:33792
	ds_read_b128 v[190:193], v149 offset:34816
	ds_read_b128 v[194:197], v149 offset:35840
	ds_read_b128 v[198:201], v149 offset:36864
	ds_read_b128 v[202:205], v149 offset:37888
	ds_read_b128 v[206:209], v149 offset:38912
	ds_read_b128 v[210:213], v149 offset:39936
	global_load_lds_dwordx4 v[224:225], off
	v_lshl_add_u64 v[224:225], s[38:39], 0, v[130:131]
	s_mov_b32 m0, s68
	s_nop 0
	global_load_lds_dwordx4 v[224:225], off
	s_waitcnt vmcnt(8)
	s_waitcnt lgkmcnt(0)
	s_barrier
	s_waitcnt lgkmcnt(0)
	v_mfma_f32_16x16x32_bf16 v[124:127], v[138:141], v[182:185], v[124:127]
	v_mfma_f32_16x16x32_bf16 v[120:123], v[150:153], v[182:185], v[120:123]
	v_mfma_f32_16x16x32_bf16 v[116:119], v[138:141], v[190:193], v[116:119]
	v_mfma_f32_16x16x32_bf16 v[112:115], v[150:153], v[190:193], v[112:115]
	v_mfma_f32_16x16x32_bf16 v[104:107], v[138:141], v[198:201], v[104:107]
	v_mfma_f32_16x16x32_bf16 v[96:99], v[150:153], v[198:201], v[96:99]
	v_mfma_f32_16x16x32_bf16 v[88:91], v[138:141], v[206:209], v[88:91]
	v_mfma_f32_16x16x32_bf16 v[80:83], v[150:153], v[206:209], v[80:83]
	v_mfma_f32_16x16x32_bf16 v[124:127], v[142:145], v[186:189], v[124:127]
	v_mfma_f32_16x16x32_bf16 v[120:123], v[154:157], v[186:189], v[120:123]
	v_mfma_f32_16x16x32_bf16 v[116:119], v[142:145], v[194:197], v[116:119]
	v_mfma_f32_16x16x32_bf16 v[112:115], v[154:157], v[194:197], v[112:115]
	v_mfma_f32_16x16x32_bf16 v[104:107], v[142:145], v[202:205], v[104:107]
	v_mfma_f32_16x16x32_bf16 v[96:99], v[154:157], v[202:205], v[96:99]
	v_mfma_f32_16x16x32_bf16 v[88:91], v[142:145], v[210:213], v[88:91]
	v_mfma_f32_16x16x32_bf16 v[80:83], v[154:157], v[210:213], v[80:83]
	v_mfma_f32_16x16x32_bf16 v[108:111], v[158:161], v[182:185], v[108:111]
	v_mfma_f32_16x16x32_bf16 v[100:103], v[166:169], v[182:185], v[100:103]
	v_mfma_f32_16x16x32_bf16 v[92:95], v[158:161], v[190:193], v[92:95]
	v_mfma_f32_16x16x32_bf16 v[84:87], v[166:169], v[190:193], v[84:87]
	v_mfma_f32_16x16x32_bf16 v[76:79], v[158:161], v[198:201], v[76:79]
	v_mfma_f32_16x16x32_bf16 v[72:75], v[166:169], v[198:201], v[72:75]
	v_mfma_f32_16x16x32_bf16 v[68:71], v[158:161], v[206:209], v[68:71]
	v_mfma_f32_16x16x32_bf16 v[64:67], v[166:169], v[206:209], v[64:67]
	v_mfma_f32_16x16x32_bf16 v[108:111], v[162:165], v[186:189], v[108:111]
	v_mfma_f32_16x16x32_bf16 v[100:103], v[170:173], v[186:189], v[100:103]
	v_mfma_f32_16x16x32_bf16 v[92:95], v[162:165], v[194:197], v[92:95]
	v_mfma_f32_16x16x32_bf16 v[84:87], v[170:173], v[194:197], v[84:87]
	v_mfma_f32_16x16x32_bf16 v[76:79], v[162:165], v[202:205], v[76:79]
	v_mfma_f32_16x16x32_bf16 v[72:75], v[170:173], v[202:205], v[72:75]
	v_mfma_f32_16x16x32_bf16 v[68:71], v[162:165], v[210:213], v[68:71]
	v_mfma_f32_16x16x32_bf16 v[64:67], v[170:173], v[210:213], v[64:67]
	s_barrier
; #define PG8_STAGE(bufoff, gbase, voff) do { _Pragma("unroll") for (int _i = 0; _i < 2; ++_i) \
;         __builtin_amdgcn_global_load_lds((const unsigned*)((const char*)(gbase) + (voff)[_i]), (PG8_LAS unsigned*)(lds + (bufoff) + ldsw + _i * 8192), 16, 0, 0); } while (0)
; #define PG8_LDA(dst, b, h) do { _Pragma("unroll") for (int m = 0; m < 4; ++m) _Pragma("unroll") for (int k = 0; k < 2; ++k) dst[m][k] = *(const PG8_LAS bf16x8*)(lds + PG8_SA(b, h) + aoff + m * 2048 + k * 1024); } while (0)
; #define PG8_MMA(ai, bj, At, Bt) do { __builtin_amdgcn_s_setprio(1); _Pragma("unroll") for (int m = 0; m < 4; ++m) _Pragma("unroll") for (int n = 0; n < 2; ++n) _Pragma("unroll") for (int k = 0; k < 2; ++k) \
;         acc[ai][bj][m][n] = __builtin_amdgcn_mfma_f32_16x16x32_bf16(Bt[n][k], At[m][k], acc[ai][bj][m][n], 0, 0, 0); __builtin_amdgcn_s_setprio(0); } while (0)
; #define PG8_WAIT_V(n) asm volatile("s_waitcnt vmcnt(" #n ")" ::: "memory")
; #define PG8_WAIT_L(n) asm volatile("s_waitcnt lgkmcnt(" #n ")" ::: "memory")
; #define PG8_BAR __builtin_amdgcn_s_barrier()
; #define PG8_SCHED __builtin_amdgcn_sched_barrier(0)
; template <class Epi, class Sched, bool ALIGN_EPI = false, bool SP2 = false>
; __device__ __forceinline__ void gemm_phase(PG8_LAS unsigned char* lds, const Gemm g, const Sched& S, const Epi& E) {
;     ...
;             PG8_LDA(At, 1, 1); PG8_STAGE(PG8_SB(1, 0), b3, voffB); PG8_STAGE(PG8_SB(1, 1), b3 + hstep, voffB); PG8_STAGE(PG8_SA(1, 0), a3, voffA);
;             PG8_WAIT_V(8); PG8_WAIT_L(0); PG8_BAR; PG8_MMA(1, 0, At, B0); PG8_MMA(1, 1, At, B1); PG8_BAR; PG8_SCHED;
	s_add_i32 s28, s28, s24
	v_lshl_add_u64 v[174:175], v[174:175], 0, s[44:45]
	s_mov_b32 m0, s28
	ds_read_b128 v[182:185], v149 offset:49152
	ds_read_b128 v[186:189], v149 offset:50176
	ds_read_b128 v[190:193], v149 offset:51200
	ds_read_b128 v[194:197], v149 offset:52224
	ds_read_b128 v[198:201], v149 offset:53248
	ds_read_b128 v[202:205], v149 offset:54272
	ds_read_b128 v[206:209], v149 offset:55296
	ds_read_b128 v[210:213], v149 offset:56320
	global_load_lds_dwordx4 v[174:175], off
	v_lshl_add_u64 v[174:175], v[214:215], 0, s[44:45]
	s_add_i32 m0, s28, 0x2000
	s_add_i32 s28, s48, s24
	global_load_lds_dwordx4 v[174:175], off
	v_lshl_add_u64 v[174:175], v[216:217], 0, s[44:45]
	s_mov_b32 m0, s28
	s_nop 0
	global_load_lds_dwordx4 v[174:175], off
	v_lshl_add_u64 v[174:175], v[218:219], 0, s[44:45]
	s_add_i32 m0, s28, 0x2000
	s_nop 0
	global_load_lds_dwordx4 v[174:175], off
	v_lshl_add_u64 v[174:175], v[220:221], 0, s[44:45]
	s_mov_b32 m0, s73
	s_nop 0
	global_load_lds_dwordx4 v[174:175], off
	v_lshl_add_u64 v[174:175], v[222:223], 0, s[44:45]
	s_mov_b32 m0, s74
	s_nop 0
	global_load_lds_dwordx4 v[174:175], off
	s_waitcnt vmcnt(8)
	s_waitcnt lgkmcnt(0)
	s_barrier
	s_waitcnt lgkmcnt(0)
	v_mfma_f32_16x16x32_bf16 v[60:63], v[138:141], v[182:185], v[60:63]
	v_mfma_f32_16x16x32_bf16 v[56:59], v[150:153], v[182:185], v[56:59]
	v_mfma_f32_16x16x32_bf16 v[52:55], v[138:141], v[190:193], v[52:55]
	v_mfma_f32_16x16x32_bf16 v[48:51], v[150:153], v[190:193], v[48:51]
	v_mfma_f32_16x16x32_bf16 v[40:43], v[138:141], v[198:201], v[40:43]
	v_mfma_f32_16x16x32_bf16 v[32:35], v[150:153], v[198:201], v[32:35]
	v_mfma_f32_16x16x32_bf16 v[24:27], v[138:141], v[206:209], v[24:27]
	v_mfma_f32_16x16x32_bf16 v[16:19], v[150:153], v[206:209], v[16:19]
	v_mfma_f32_16x16x32_bf16 v[60:63], v[142:145], v[186:189], v[60:63]
	v_mfma_f32_16x16x32_bf16 v[56:59], v[154:157], v[186:189], v[56:59]
	v_mfma_f32_16x16x32_bf16 v[52:55], v[142:145], v[194:197], v[52:55]
	v_mfma_f32_16x16x32_bf16 v[48:51], v[154:157], v[194:197], v[48:51]
	v_mfma_f32_16x16x32_bf16 v[40:43], v[142:145], v[202:205], v[40:43]
	v_mfma_f32_16x16x32_bf16 v[32:35], v[154:157], v[202:205], v[32:35]
	v_mfma_f32_16x16x32_bf16 v[24:27], v[142:145], v[210:213], v[24:27]
	v_mfma_f32_16x16x32_bf16 v[16:19], v[154:157], v[210:213], v[16:19]
	v_mfma_f32_16x16x32_bf16 v[44:47], v[158:161], v[182:185], v[44:47]
	v_mfma_f32_16x16x32_bf16 v[36:39], v[166:169], v[182:185], v[36:39]
	v_mfma_f32_16x16x32_bf16 v[28:31], v[158:161], v[190:193], v[28:31]
	v_mfma_f32_16x16x32_bf16 v[20:23], v[166:169], v[190:193], v[20:23]
	v_mfma_f32_16x16x32_bf16 v[12:15], v[158:161], v[198:201], v[12:15]
	v_mfma_f32_16x16x32_bf16 v[8:11], v[166:169], v[198:201], v[8:11]
	v_mfma_f32_16x16x32_bf16 v[4:7], v[158:161], v[206:209], v[4:7]
	v_mfma_f32_16x16x32_bf16 v[0:3], v[166:169], v[206:209], v[0:3]
	v_mfma_f32_16x16x32_bf16 v[44:47], v[162:165], v[186:189], v[44:47]
	v_mfma_f32_16x16x32_bf16 v[36:39], v[170:173], v[186:189], v[36:39]
	s_add_u32 s64, s64, 0x100
	v_mfma_f32_16x16x32_bf16 v[28:31], v[162:165], v[194:197], v[28:31]
	s_addc_u32 s65, s65, 0
	v_mfma_f32_16x16x32_bf16 v[20:23], v[170:173], v[194:197], v[20:23]
	s_add_u32 s79, s79, 0x100
	v_mfma_f32_16x16x32_bf16 v[12:15], v[162:165], v[202:205], v[12:15]
	s_addc_u32 s80, s80, 0
	v_mfma_f32_16x16x32_bf16 v[8:11], v[170:173], v[202:205], v[8:11]
	s_cmp_ge_i32 s81, s69
	v_mfma_f32_16x16x32_bf16 v[4:7], v[162:165], v[210:213], v[4:7]
	s_mov_b32 s66, s81
	v_mfma_f32_16x16x32_bf16 v[0:3], v[170:173], v[210:213], v[0:3]
	s_barrier
	s_cbranch_scc0 .LBB0_406
; __device__ __forceinline__ unsigned cvt_pk_bf16(float lo, float hi) { unsigned r; asm volatile("v_cvt_pk_bf16_f32 %0, %1, %2" : "=v"(r) : "v"(lo), "v"(hi)); return r; }
;     __device__ __forceinline__ void operator()(const f32x4 (&acc)[2][2][4][2], const Unit& u, int wr, int wc, int fr, int fq) const {
;     ...
;                 for (int bj = 0; bj < 2; ++bj) { f32x4 v0 = acc[ai][bj][m][0], v1 = acc[ai][bj][m][1];
;                     if (ACT == 1) {
; #pragma unroll
;                         for (int j = 0; j < 4; ++j) { float a = fmaxf(v0[j], 0.f), b = fmaxf(v1[j], 0.f); v0[j] = a * a; v1[j] = b * b; } }
;                     v0 = v0 * scale; v1 = v1 * scale;
;                     u32x4 w; w.x = cvt_pk_bf16(v0[0], v0[1]); w.y = cvt_pk_bf16(v0[2], v0[3]); w.z = cvt_pk_bf16(v1[0], v1[1]); w.w = cvt_pk_bf16(v1[2], v1[3]);
	s_brev_b32 s28, 60
	v_readlane_b32 s80, v254, 45
	v_pk_mul_f32 v[126:127], v[126:127], s[28:29] op_sel_hi:[1,0]
	v_pk_mul_f32 v[124:125], v[124:125], s[28:29] op_sel_hi:[1,0]
	v_pk_mul_f32 v[122:123], v[122:123], s[28:29] op_sel_hi:[1,0]
	v_pk_mul_f32 v[120:121], v[120:121], s[28:29] op_sel_hi:[1,0]
	v_pk_mul_f32 v[138:139], v[110:111], s[28:29] op_sel_hi:[1,0]
	v_pk_mul_f32 v[140:141], v[108:109], s[28:29] op_sel_hi:[1,0]
	v_pk_mul_f32 v[142:143], v[102:103], s[28:29] op_sel_hi:[1,0]
	v_pk_mul_f32 v[144:145], v[100:101], s[28:29] op_sel_hi:[1,0]
	v_pk_mul_f32 v[100:101], v[118:119], s[28:29] op_sel_hi:[1,0]
	v_pk_mul_f32 v[102:103], v[116:117], s[28:29] op_sel_hi:[1,0]
	v_pk_mul_f32 v[108:109], v[114:115], s[28:29] op_sel_hi:[1,0]
	v_pk_mul_f32 v[110:111], v[112:113], s[28:29] op_sel_hi:[1,0]
	v_pk_mul_f32 v[112:113], v[94:95], s[28:29] op_sel_hi:[1,0]
	v_pk_mul_f32 v[114:115], v[92:93], s[28:29] op_sel_hi:[1,0]
	v_pk_mul_f32 v[116:117], v[86:87], s[28:29] op_sel_hi:[1,0]
	v_pk_mul_f32 v[118:119], v[84:85], s[28:29] op_sel_hi:[1,0]
	v_pk_mul_f32 v[84:85], v[106:107], s[28:29] op_sel_hi:[1,0]
	v_pk_mul_f32 v[86:87], v[104:105], s[28:29] op_sel_hi:[1,0]
	v_pk_mul_f32 v[92:93], v[98:99], s[28:29] op_sel_hi:[1,0]
	v_pk_mul_f32 v[94:95], v[96:97], s[28:29] op_sel_hi:[1,0]
	v_pk_mul_f32 v[96:97], v[78:79], s[28:29] op_sel_hi:[1,0]
	v_pk_mul_f32 v[98:99], v[76:77], s[28:29] op_sel_hi:[1,0]
	v_pk_mul_f32 v[104:105], v[74:75], s[28:29] op_sel_hi:[1,0]
	v_pk_mul_f32 v[106:107], v[72:73], s[28:29] op_sel_hi:[1,0]
	v_pk_mul_f32 v[72:73], v[90:91], s[28:29] op_sel_hi:[1,0]
	v_pk_mul_f32 v[74:75], v[88:89], s[28:29] op_sel_hi:[1,0]
	v_pk_mul_f32 v[76:77], v[82:83], s[28:29] op_sel_hi:[1,0]
	v_pk_mul_f32 v[78:79], v[80:81], s[28:29] op_sel_hi:[1,0]
	v_pk_mul_f32 v[70:71], v[70:71], s[28:29] op_sel_hi:[1,0]
	v_pk_mul_f32 v[68:69], v[68:69], s[28:29] op_sel_hi:[1,0]
	v_pk_mul_f32 v[66:67], v[66:67], s[28:29] op_sel_hi:[1,0]
	v_pk_mul_f32 v[64:65], v[64:65], s[28:29] op_sel_hi:[1,0]
	v_pk_mul_f32 v[62:63], v[62:63], s[28:29] op_sel_hi:[1,0]
	v_pk_mul_f32 v[60:61], v[60:61], s[28:29] op_sel_hi:[1,0]
	v_pk_mul_f32 v[58:59], v[58:59], s[28:29] op_sel_hi:[1,0]
	v_pk_mul_f32 v[56:57], v[56:57], s[28:29] op_sel_hi:[1,0]
	v_pk_mul_f32 v[80:81], v[46:47], s[28:29] op_sel_hi:[1,0]
	v_pk_mul_f32 v[82:83], v[44:45], s[28:29] op_sel_hi:[1,0]
	v_pk_mul_f32 v[88:89], v[38:39], s[28:29] op_sel_hi:[1,0]
	v_pk_mul_f32 v[90:91], v[36:37], s[28:29] op_sel_hi:[1,0]
	v_pk_mul_f32 v[36:37], v[54:55], s[28:29] op_sel_hi:[1,0]
	v_pk_mul_f32 v[38:39], v[52:53], s[28:29] op_sel_hi:[1,0]
	v_pk_mul_f32 v[44:45], v[50:51], s[28:29] op_sel_hi:[1,0]
	v_pk_mul_f32 v[46:47], v[48:49], s[28:29] op_sel_hi:[1,0]
	v_pk_mul_f32 v[48:49], v[30:31], s[28:29] op_sel_hi:[1,0]
	v_pk_mul_f32 v[50:51], v[28:29], s[28:29] op_sel_hi:[1,0]
	v_pk_mul_f32 v[52:53], v[22:23], s[28:29] op_sel_hi:[1,0]
	v_pk_mul_f32 v[54:55], v[20:21], s[28:29] op_sel_hi:[1,0]
	v_pk_mul_f32 v[20:21], v[42:43], s[28:29] op_sel_hi:[1,0]
	v_pk_mul_f32 v[22:23], v[40:41], s[28:29] op_sel_hi:[1,0]
	v_pk_mul_f32 v[28:29], v[34:35], s[28:29] op_sel_hi:[1,0]
	v_pk_mul_f32 v[30:31], v[32:33], s[28:29] op_sel_hi:[1,0]
	v_pk_mul_f32 v[32:33], v[14:15], s[28:29] op_sel_hi:[1,0]
	v_pk_mul_f32 v[34:35], v[12:13], s[28:29] op_sel_hi:[1,0]
	v_pk_mul_f32 v[40:41], v[10:11], s[28:29] op_sel_hi:[1,0]
	v_pk_mul_f32 v[42:43], v[8:9], s[28:29] op_sel_hi:[1,0]
	v_pk_mul_f32 v[8:9], v[26:27], s[28:29] op_sel_hi:[1,0]
	v_pk_mul_f32 v[10:11], v[24:25], s[28:29] op_sel_hi:[1,0]
	v_pk_mul_f32 v[12:13], v[18:19], s[28:29] op_sel_hi:[1,0]
	v_pk_mul_f32 v[14:15], v[16:17], s[28:29] op_sel_hi:[1,0]
	v_pk_mul_f32 v[6:7], v[6:7], s[28:29] op_sel_hi:[1,0]
	v_pk_mul_f32 v[4:5], v[4:5], s[28:29] op_sel_hi:[1,0]
	v_pk_mul_f32 v[2:3], v[2:3], s[28:29] op_sel_hi:[1,0]
	v_pk_mul_f32 v[0:1], v[0:1], s[28:29] op_sel_hi:[1,0]
	v_readlane_b32 s81, v254, 46
	v_readlane_b32 s82, v254, 47
	v_readlane_b32 s83, v254, 48
	v_readlane_b32 s84, v254, 49
	v_readlane_b32 s85, v254, 50
	v_readlane_b32 s86, v254, 51
	v_readlane_b32 s87, v254, 52
	v_readlane_b32 s88, v254, 53
	v_readlane_b32 s89, v254, 54
	v_readlane_b32 s92, v254, 57
	v_readlane_b32 s93, v254, 58
	v_readlane_b32 s94, v254, 59
	v_readlane_b32 s95, v254, 60
	v_readlane_b32 s90, v254, 55
	v_readlane_b32 s91, v254, 56

; #define PG8_STAGE(bufoff, gbase, voff) do { _Pragma("unroll") for (int _i = 0; _i < 2; ++_i) \
;         __builtin_amdgcn_global_load_lds((const unsigned*)((const char*)(gbase) + (voff)[_i]), (PG8_LAS unsigned*)(lds + (bufoff) + ldsw + _i * 8192), 16, 0, 0); } while (0)
; #define PG8_LDA(dst, b, h) do { _Pragma("unroll") for (int m = 0; m < 4; ++m) _Pragma("unroll") for (int k = 0; k < 2; ++k) dst[m][k] = *(const PG8_LAS bf16x8*)(lds + PG8_SA(b, h) + aoff + m * 2048 + k * 1024); } while (0)
; #define PG8_LDB(dst, b, h) do { _Pragma("unroll") for (int n = 0; n < 2; ++n) _Pragma("unroll") for (int k = 0; k < 2; ++k) dst[n][k] = *(const PG8_LAS bf16x8*)(lds + PG8_SB(b, h) + boff + n * 2048 + k * 1024); } while (0)
; #define PG8_MMA(ai, bj, At, Bt) do { __builtin_amdgcn_s_setprio(1); _Pragma("unroll") for (int m = 0; m < 4; ++m) _Pragma("unroll") for (int n = 0; n < 2; ++n) _Pragma("unroll") for (int k = 0; k < 2; ++k) \
;         acc[ai][bj][m][n] = __builtin_amdgcn_mfma_f32_16x16x32_bf16(Bt[n][k], At[m][k], acc[ai][bj][m][n], 0, 0, 0); __builtin_amdgcn_s_setprio(0); } while (0)
; #define PG8_WAIT_V(n) asm volatile("s_waitcnt vmcnt(" #n ")" ::: "memory")
; #define PG8_WAIT_L(n) asm volatile("s_waitcnt lgkmcnt(" #n ")" ::: "memory")
; #define PG8_BAR __builtin_amdgcn_s_barrier()
; #define PG8_SCHED __builtin_amdgcn_sched_barrier(0)
; template <class Epi, class Sched, bool ALIGN_EPI = false, bool SP2 = false>
; __device__ __forceinline__ void gemm_phase(PG8_LAS unsigned char* lds, const Gemm g, const Sched& S, const Epi& E) {
;     ...
;             const bool last = (t == nt - 2);
;             const char* a1 = cA + (size_t)(t + 1) * kstep;
;             const char* a2 = last ? nA : cA + (size_t)(t + 2) * kstep; const char* b2 = last ? nB : cB + (size_t)(t + 2) * kstep;
;             const char* a3 = a2 + kstep; const char* b3 = b2 + kstep;
;             if (last && has_next) S.a_ready(nxt);
;             if constexpr (SP2) {
;             PG8_LDB(B0, 0, 0); PG8_LDB(B1, 0, 1); PG8_SCHED; PG8_LDA(At, 0, 0); PG8_STAGE(PG8_SA(1, 1), a1 + hstep, voffA);
;             PG8_WAIT_V(8); PG8_WAIT_L(0); PG8_BAR; PG8_MMA(0, 0, At, B0); PG8_MMA(0, 1, At, B1); PG8_BAR; PG8_SCHED;
;             PG8_LDA(At, 0, 1); PG8_STAGE(PG8_SB(0, 0), b2, voffB); PG8_STAGE(PG8_SB(0, 1), b2 + hstep, voffB); PG8_STAGE(PG8_SA(0, 0), a2, voffA);
.LBB0_570:
	s_add_u32 s4, s40, 0xfffc0080
	s_addc_u32 s5, s41, -1
	s_add_i32 s28, 0, 0x10000
	s_cmp_eq_u32 s72, 12
	s_cselect_b32 s65, s18, s5
	s_cselect_b32 s64, s19, s4
	v_add_u32_e32 v138, s28, v142
	s_cselect_b32 s5, s13, s71
	s_cselect_b32 s4, s27, s70
	s_add_i32 s48, 0, 0x14000
	ds_read_b128 v[144:147], v138
	ds_read_b128 v[148:151], v138 offset:1024
	ds_read_b128 v[152:155], v138 offset:2048
	ds_read_b128 v[156:159], v138 offset:3072
	v_add_u32_e32 v138, s48, v142
	ds_read_b128 v[160:163], v138
	ds_read_b128 v[164:167], v138 offset:1024
	ds_read_b128 v[168:171], v138 offset:2048
	ds_read_b128 v[172:175], v138 offset:3072
	v_lshl_add_u64 v[138:139], s[40:41], 0, v[134:135]
	s_add_i32 m0, s25, 0xc000
	ds_read_b128 v[182:185], v143
	ds_read_b128 v[186:189], v143 offset:1024
	ds_read_b128 v[190:193], v143 offset:2048
	ds_read_b128 v[194:197], v143 offset:3072
	ds_read_b128 v[198:201], v143 offset:4096
	ds_read_b128 v[202:205], v143 offset:5120
	ds_read_b128 v[206:209], v143 offset:6144
	ds_read_b128 v[210:213], v143 offset:7168
	global_load_lds_dwordx4 v[138:139], off
	v_lshl_add_u64 v[138:139], s[40:41], 0, v[136:137]
	s_add_i32 m0, s25, 0xe000
	s_nop 0
	global_load_lds_dwordx4 v[138:139], off
	s_waitcnt vmcnt(8)
	s_waitcnt lgkmcnt(0)
	s_barrier
	s_waitcnt lgkmcnt(0)
	v_mfma_f32_16x16x32_bf16 v[124:127], v[144:147], v[182:185], v[124:127]
	v_mfma_f32_16x16x32_bf16 v[120:123], v[152:155], v[182:185], v[120:123]
	v_mfma_f32_16x16x32_bf16 v[116:119], v[144:147], v[190:193], v[116:119]
	v_mfma_f32_16x16x32_bf16 v[108:111], v[152:155], v[190:193], v[108:111]
	v_mfma_f32_16x16x32_bf16 v[100:103], v[144:147], v[198:201], v[100:103]
	v_mfma_f32_16x16x32_bf16 v[92:95], v[152:155], v[198:201], v[92:95]
	v_mfma_f32_16x16x32_bf16 v[84:87], v[144:147], v[206:209], v[84:87]
	v_mfma_f32_16x16x32_bf16 v[76:79], v[152:155], v[206:209], v[76:79]
	v_mfma_f32_16x16x32_bf16 v[124:127], v[148:151], v[186:189], v[124:127]
	v_mfma_f32_16x16x32_bf16 v[120:123], v[156:159], v[186:189], v[120:123]
	v_mfma_f32_16x16x32_bf16 v[116:119], v[148:151], v[194:197], v[116:119]
	v_mfma_f32_16x16x32_bf16 v[108:111], v[156:159], v[194:197], v[108:111]
	v_mfma_f32_16x16x32_bf16 v[100:103], v[148:151], v[202:205], v[100:103]
	v_mfma_f32_16x16x32_bf16 v[92:95], v[156:159], v[202:205], v[92:95]
	v_mfma_f32_16x16x32_bf16 v[84:87], v[148:151], v[210:213], v[84:87]
	v_mfma_f32_16x16x32_bf16 v[76:79], v[156:159], v[210:213], v[76:79]
	v_mfma_f32_16x16x32_bf16 v[112:115], v[160:163], v[182:185], v[112:115]
	v_mfma_f32_16x16x32_bf16 v[104:107], v[168:171], v[182:185], v[104:107]
	v_mfma_f32_16x16x32_bf16 v[96:99], v[160:163], v[190:193], v[96:99]
	v_mfma_f32_16x16x32_bf16 v[88:91], v[168:171], v[190:193], v[88:91]
	v_mfma_f32_16x16x32_bf16 v[80:83], v[160:163], v[198:201], v[80:83]
	v_mfma_f32_16x16x32_bf16 v[72:75], v[168:171], v[198:201], v[72:75]
	v_mfma_f32_16x16x32_bf16 v[68:71], v[160:163], v[206:209], v[68:71]
	v_mfma_f32_16x16x32_bf16 v[64:67], v[168:171], v[206:209], v[64:67]
	v_mfma_f32_16x16x32_bf16 v[112:115], v[164:167], v[186:189], v[112:115]
	v_mfma_f32_16x16x32_bf16 v[104:107], v[172:175], v[186:189], v[104:107]
	v_mfma_f32_16x16x32_bf16 v[96:99], v[164:167], v[194:197], v[96:99]
	v_mfma_f32_16x16x32_bf16 v[88:91], v[172:175], v[194:197], v[88:91]
	v_mfma_f32_16x16x32_bf16 v[80:83], v[164:167], v[202:205], v[80:83]
	v_mfma_f32_16x16x32_bf16 v[72:75], v[172:175], v[202:205], v[72:75]
	v_mfma_f32_16x16x32_bf16 v[68:71], v[164:167], v[210:213], v[68:71]
	v_mfma_f32_16x16x32_bf16 v[64:67], v[172:175], v[210:213], v[64:67]
	s_barrier
	s_add_i32 s28, s28, s24
	v_lshl_add_u64 v[138:139], s[4:5], 0, v[176:177]
	s_mov_b32 m0, s28
	ds_read_b128 v[182:185], v143 offset:16384
	ds_read_b128 v[186:189], v143 offset:17408
	ds_read_b128 v[190:193], v143 offset:18432
	ds_read_b128 v[194:197], v143 offset:19456
	ds_read_b128 v[198:201], v143 offset:20480
	ds_read_b128 v[202:205], v143 offset:21504
	ds_read_b128 v[206:209], v143 offset:22528
	ds_read_b128 v[210:213], v143 offset:23552
	global_load_lds_dwordx4 v[138:139], off
	s_add_i32 m0, s28, 0x2000
	s_add_u32 s38, s4, 0x40000
	v_lshl_add_u64 v[214:215], s[4:5], 0, v[128:129]
	s_addc_u32 s39, s5, 0
	s_add_i32 s28, s48, s24
	global_load_lds_dwordx4 v[214:215], off
	v_lshl_add_u64 v[216:217], s[38:39], 0, v[176:177]
	s_mov_b32 m0, s28
	v_lshl_add_u64 v[218:219], s[64:65], 0, v[130:131]
	global_load_lds_dwordx4 v[216:217], off
	v_lshl_add_u64 v[216:217], s[38:39], 0, v[128:129]
	s_add_i32 m0, s28, 0x2000
	s_nop 0
	global_load_lds_dwordx4 v[216:217], off
	v_lshl_add_u64 v[216:217], s[64:65], 0, v[132:133]
	s_mov_b32 m0, s25
	s_nop 0
	global_load_lds_dwordx4 v[216:217], off
	s_mov_b32 m0, s30
	s_nop 0
	global_load_lds_dwordx4 v[218:219], off
	s_waitcnt vmcnt(8)
	s_waitcnt lgkmcnt(0)
	s_barrier
; #define PG8_STAGE(bufoff, gbase, voff) do { _Pragma("unroll") for (int _i = 0; _i < 2; ++_i) \
;         __builtin_amdgcn_global_load_lds((const unsigned*)((const char*)(gbase) + (voff)[_i]), (PG8_LAS unsigned*)(lds + (bufoff) + ldsw + _i * 8192), 16, 0, 0); } while (0)
; #define PG8_LDA(dst, b, h) do { _Pragma("unroll") for (int m = 0; m < 4; ++m) _Pragma("unroll") for (int k = 0; k < 2; ++k) dst[m][k] = *(const PG8_LAS bf16x8*)(lds + PG8_SA(b, h) + aoff + m * 2048 + k * 1024); } while (0)
; #define PG8_LDB(dst, b, h) do { _Pragma("unroll") for (int n = 0; n < 2; ++n) _Pragma("unroll") for (int k = 0; k < 2; ++k) dst[n][k] = *(const PG8_LAS bf16x8*)(lds + PG8_SB(b, h) + boff + n * 2048 + k * 1024); } while (0)
; #define PG8_MMA(ai, bj, At, Bt) do { __builtin_amdgcn_s_setprio(1); _Pragma("unroll") for (int m = 0; m < 4; ++m) _Pragma("unroll") for (int n = 0; n < 2; ++n) _Pragma("unroll") for (int k = 0; k < 2; ++k) \
;         acc[ai][bj][m][n] = __builtin_amdgcn_mfma_f32_16x16x32_bf16(Bt[n][k], At[m][k], acc[ai][bj][m][n], 0, 0, 0); __builtin_amdgcn_s_setprio(0); } while (0)
; #define PG8_WAIT_V(n) asm volatile("s_waitcnt vmcnt(" #n ")" ::: "memory")
; #define PG8_WAIT_L(n) asm volatile("s_waitcnt lgkmcnt(" #n ")" ::: "memory")
; #define PG8_BAR __builtin_amdgcn_s_barrier()
; #define PG8_SCHED __builtin_amdgcn_sched_barrier(0)
; template <class Epi, class Sched, bool ALIGN_EPI = false, bool SP2 = false>
; __device__ __forceinline__ void gemm_phase(PG8_LAS unsigned char* lds, const Gemm g, const Sched& S, const Epi& E) {
;     ...
;             PG8_WAIT_V(8); PG8_WAIT_L(0); PG8_BAR; PG8_MMA(1, 0, At, B0); PG8_MMA(1, 1, At, B1); PG8_BAR; PG8_SCHED;
;             PG8_LDB(B0, 1, 0); PG8_LDB(B1, 1, 1); PG8_SCHED; PG8_LDA(At, 1, 0); PG8_STAGE(PG8_SA(0, 1), a2 + hstep, voffA);
;             PG8_WAIT_V(8); PG8_WAIT_L(0); PG8_BAR; PG8_MMA(0, 0, At, B0); PG8_MMA(0, 1, At, B1); PG8_BAR; PG8_SCHED;
	s_waitcnt lgkmcnt(0)
	v_mfma_f32_16x16x32_bf16 v[60:63], v[144:147], v[182:185], v[60:63]
	v_mfma_f32_16x16x32_bf16 v[56:59], v[152:155], v[182:185], v[56:59]
	v_mfma_f32_16x16x32_bf16 v[52:55], v[144:147], v[190:193], v[52:55]
	v_mfma_f32_16x16x32_bf16 v[44:47], v[152:155], v[190:193], v[44:47]
	v_mfma_f32_16x16x32_bf16 v[36:39], v[144:147], v[198:201], v[36:39]
	v_mfma_f32_16x16x32_bf16 v[28:31], v[152:155], v[198:201], v[28:31]
	v_mfma_f32_16x16x32_bf16 v[20:23], v[144:147], v[206:209], v[20:23]
	v_mfma_f32_16x16x32_bf16 v[12:15], v[152:155], v[206:209], v[12:15]
	v_mfma_f32_16x16x32_bf16 v[60:63], v[148:151], v[186:189], v[60:63]
	v_mfma_f32_16x16x32_bf16 v[56:59], v[156:159], v[186:189], v[56:59]
	v_mfma_f32_16x16x32_bf16 v[52:55], v[148:151], v[194:197], v[52:55]
	v_mfma_f32_16x16x32_bf16 v[44:47], v[156:159], v[194:197], v[44:47]
	v_mfma_f32_16x16x32_bf16 v[36:39], v[148:151], v[202:205], v[36:39]
	v_mfma_f32_16x16x32_bf16 v[28:31], v[156:159], v[202:205], v[28:31]
	v_mfma_f32_16x16x32_bf16 v[20:23], v[148:151], v[210:213], v[20:23]
	v_mfma_f32_16x16x32_bf16 v[12:15], v[156:159], v[210:213], v[12:15]
	v_mfma_f32_16x16x32_bf16 v[48:51], v[160:163], v[182:185], v[48:51]
	v_mfma_f32_16x16x32_bf16 v[40:43], v[168:171], v[182:185], v[40:43]
	v_mfma_f32_16x16x32_bf16 v[32:35], v[160:163], v[190:193], v[32:35]
	v_mfma_f32_16x16x32_bf16 v[24:27], v[168:171], v[190:193], v[24:27]
	v_mfma_f32_16x16x32_bf16 v[16:19], v[160:163], v[198:201], v[16:19]
	v_mfma_f32_16x16x32_bf16 v[8:11], v[168:171], v[198:201], v[8:11]
	v_mfma_f32_16x16x32_bf16 v[4:7], v[160:163], v[206:209], v[4:7]
	v_mfma_f32_16x16x32_bf16 v[0:3], v[168:171], v[206:209], v[0:3]
	v_mfma_f32_16x16x32_bf16 v[48:51], v[164:167], v[186:189], v[48:51]
	v_mfma_f32_16x16x32_bf16 v[40:43], v[172:175], v[186:189], v[40:43]
	v_mfma_f32_16x16x32_bf16 v[32:35], v[164:167], v[194:197], v[32:35]
	v_mfma_f32_16x16x32_bf16 v[24:27], v[172:175], v[194:197], v[24:27]
	v_mfma_f32_16x16x32_bf16 v[16:19], v[164:167], v[202:205], v[16:19]
	v_mfma_f32_16x16x32_bf16 v[8:11], v[172:175], v[202:205], v[8:11]
	v_mfma_f32_16x16x32_bf16 v[4:7], v[164:167], v[210:213], v[4:7]
	v_mfma_f32_16x16x32_bf16 v[0:3], v[172:175], v[210:213], v[0:3]
	s_barrier
	s_add_i32 s28, 0, 0x18000
	s_add_i32 s48, 0, 0x1c000
	v_add_u32_e32 v156, s28, v142
	v_add_u32_e32 v172, s48, v142
	ds_read_b128 v[144:147], v156
	ds_read_b128 v[148:151], v156 offset:1024
	ds_read_b128 v[152:155], v156 offset:2048
	ds_read_b128 v[156:159], v156 offset:3072
	ds_read_b128 v[160:163], v172
	ds_read_b128 v[164:167], v172 offset:1024
	ds_read_b128 v[168:171], v172 offset:2048
	ds_read_b128 v[172:175], v172 offset:3072
	s_add_u32 s38, s64, 0x40000
	s_addc_u32 s39, s65, 0
	s_mov_b32 m0, s31
	v_lshl_add_u64 v[220:221], s[38:39], 0, v[132:133]
	ds_read_b128 v[182:185], v143 offset:32768
	ds_read_b128 v[186:189], v143 offset:33792
	ds_read_b128 v[190:193], v143 offset:34816
	ds_read_b128 v[194:197], v143 offset:35840
	ds_read_b128 v[198:201], v143 offset:36864
	ds_read_b128 v[202:205], v143 offset:37888
	ds_read_b128 v[206:209], v143 offset:38912
	ds_read_b128 v[210:213], v143 offset:39936
	global_load_lds_dwordx4 v[220:221], off
	v_lshl_add_u64 v[220:221], s[38:39], 0, v[130:131]
	s_mov_b32 m0, s42
	s_nop 0
	global_load_lds_dwordx4 v[220:221], off
	s_waitcnt vmcnt(8)
	s_waitcnt lgkmcnt(0)
	s_barrier
	s_waitcnt lgkmcnt(0)
	v_mfma_f32_16x16x32_bf16 v[124:127], v[144:147], v[182:185], v[124:127]
	v_mfma_f32_16x16x32_bf16 v[120:123], v[152:155], v[182:185], v[120:123]
	v_mfma_f32_16x16x32_bf16 v[116:119], v[144:147], v[190:193], v[116:119]
	v_mfma_f32_16x16x32_bf16 v[108:111], v[152:155], v[190:193], v[108:111]
	v_mfma_f32_16x16x32_bf16 v[100:103], v[144:147], v[198:201], v[100:103]
	v_mfma_f32_16x16x32_bf16 v[92:95], v[152:155], v[198:201], v[92:95]
	v_mfma_f32_16x16x32_bf16 v[84:87], v[144:147], v[206:209], v[84:87]
	v_mfma_f32_16x16x32_bf16 v[76:79], v[152:155], v[206:209], v[76:79]
	v_mfma_f32_16x16x32_bf16 v[124:127], v[148:151], v[186:189], v[124:127]
	v_mfma_f32_16x16x32_bf16 v[120:123], v[156:159], v[186:189], v[120:123]
	v_mfma_f32_16x16x32_bf16 v[116:119], v[148:151], v[194:197], v[116:119]
	v_mfma_f32_16x16x32_bf16 v[108:111], v[156:159], v[194:197], v[108:111]
	v_mfma_f32_16x16x32_bf16 v[100:103], v[148:151], v[202:205], v[100:103]
	v_mfma_f32_16x16x32_bf16 v[92:95], v[156:159], v[202:205], v[92:95]
	v_mfma_f32_16x16x32_bf16 v[84:87], v[148:151], v[210:213], v[84:87]
	v_mfma_f32_16x16x32_bf16 v[76:79], v[156:159], v[210:213], v[76:79]
	v_mfma_f32_16x16x32_bf16 v[112:115], v[160:163], v[182:185], v[112:115]
	v_mfma_f32_16x16x32_bf16 v[104:107], v[168:171], v[182:185], v[104:107]
	v_mfma_f32_16x16x32_bf16 v[96:99], v[160:163], v[190:193], v[96:99]
	v_mfma_f32_16x16x32_bf16 v[88:91], v[168:171], v[190:193], v[88:91]
	v_mfma_f32_16x16x32_bf16 v[80:83], v[160:163], v[198:201], v[80:83]
	v_mfma_f32_16x16x32_bf16 v[72:75], v[168:171], v[198:201], v[72:75]
	v_mfma_f32_16x16x32_bf16 v[68:71], v[160:163], v[206:209], v[68:71]
	v_mfma_f32_16x16x32_bf16 v[64:67], v[168:171], v[206:209], v[64:67]
	v_mfma_f32_16x16x32_bf16 v[112:115], v[164:167], v[186:189], v[112:115]
	v_mfma_f32_16x16x32_bf16 v[104:107], v[172:175], v[186:189], v[104:107]
	v_mfma_f32_16x16x32_bf16 v[96:99], v[164:167], v[194:197], v[96:99]
	v_mfma_f32_16x16x32_bf16 v[88:91], v[172:175], v[194:197], v[88:91]
	v_mfma_f32_16x16x32_bf16 v[80:83], v[164:167], v[202:205], v[80:83]
	v_mfma_f32_16x16x32_bf16 v[72:75], v[172:175], v[202:205], v[72:75]
	v_mfma_f32_16x16x32_bf16 v[68:71], v[164:167], v[210:213], v[68:71]
	v_mfma_f32_16x16x32_bf16 v[64:67], v[172:175], v[210:213], v[64:67]
	s_barrier
; #define PG8_STAGE(bufoff, gbase, voff) do { _Pragma("unroll") for (int _i = 0; _i < 2; ++_i) \
;         __builtin_amdgcn_global_load_lds((const unsigned*)((const char*)(gbase) + (voff)[_i]), (PG8_LAS unsigned*)(lds + (bufoff) + ldsw + _i * 8192), 16, 0, 0); } while (0)
; #define PG8_LDA(dst, b, h) do { _Pragma("unroll") for (int m = 0; m < 4; ++m) _Pragma("unroll") for (int k = 0; k < 2; ++k) dst[m][k] = *(const PG8_LAS bf16x8*)(lds + PG8_SA(b, h) + aoff + m * 2048 + k * 1024); } while (0)
; #define PG8_MMA(ai, bj, At, Bt) do { __builtin_amdgcn_s_setprio(1); _Pragma("unroll") for (int m = 0; m < 4; ++m) _Pragma("unroll") for (int n = 0; n < 2; ++n) _Pragma("unroll") for (int k = 0; k < 2; ++k) \
;         acc[ai][bj][m][n] = __builtin_amdgcn_mfma_f32_16x16x32_bf16(Bt[n][k], At[m][k], acc[ai][bj][m][n], 0, 0, 0); __builtin_amdgcn_s_setprio(0); } while (0)
; #define PG8_WAIT_V(n) asm volatile("s_waitcnt vmcnt(" #n ")" ::: "memory")
; #define PG8_WAIT_L(n) asm volatile("s_waitcnt lgkmcnt(" #n ")" ::: "memory")
; #define PG8_BAR __builtin_amdgcn_s_barrier()
; #define PG8_SCHED __builtin_amdgcn_sched_barrier(0)
; template <class Epi, class Sched, bool ALIGN_EPI = false, bool SP2 = false>
; __device__ __forceinline__ void gemm_phase(PG8_LAS unsigned char* lds, const Gemm g, const Sched& S, const Epi& E) {
;     ...
;             PG8_LDA(At, 1, 1); PG8_STAGE(PG8_SB(1, 0), b3, voffB); PG8_STAGE(PG8_SB(1, 1), b3 + hstep, voffB); PG8_STAGE(PG8_SA(1, 0), a3, voffA);
;             PG8_WAIT_V(8); PG8_WAIT_L(0); PG8_BAR; PG8_MMA(1, 0, At, B0); PG8_MMA(1, 1, At, B1); PG8_BAR; PG8_SCHED;
	s_add_i32 s28, s28, s24
	v_lshl_add_u64 v[138:139], v[138:139], 0, s[44:45]
	s_mov_b32 m0, s28
	ds_read_b128 v[182:185], v143 offset:49152
	ds_read_b128 v[186:189], v143 offset:50176
	ds_read_b128 v[190:193], v143 offset:51200
	ds_read_b128 v[194:197], v143 offset:52224
	ds_read_b128 v[198:201], v143 offset:53248
	ds_read_b128 v[202:205], v143 offset:54272
	ds_read_b128 v[206:209], v143 offset:55296
	ds_read_b128 v[210:213], v143 offset:56320
	global_load_lds_dwordx4 v[138:139], off
	s_add_i32 m0, s28, 0x2000
	s_add_u32 s4, s4, 0x40080
	v_lshl_add_u64 v[138:139], v[214:215], 0, s[44:45]
	s_addc_u32 s5, s5, 0
	s_add_i32 s28, s48, s24
	global_load_lds_dwordx4 v[138:139], off
	v_lshl_add_u64 v[138:139], s[4:5], 0, v[176:177]
	s_mov_b32 m0, s28
	s_nop 0
	global_load_lds_dwordx4 v[138:139], off
	v_lshl_add_u64 v[138:139], s[4:5], 0, v[128:129]
	s_add_i32 m0, s28, 0x2000
	s_nop 0
	global_load_lds_dwordx4 v[138:139], off
	v_lshl_add_u64 v[138:139], v[216:217], 0, s[44:45]
	s_mov_b32 m0, s63
	s_nop 0
	global_load_lds_dwordx4 v[138:139], off
	v_lshl_add_u64 v[138:139], v[218:219], 0, s[44:45]
	s_mov_b32 m0, s66
	s_nop 0
	global_load_lds_dwordx4 v[138:139], off
	s_waitcnt vmcnt(8)
	s_waitcnt lgkmcnt(0)
	s_barrier
	s_waitcnt lgkmcnt(0)
	v_mfma_f32_16x16x32_bf16 v[60:63], v[144:147], v[182:185], v[60:63]
	v_mfma_f32_16x16x32_bf16 v[56:59], v[152:155], v[182:185], v[56:59]
	v_mfma_f32_16x16x32_bf16 v[52:55], v[144:147], v[190:193], v[52:55]
	v_mfma_f32_16x16x32_bf16 v[44:47], v[152:155], v[190:193], v[44:47]
	v_mfma_f32_16x16x32_bf16 v[36:39], v[144:147], v[198:201], v[36:39]
	v_mfma_f32_16x16x32_bf16 v[28:31], v[152:155], v[198:201], v[28:31]
	v_mfma_f32_16x16x32_bf16 v[20:23], v[144:147], v[206:209], v[20:23]
	v_mfma_f32_16x16x32_bf16 v[12:15], v[152:155], v[206:209], v[12:15]
	v_mfma_f32_16x16x32_bf16 v[60:63], v[148:151], v[186:189], v[60:63]
	v_mfma_f32_16x16x32_bf16 v[56:59], v[156:159], v[186:189], v[56:59]
	v_mfma_f32_16x16x32_bf16 v[52:55], v[148:151], v[194:197], v[52:55]
	v_mfma_f32_16x16x32_bf16 v[44:47], v[156:159], v[194:197], v[44:47]
	v_mfma_f32_16x16x32_bf16 v[36:39], v[148:151], v[202:205], v[36:39]
	v_mfma_f32_16x16x32_bf16 v[28:31], v[156:159], v[202:205], v[28:31]
	v_mfma_f32_16x16x32_bf16 v[20:23], v[148:151], v[210:213], v[20:23]
	v_mfma_f32_16x16x32_bf16 v[12:15], v[156:159], v[210:213], v[12:15]
	v_mfma_f32_16x16x32_bf16 v[48:51], v[160:163], v[182:185], v[48:51]
	v_mfma_f32_16x16x32_bf16 v[40:43], v[168:171], v[182:185], v[40:43]
	v_mfma_f32_16x16x32_bf16 v[32:35], v[160:163], v[190:193], v[32:35]
	v_mfma_f32_16x16x32_bf16 v[24:27], v[168:171], v[190:193], v[24:27]
	v_mfma_f32_16x16x32_bf16 v[16:19], v[160:163], v[198:201], v[16:19]
	v_mfma_f32_16x16x32_bf16 v[8:11], v[168:171], v[198:201], v[8:11]
	v_mfma_f32_16x16x32_bf16 v[4:7], v[160:163], v[206:209], v[4:7]
	v_mfma_f32_16x16x32_bf16 v[0:3], v[168:171], v[206:209], v[0:3]
	v_mfma_f32_16x16x32_bf16 v[48:51], v[164:167], v[186:189], v[48:51]
	v_mfma_f32_16x16x32_bf16 v[40:43], v[172:175], v[186:189], v[40:43]
	s_add_i32 s72, s72, 2
	v_mfma_f32_16x16x32_bf16 v[32:35], v[164:167], v[194:197], v[32:35]
	s_add_u32 s40, s40, 0x100
	v_mfma_f32_16x16x32_bf16 v[24:27], v[172:175], v[194:197], v[24:27]
	s_addc_u32 s41, s41, 0
	v_mfma_f32_16x16x32_bf16 v[16:19], v[164:167], v[202:205], v[16:19]
	s_add_u32 s70, s70, 0x100
	v_mfma_f32_16x16x32_bf16 v[8:11], v[172:175], v[202:205], v[8:11]
	s_addc_u32 s71, s71, 0
	v_mfma_f32_16x16x32_bf16 v[4:7], v[164:167], v[210:213], v[4:7]
	s_cmp_gt_u32 s72, 13
	v_mfma_f32_16x16x32_bf16 v[0:3], v[172:175], v[210:213], v[0:3]
	s_barrier
	s_cbranch_scc0 .LBB0_570

; #define PG8_STAGE(bufoff, gbase, voff) do { _Pragma("unroll") for (int _i = 0; _i < 2; ++_i) \
;         __builtin_amdgcn_global_load_lds((const unsigned*)((const char*)(gbase) + (voff)[_i]), (PG8_LAS unsigned*)(lds + (bufoff) + ldsw + _i * 8192), 16, 0, 0); } while (0)
; #define PG8_LDA(dst, b, h) do { _Pragma("unroll") for (int m = 0; m < 4; ++m) _Pragma("unroll") for (int k = 0; k < 2; ++k) dst[m][k] = *(const PG8_LAS bf16x8*)(lds + PG8_SA(b, h) + aoff + m * 2048 + k * 1024); } while (0)
; #define PG8_LDB(dst, b, h) do { _Pragma("unroll") for (int n = 0; n < 2; ++n) _Pragma("unroll") for (int k = 0; k < 2; ++k) dst[n][k] = *(const PG8_LAS bf16x8*)(lds + PG8_SB(b, h) + boff + n * 2048 + k * 1024); } while (0)
; #define PG8_MMA(ai, bj, At, Bt) do { __builtin_amdgcn_s_setprio(1); _Pragma("unroll") for (int m = 0; m < 4; ++m) _Pragma("unroll") for (int n = 0; n < 2; ++n) _Pragma("unroll") for (int k = 0; k < 2; ++k) \
;         acc[ai][bj][m][n] = __builtin_amdgcn_mfma_f32_16x16x32_bf16(Bt[n][k], At[m][k], acc[ai][bj][m][n], 0, 0, 0); __builtin_amdgcn_s_setprio(0); } while (0)
; #define PG8_WAIT_V(n) asm volatile("s_waitcnt vmcnt(" #n ")" ::: "memory")
; #define PG8_WAIT_L(n) asm volatile("s_waitcnt lgkmcnt(" #n ")" ::: "memory")
; template <class Epi, class Sched, bool ALIGN_EPI = false, bool SP2 = false>
; __device__ __forceinline__ void gemm_phase(PG8_LAS unsigned char* lds, const Gemm g, const Sched& S, const Epi& E) {
;     ...
;             const bool last = (t == nt - 2);
;             const char* a1 = cA + (size_t)(t + 1) * kstep;
;             const char* a2 = last ? nA : cA + (size_t)(t + 2) * kstep; const char* b2 = last ? nB : cB + (size_t)(t + 2) * kstep;
;             const char* a3 = a2 + kstep; const char* b3 = b2 + kstep;
;             if (last && has_next) S.a_ready(nxt);
;             if constexpr (SP2) {
;             PG8_LDB(B0, 0, 0); PG8_LDB(B1, 0, 1); PG8_SCHED; PG8_LDA(At, 0, 0); PG8_STAGE(PG8_SA(1, 1), a1 + hstep, voffA);
;             PG8_WAIT_V(8); PG8_WAIT_L(0); PG8_BAR; PG8_MMA(0, 0, At, B0); PG8_MMA(0, 1, At, B1); PG8_BAR; PG8_SCHED;
;             PG8_LDA(At, 0, 1); PG8_STAGE(PG8_SB(0, 0), b2, voffB); PG8_STAGE(PG8_SB(0, 1), b2 + hstep, voffB); PG8_STAGE(PG8_SA(0, 0), a2, voffA);
;             PG8_WAIT_V(8); PG8_WAIT_L(0); PG8_BAR; PG8_MMA(1, 0, At, B0); PG8_MMA(1, 1, At, B1); PG8_BAR; PG8_SCHED;
.Lg2_peel:
	s_add_u32 s4, s40, 0xfffc0080
	s_addc_u32 s5, s41, -1
	s_add_i32 s28, 0, 0x10000
	s_cmp_eq_u32 s72, 12
	s_cselect_b32 s65, s18, s5
	s_cselect_b32 s64, s19, s4
	v_add_u32_e32 v138, s28, v142
	s_cselect_b32 s5, s13, s71
	s_cselect_b32 s4, s27, s70
	s_add_i32 s48, 0, 0x14000
	ds_read_b128 v[144:147], v138
	ds_read_b128 v[148:151], v138 offset:1024
	ds_read_b128 v[152:155], v138 offset:2048
	ds_read_b128 v[156:159], v138 offset:3072
	v_add_u32_e32 v138, s48, v142
	ds_read_b128 v[160:163], v138
	ds_read_b128 v[164:167], v138 offset:1024
	ds_read_b128 v[168:171], v138 offset:2048
	ds_read_b128 v[172:175], v138 offset:3072
	v_lshl_add_u64 v[138:139], s[40:41], 0, v[134:135]
	s_add_i32 m0, s25, 0xc000
	ds_read_b128 v[182:185], v143
	ds_read_b128 v[186:189], v143 offset:1024
	ds_read_b128 v[190:193], v143 offset:2048
	ds_read_b128 v[194:197], v143 offset:3072
	ds_read_b128 v[198:201], v143 offset:4096
	ds_read_b128 v[202:205], v143 offset:5120
	ds_read_b128 v[206:209], v143 offset:6144
	ds_read_b128 v[210:213], v143 offset:7168
	global_load_lds_dwordx4 v[138:139], off
	v_lshl_add_u64 v[138:139], s[40:41], 0, v[136:137]
	s_add_i32 m0, s25, 0xe000
	s_nop 0
	global_load_lds_dwordx4 v[138:139], off
	s_waitcnt vmcnt(24)
	s_waitcnt lgkmcnt(0)
	s_barrier
	s_waitcnt lgkmcnt(0)
	v_mfma_f32_16x16x32_bf16 v[124:127], v[144:147], v[182:185], 0
	v_mfma_f32_16x16x32_bf16 v[120:123], v[152:155], v[182:185], 0
	v_mfma_f32_16x16x32_bf16 v[116:119], v[144:147], v[190:193], 0
	v_mfma_f32_16x16x32_bf16 v[108:111], v[152:155], v[190:193], 0
	v_mfma_f32_16x16x32_bf16 v[100:103], v[144:147], v[198:201], 0
	v_mfma_f32_16x16x32_bf16 v[92:95], v[152:155], v[198:201], 0
	v_mfma_f32_16x16x32_bf16 v[84:87], v[144:147], v[206:209], 0
	v_mfma_f32_16x16x32_bf16 v[76:79], v[152:155], v[206:209], 0
	v_mfma_f32_16x16x32_bf16 v[124:127], v[148:151], v[186:189], v[124:127]
	v_mfma_f32_16x16x32_bf16 v[120:123], v[156:159], v[186:189], v[120:123]
	v_mfma_f32_16x16x32_bf16 v[116:119], v[148:151], v[194:197], v[116:119]
	v_mfma_f32_16x16x32_bf16 v[108:111], v[156:159], v[194:197], v[108:111]
	v_mfma_f32_16x16x32_bf16 v[100:103], v[148:151], v[202:205], v[100:103]
	v_mfma_f32_16x16x32_bf16 v[92:95], v[156:159], v[202:205], v[92:95]
	v_mfma_f32_16x16x32_bf16 v[84:87], v[148:151], v[210:213], v[84:87]
	v_mfma_f32_16x16x32_bf16 v[76:79], v[156:159], v[210:213], v[76:79]
	v_mfma_f32_16x16x32_bf16 v[112:115], v[160:163], v[182:185], 0
	v_mfma_f32_16x16x32_bf16 v[104:107], v[168:171], v[182:185], 0
	v_mfma_f32_16x16x32_bf16 v[96:99], v[160:163], v[190:193], 0
	v_mfma_f32_16x16x32_bf16 v[88:91], v[168:171], v[190:193], 0
	v_mfma_f32_16x16x32_bf16 v[80:83], v[160:163], v[198:201], 0
	v_mfma_f32_16x16x32_bf16 v[72:75], v[168:171], v[198:201], 0
	v_mfma_f32_16x16x32_bf16 v[68:71], v[160:163], v[206:209], 0
	v_mfma_f32_16x16x32_bf16 v[64:67], v[168:171], v[206:209], 0
	v_mfma_f32_16x16x32_bf16 v[112:115], v[164:167], v[186:189], v[112:115]
	v_mfma_f32_16x16x32_bf16 v[104:107], v[172:175], v[186:189], v[104:107]
	v_mfma_f32_16x16x32_bf16 v[96:99], v[164:167], v[194:197], v[96:99]
	v_mfma_f32_16x16x32_bf16 v[88:91], v[172:175], v[194:197], v[88:91]
	v_mfma_f32_16x16x32_bf16 v[80:83], v[164:167], v[202:205], v[80:83]
	v_mfma_f32_16x16x32_bf16 v[72:75], v[172:175], v[202:205], v[72:75]
	v_mfma_f32_16x16x32_bf16 v[68:71], v[164:167], v[210:213], v[68:71]
	v_mfma_f32_16x16x32_bf16 v[64:67], v[172:175], v[210:213], v[64:67]
	s_barrier
	s_add_i32 s28, s28, s24
	v_lshl_add_u64 v[138:139], s[4:5], 0, v[176:177]
	s_mov_b32 m0, s28
	ds_read_b128 v[182:185], v143 offset:16384
	ds_read_b128 v[186:189], v143 offset:17408
	ds_read_b128 v[190:193], v143 offset:18432
	ds_read_b128 v[194:197], v143 offset:19456
	ds_read_b128 v[198:201], v143 offset:20480
	ds_read_b128 v[202:205], v143 offset:21504
	ds_read_b128 v[206:209], v143 offset:22528
	ds_read_b128 v[210:213], v143 offset:23552
	global_load_lds_dwordx4 v[138:139], off
	s_add_i32 m0, s28, 0x2000
	s_add_u32 s38, s4, 0x40000
	v_lshl_add_u64 v[214:215], s[4:5], 0, v[128:129]
	s_addc_u32 s39, s5, 0
	s_add_i32 s28, s48, s24
	global_load_lds_dwordx4 v[214:215], off
	v_lshl_add_u64 v[216:217], s[38:39], 0, v[176:177]
	s_mov_b32 m0, s28
	v_lshl_add_u64 v[218:219], s[64:65], 0, v[130:131]
	global_load_lds_dwordx4 v[216:217], off
	v_lshl_add_u64 v[216:217], s[38:39], 0, v[128:129]
	s_add_i32 m0, s28, 0x2000
	s_nop 0
	global_load_lds_dwordx4 v[216:217], off
	v_lshl_add_u64 v[216:217], s[64:65], 0, v[132:133]
	s_mov_b32 m0, s25
	s_nop 0
	global_load_lds_dwordx4 v[216:217], off
	s_mov_b32 m0, s30
	s_nop 0
	global_load_lds_dwordx4 v[218:219], off
	s_waitcnt vmcnt(24)
	s_waitcnt lgkmcnt(0)
	s_barrier
; #define PG8_STAGE(bufoff, gbase, voff) do { _Pragma("unroll") for (int _i = 0; _i < 2; ++_i) \
;         __builtin_amdgcn_global_load_lds((const unsigned*)((const char*)(gbase) + (voff)[_i]), (PG8_LAS unsigned*)(lds + (bufoff) + ldsw + _i * 8192), 16, 0, 0); } while (0)
; #define PG8_LDA(dst, b, h) do { _Pragma("unroll") for (int m = 0; m < 4; ++m) _Pragma("unroll") for (int k = 0; k < 2; ++k) dst[m][k] = *(const PG8_LAS bf16x8*)(lds + PG8_SA(b, h) + aoff + m * 2048 + k * 1024); } while (0)
; #define PG8_LDB(dst, b, h) do { _Pragma("unroll") for (int n = 0; n < 2; ++n) _Pragma("unroll") for (int k = 0; k < 2; ++k) dst[n][k] = *(const PG8_LAS bf16x8*)(lds + PG8_SB(b, h) + boff + n * 2048 + k * 1024); } while (0)
; #define PG8_MMA(ai, bj, At, Bt) do { __builtin_amdgcn_s_setprio(1); _Pragma("unroll") for (int m = 0; m < 4; ++m) _Pragma("unroll") for (int n = 0; n < 2; ++n) _Pragma("unroll") for (int k = 0; k < 2; ++k) \
;         acc[ai][bj][m][n] = __builtin_amdgcn_mfma_f32_16x16x32_bf16(Bt[n][k], At[m][k], acc[ai][bj][m][n], 0, 0, 0); __builtin_amdgcn_s_setprio(0); } while (0)
; #define PG8_WAIT_V(n) asm volatile("s_waitcnt vmcnt(" #n ")" ::: "memory")
; #define PG8_WAIT_L(n) asm volatile("s_waitcnt lgkmcnt(" #n ")" ::: "memory")
; #define PG8_BAR __builtin_amdgcn_s_barrier()
; #define PG8_SCHED __builtin_amdgcn_sched_barrier(0)
; template <class Epi, class Sched, bool ALIGN_EPI = false, bool SP2 = false>
; __device__ __forceinline__ void gemm_phase(PG8_LAS unsigned char* lds, const Gemm g, const Sched& S, const Epi& E) {
;     ...
;             PG8_WAIT_V(8); PG8_WAIT_L(0); PG8_BAR; PG8_MMA(1, 0, At, B0); PG8_MMA(1, 1, At, B1); PG8_BAR; PG8_SCHED;
;             PG8_LDB(B0, 1, 0); PG8_LDB(B1, 1, 1); PG8_SCHED; PG8_LDA(At, 1, 0); PG8_STAGE(PG8_SA(0, 1), a2 + hstep, voffA);
;             PG8_WAIT_V(8); PG8_WAIT_L(0); PG8_BAR; PG8_MMA(0, 0, At, B0); PG8_MMA(0, 1, At, B1); PG8_BAR; PG8_SCHED;
	s_waitcnt lgkmcnt(0)
	v_mfma_f32_16x16x32_bf16 v[60:63], v[144:147], v[182:185], 0
	v_mfma_f32_16x16x32_bf16 v[56:59], v[152:155], v[182:185], 0
	v_mfma_f32_16x16x32_bf16 v[52:55], v[144:147], v[190:193], 0
	v_mfma_f32_16x16x32_bf16 v[44:47], v[152:155], v[190:193], 0
	v_mfma_f32_16x16x32_bf16 v[36:39], v[144:147], v[198:201], 0
	v_mfma_f32_16x16x32_bf16 v[28:31], v[152:155], v[198:201], 0
	v_mfma_f32_16x16x32_bf16 v[20:23], v[144:147], v[206:209], 0
	v_mfma_f32_16x16x32_bf16 v[12:15], v[152:155], v[206:209], 0
	v_mfma_f32_16x16x32_bf16 v[60:63], v[148:151], v[186:189], v[60:63]
	v_mfma_f32_16x16x32_bf16 v[56:59], v[156:159], v[186:189], v[56:59]
	v_mfma_f32_16x16x32_bf16 v[52:55], v[148:151], v[194:197], v[52:55]
	v_mfma_f32_16x16x32_bf16 v[44:47], v[156:159], v[194:197], v[44:47]
	v_mfma_f32_16x16x32_bf16 v[36:39], v[148:151], v[202:205], v[36:39]
	v_mfma_f32_16x16x32_bf16 v[28:31], v[156:159], v[202:205], v[28:31]
	v_mfma_f32_16x16x32_bf16 v[20:23], v[148:151], v[210:213], v[20:23]
	v_mfma_f32_16x16x32_bf16 v[12:15], v[156:159], v[210:213], v[12:15]
	v_mfma_f32_16x16x32_bf16 v[48:51], v[160:163], v[182:185], 0
	v_mfma_f32_16x16x32_bf16 v[40:43], v[168:171], v[182:185], 0
	v_mfma_f32_16x16x32_bf16 v[32:35], v[160:163], v[190:193], 0
	v_mfma_f32_16x16x32_bf16 v[24:27], v[168:171], v[190:193], 0
	v_mfma_f32_16x16x32_bf16 v[16:19], v[160:163], v[198:201], 0
	v_mfma_f32_16x16x32_bf16 v[8:11], v[168:171], v[198:201], 0
	v_mfma_f32_16x16x32_bf16 v[4:7], v[160:163], v[206:209], 0
	v_mfma_f32_16x16x32_bf16 v[0:3], v[168:171], v[206:209], 0
	v_mfma_f32_16x16x32_bf16 v[48:51], v[164:167], v[186:189], v[48:51]
	v_mfma_f32_16x16x32_bf16 v[40:43], v[172:175], v[186:189], v[40:43]
	v_mfma_f32_16x16x32_bf16 v[32:35], v[164:167], v[194:197], v[32:35]
	v_mfma_f32_16x16x32_bf16 v[24:27], v[172:175], v[194:197], v[24:27]
	v_mfma_f32_16x16x32_bf16 v[16:19], v[164:167], v[202:205], v[16:19]
	v_mfma_f32_16x16x32_bf16 v[8:11], v[172:175], v[202:205], v[8:11]
	v_mfma_f32_16x16x32_bf16 v[4:7], v[164:167], v[210:213], v[4:7]
	v_mfma_f32_16x16x32_bf16 v[0:3], v[172:175], v[210:213], v[0:3]
	s_barrier
	s_add_i32 s28, 0, 0x18000
	s_add_i32 s48, 0, 0x1c000
	v_add_u32_e32 v156, s28, v142
	v_add_u32_e32 v172, s48, v142
	ds_read_b128 v[144:147], v156
	ds_read_b128 v[148:151], v156 offset:1024
	ds_read_b128 v[152:155], v156 offset:2048
	ds_read_b128 v[156:159], v156 offset:3072
	ds_read_b128 v[160:163], v172
	ds_read_b128 v[164:167], v172 offset:1024
	ds_read_b128 v[168:171], v172 offset:2048
	ds_read_b128 v[172:175], v172 offset:3072
	s_add_u32 s38, s64, 0x40000
	s_addc_u32 s39, s65, 0
	s_mov_b32 m0, s31
	v_lshl_add_u64 v[220:221], s[38:39], 0, v[132:133]
	ds_read_b128 v[182:185], v143 offset:32768
	ds_read_b128 v[186:189], v143 offset:33792
	ds_read_b128 v[190:193], v143 offset:34816
	ds_read_b128 v[194:197], v143 offset:35840
	ds_read_b128 v[198:201], v143 offset:36864
	ds_read_b128 v[202:205], v143 offset:37888
	ds_read_b128 v[206:209], v143 offset:38912
	ds_read_b128 v[210:213], v143 offset:39936
	global_load_lds_dwordx4 v[220:221], off
	v_lshl_add_u64 v[220:221], s[38:39], 0, v[130:131]
	s_mov_b32 m0, s42
	s_nop 0
	global_load_lds_dwordx4 v[220:221], off
	s_waitcnt vmcnt(8)
	s_waitcnt lgkmcnt(0)
	s_barrier
	s_waitcnt lgkmcnt(0)
	v_mfma_f32_16x16x32_bf16 v[124:127], v[144:147], v[182:185], v[124:127]
	v_mfma_f32_16x16x32_bf16 v[120:123], v[152:155], v[182:185], v[120:123]
	v_mfma_f32_16x16x32_bf16 v[116:119], v[144:147], v[190:193], v[116:119]
	v_mfma_f32_16x16x32_bf16 v[108:111], v[152:155], v[190:193], v[108:111]
	v_mfma_f32_16x16x32_bf16 v[100:103], v[144:147], v[198:201], v[100:103]
	v_mfma_f32_16x16x32_bf16 v[92:95], v[152:155], v[198:201], v[92:95]
	v_mfma_f32_16x16x32_bf16 v[84:87], v[144:147], v[206:209], v[84:87]
	v_mfma_f32_16x16x32_bf16 v[76:79], v[152:155], v[206:209], v[76:79]
	v_mfma_f32_16x16x32_bf16 v[124:127], v[148:151], v[186:189], v[124:127]
	v_mfma_f32_16x16x32_bf16 v[120:123], v[156:159], v[186:189], v[120:123]
	v_mfma_f32_16x16x32_bf16 v[116:119], v[148:151], v[194:197], v[116:119]
	v_mfma_f32_16x16x32_bf16 v[108:111], v[156:159], v[194:197], v[108:111]
	v_mfma_f32_16x16x32_bf16 v[100:103], v[148:151], v[202:205], v[100:103]
	v_mfma_f32_16x16x32_bf16 v[92:95], v[156:159], v[202:205], v[92:95]
	v_mfma_f32_16x16x32_bf16 v[84:87], v[148:151], v[210:213], v[84:87]
	v_mfma_f32_16x16x32_bf16 v[76:79], v[156:159], v[210:213], v[76:79]
	v_mfma_f32_16x16x32_bf16 v[112:115], v[160:163], v[182:185], v[112:115]
	v_mfma_f32_16x16x32_bf16 v[104:107], v[168:171], v[182:185], v[104:107]
	v_mfma_f32_16x16x32_bf16 v[96:99], v[160:163], v[190:193], v[96:99]
	v_mfma_f32_16x16x32_bf16 v[88:91], v[168:171], v[190:193], v[88:91]
	v_mfma_f32_16x16x32_bf16 v[80:83], v[160:163], v[198:201], v[80:83]
	v_mfma_f32_16x16x32_bf16 v[72:75], v[168:171], v[198:201], v[72:75]
	v_mfma_f32_16x16x32_bf16 v[68:71], v[160:163], v[206:209], v[68:71]
	v_mfma_f32_16x16x32_bf16 v[64:67], v[168:171], v[206:209], v[64:67]
	v_mfma_f32_16x16x32_bf16 v[112:115], v[164:167], v[186:189], v[112:115]
	v_mfma_f32_16x16x32_bf16 v[104:107], v[172:175], v[186:189], v[104:107]
	v_mfma_f32_16x16x32_bf16 v[96:99], v[164:167], v[194:197], v[96:99]
	v_mfma_f32_16x16x32_bf16 v[88:91], v[172:175], v[194:197], v[88:91]
	v_mfma_f32_16x16x32_bf16 v[80:83], v[164:167], v[202:205], v[80:83]
	v_mfma_f32_16x16x32_bf16 v[72:75], v[172:175], v[202:205], v[72:75]
	v_mfma_f32_16x16x32_bf16 v[68:71], v[164:167], v[210:213], v[68:71]
	v_mfma_f32_16x16x32_bf16 v[64:67], v[172:175], v[210:213], v[64:67]
	s_barrier
; #define PG8_STAGE(bufoff, gbase, voff) do { _Pragma("unroll") for (int _i = 0; _i < 2; ++_i) \
;         __builtin_amdgcn_global_load_lds((const unsigned*)((const char*)(gbase) + (voff)[_i]), (PG8_LAS unsigned*)(lds + (bufoff) + ldsw + _i * 8192), 16, 0, 0); } while (0)
; #define PG8_LDA(dst, b, h) do { _Pragma("unroll") for (int m = 0; m < 4; ++m) _Pragma("unroll") for (int k = 0; k < 2; ++k) dst[m][k] = *(const PG8_LAS bf16x8*)(lds + PG8_SA(b, h) + aoff + m * 2048 + k * 1024); } while (0)
; #define PG8_MMA(ai, bj, At, Bt) do { __builtin_amdgcn_s_setprio(1); _Pragma("unroll") for (int m = 0; m < 4; ++m) _Pragma("unroll") for (int n = 0; n < 2; ++n) _Pragma("unroll") for (int k = 0; k < 2; ++k) \
;         acc[ai][bj][m][n] = __builtin_amdgcn_mfma_f32_16x16x32_bf16(Bt[n][k], At[m][k], acc[ai][bj][m][n], 0, 0, 0); __builtin_amdgcn_s_setprio(0); } while (0)
; #define PG8_WAIT_V(n) asm volatile("s_waitcnt vmcnt(" #n ")" ::: "memory")
; #define PG8_WAIT_L(n) asm volatile("s_waitcnt lgkmcnt(" #n ")" ::: "memory")
; #define PG8_BAR __builtin_amdgcn_s_barrier()
; #define PG8_SCHED __builtin_amdgcn_sched_barrier(0)
; template <class Epi, class Sched, bool ALIGN_EPI = false, bool SP2 = false>
; __device__ __forceinline__ void gemm_phase(PG8_LAS unsigned char* lds, const Gemm g, const Sched& S, const Epi& E) {
;     ...
;             PG8_LDA(At, 1, 1); PG8_STAGE(PG8_SB(1, 0), b3, voffB); PG8_STAGE(PG8_SB(1, 1), b3 + hstep, voffB); PG8_STAGE(PG8_SA(1, 0), a3, voffA);
;             PG8_WAIT_V(8); PG8_WAIT_L(0); PG8_BAR; PG8_MMA(1, 0, At, B0); PG8_MMA(1, 1, At, B1); PG8_BAR; PG8_SCHED;
	s_add_i32 s28, s28, s24
	v_lshl_add_u64 v[138:139], v[138:139], 0, s[44:45]
	s_mov_b32 m0, s28
	ds_read_b128 v[182:185], v143 offset:49152
	ds_read_b128 v[186:189], v143 offset:50176
	ds_read_b128 v[190:193], v143 offset:51200
	ds_read_b128 v[194:197], v143 offset:52224
	ds_read_b128 v[198:201], v143 offset:53248
	ds_read_b128 v[202:205], v143 offset:54272
	ds_read_b128 v[206:209], v143 offset:55296
	ds_read_b128 v[210:213], v143 offset:56320
	global_load_lds_dwordx4 v[138:139], off
	s_add_i32 m0, s28, 0x2000
	s_add_u32 s4, s4, 0x40080
	v_lshl_add_u64 v[138:139], v[214:215], 0, s[44:45]
	s_addc_u32 s5, s5, 0
	s_add_i32 s28, s48, s24
	global_load_lds_dwordx4 v[138:139], off
	v_lshl_add_u64 v[138:139], s[4:5], 0, v[176:177]
	s_mov_b32 m0, s28
	s_nop 0
	global_load_lds_dwordx4 v[138:139], off
	v_lshl_add_u64 v[138:139], s[4:5], 0, v[128:129]
	s_add_i32 m0, s28, 0x2000
	s_nop 0
	global_load_lds_dwordx4 v[138:139], off
	v_lshl_add_u64 v[138:139], v[216:217], 0, s[44:45]
	s_mov_b32 m0, s63
	s_nop 0
	global_load_lds_dwordx4 v[138:139], off
	v_lshl_add_u64 v[138:139], v[218:219], 0, s[44:45]
	s_mov_b32 m0, s66
	s_nop 0
	global_load_lds_dwordx4 v[138:139], off
	s_waitcnt vmcnt(8)
	s_waitcnt lgkmcnt(0)
	s_barrier
	s_waitcnt lgkmcnt(0)
	v_mfma_f32_16x16x32_bf16 v[60:63], v[144:147], v[182:185], v[60:63]
	v_mfma_f32_16x16x32_bf16 v[56:59], v[152:155], v[182:185], v[56:59]
	v_mfma_f32_16x16x32_bf16 v[52:55], v[144:147], v[190:193], v[52:55]
	v_mfma_f32_16x16x32_bf16 v[44:47], v[152:155], v[190:193], v[44:47]
	v_mfma_f32_16x16x32_bf16 v[36:39], v[144:147], v[198:201], v[36:39]
	v_mfma_f32_16x16x32_bf16 v[28:31], v[152:155], v[198:201], v[28:31]
	v_mfma_f32_16x16x32_bf16 v[20:23], v[144:147], v[206:209], v[20:23]
	v_mfma_f32_16x16x32_bf16 v[12:15], v[152:155], v[206:209], v[12:15]
	v_mfma_f32_16x16x32_bf16 v[60:63], v[148:151], v[186:189], v[60:63]
	v_mfma_f32_16x16x32_bf16 v[56:59], v[156:159], v[186:189], v[56:59]
	v_mfma_f32_16x16x32_bf16 v[52:55], v[148:151], v[194:197], v[52:55]
	v_mfma_f32_16x16x32_bf16 v[44:47], v[156:159], v[194:197], v[44:47]
	v_mfma_f32_16x16x32_bf16 v[36:39], v[148:151], v[202:205], v[36:39]
	v_mfma_f32_16x16x32_bf16 v[28:31], v[156:159], v[202:205], v[28:31]
	v_mfma_f32_16x16x32_bf16 v[20:23], v[148:151], v[210:213], v[20:23]
	v_mfma_f32_16x16x32_bf16 v[12:15], v[156:159], v[210:213], v[12:15]
	v_mfma_f32_16x16x32_bf16 v[48:51], v[160:163], v[182:185], v[48:51]
	v_mfma_f32_16x16x32_bf16 v[40:43], v[168:171], v[182:185], v[40:43]
	v_mfma_f32_16x16x32_bf16 v[32:35], v[160:163], v[190:193], v[32:35]
	v_mfma_f32_16x16x32_bf16 v[24:27], v[168:171], v[190:193], v[24:27]
	v_mfma_f32_16x16x32_bf16 v[16:19], v[160:163], v[198:201], v[16:19]
	v_mfma_f32_16x16x32_bf16 v[8:11], v[168:171], v[198:201], v[8:11]
	v_mfma_f32_16x16x32_bf16 v[4:7], v[160:163], v[206:209], v[4:7]
	v_mfma_f32_16x16x32_bf16 v[0:3], v[168:171], v[206:209], v[0:3]
	v_mfma_f32_16x16x32_bf16 v[48:51], v[164:167], v[186:189], v[48:51]
	v_mfma_f32_16x16x32_bf16 v[40:43], v[172:175], v[186:189], v[40:43]
	s_add_i32 s72, s72, 2
	v_mfma_f32_16x16x32_bf16 v[32:35], v[164:167], v[194:197], v[32:35]
	s_add_u32 s40, s40, 0x100
	v_mfma_f32_16x16x32_bf16 v[24:27], v[172:175], v[194:197], v[24:27]
	s_addc_u32 s41, s41, 0
	v_mfma_f32_16x16x32_bf16 v[16:19], v[164:167], v[202:205], v[16:19]
	s_add_u32 s70, s70, 0x100
	v_mfma_f32_16x16x32_bf16 v[8:11], v[172:175], v[202:205], v[8:11]
	s_addc_u32 s71, s71, 0
	v_mfma_f32_16x16x32_bf16 v[4:7], v[164:167], v[210:213], v[4:7]
	s_cmp_gt_u32 s72, 13
	v_mfma_f32_16x16x32_bf16 v[0:3], v[172:175], v[210:213], v[0:3]
	s_barrier
	s_cbranch_scc0 .LBB0_570
	s_branch .Lg2_post

; #define PG8_STAGE(bufoff, gbase, voff) do { _Pragma("unroll") for (int _i = 0; _i < 2; ++_i) \
;         __builtin_amdgcn_global_load_lds((const unsigned*)((const char*)(gbase) + (voff)[_i]), (PG8_LAS unsigned*)(lds + (bufoff) + ldsw + _i * 8192), 16, 0, 0); } while (0)
; #define PG8_LDA(dst, b, h) do { _Pragma("unroll") for (int m = 0; m < 4; ++m) _Pragma("unroll") for (int k = 0; k < 2; ++k) dst[m][k] = *(const PG8_LAS bf16x8*)(lds + PG8_SA(b, h) + aoff + m * 2048 + k * 1024); } while (0)
; #define PG8_LDB(dst, b, h) do { _Pragma("unroll") for (int n = 0; n < 2; ++n) _Pragma("unroll") for (int k = 0; k < 2; ++k) dst[n][k] = *(const PG8_LAS bf16x8*)(lds + PG8_SB(b, h) + boff + n * 2048 + k * 1024); } while (0)
; #define PG8_MMA(ai, bj, At, Bt) do { __builtin_amdgcn_s_setprio(1); _Pragma("unroll") for (int m = 0; m < 4; ++m) _Pragma("unroll") for (int n = 0; n < 2; ++n) _Pragma("unroll") for (int k = 0; k < 2; ++k) \
;         acc[ai][bj][m][n] = __builtin_amdgcn_mfma_f32_16x16x32_bf16(Bt[n][k], At[m][k], acc[ai][bj][m][n], 0, 0, 0); __builtin_amdgcn_s_setprio(0); } while (0)
; #define PG8_WAIT_V(n) asm volatile("s_waitcnt vmcnt(" #n ")" ::: "memory")
; #define PG8_WAIT_L(n) asm volatile("s_waitcnt lgkmcnt(" #n ")" ::: "memory")
; template <class Epi, class Sched, bool ALIGN_EPI = false, bool SP2 = false>
; __device__ __forceinline__ void gemm_phase(PG8_LAS unsigned char* lds, const Gemm g, const Sched& S, const Epi& E) {
;     ...
;             const bool last = (t == nt - 2);
;             const char* a1 = cA + (size_t)(t + 1) * kstep;
;             const char* a2 = last ? nA : cA + (size_t)(t + 2) * kstep; const char* b2 = last ? nB : cB + (size_t)(t + 2) * kstep;
;             const char* a3 = a2 + kstep; const char* b3 = b2 + kstep;
;             if (last && has_next) S.a_ready(nxt);
;             if constexpr (SP2) {
;             PG8_LDB(B0, 0, 0); PG8_LDB(B1, 0, 1); PG8_SCHED; PG8_LDA(At, 0, 0); PG8_STAGE(PG8_SA(1, 1), a1 + hstep, voffA);
;             PG8_WAIT_V(8); PG8_WAIT_L(0); PG8_BAR; PG8_MMA(0, 0, At, B0); PG8_MMA(0, 1, At, B1); PG8_BAR; PG8_SCHED;
;             PG8_LDA(At, 0, 1); PG8_STAGE(PG8_SB(0, 0), b2, voffB); PG8_STAGE(PG8_SB(0, 1), b2 + hstep, voffB); PG8_STAGE(PG8_SA(0, 0), a2, voffA);
;             PG8_WAIT_V(8); PG8_WAIT_L(0); PG8_BAR; PG8_MMA(1, 0, At, B0); PG8_MMA(1, 1, At, B1); PG8_BAR; PG8_SCHED;
.LBB0_592:
	s_add_i32 s81, s4, 2
	s_add_u32 s28, s66, 0x80
	s_addc_u32 s5, s67, 0
	s_add_i32 s48, 0, 0x10000
	s_cmp_eq_u32 s70, s4
	s_cselect_b32 s5, s41, s5
	s_cselect_b32 s4, s40, s28
	s_cselect_b32 s39, s65, s69
	s_cselect_b32 s38, s64, s68
	s_add_i32 s28, 0, 0x14000
	v_add_u32_e32 v154, s48, v140
	v_add_u32_e32 v170, s28, v140
	ds_read_b128 v[142:145], v154
	ds_read_b128 v[146:149], v154 offset:1024
	ds_read_b128 v[150:153], v154 offset:2048
	ds_read_b128 v[154:157], v154 offset:3072
	ds_read_b128 v[158:161], v170
	ds_read_b128 v[162:165], v170 offset:1024
	ds_read_b128 v[166:169], v170 offset:2048
	ds_read_b128 v[170:173], v170 offset:3072
	v_lshl_add_u64 v[174:175], s[66:67], 0, v[134:135]
	s_add_i32 m0, s19, 0xc000
	ds_read_b128 v[182:185], v141
	ds_read_b128 v[186:189], v141 offset:1024
	ds_read_b128 v[190:193], v141 offset:2048
	ds_read_b128 v[194:197], v141 offset:3072
	ds_read_b128 v[198:201], v141 offset:4096
	ds_read_b128 v[202:205], v141 offset:5120
	ds_read_b128 v[206:209], v141 offset:6144
	ds_read_b128 v[210:213], v141 offset:7168
	global_load_lds_dwordx4 v[174:175], off
	v_lshl_add_u64 v[174:175], s[66:67], 0, v[136:137]
	s_add_i32 m0, s19, 0xe000
	s_nop 0
	global_load_lds_dwordx4 v[174:175], off
	s_waitcnt vmcnt(8)
	s_waitcnt lgkmcnt(0)
	s_barrier
	s_waitcnt lgkmcnt(0)
	v_mfma_f32_16x16x32_bf16 v[124:127], v[142:145], v[182:185], v[124:127]
	v_mfma_f32_16x16x32_bf16 v[120:123], v[150:153], v[182:185], v[120:123]
	v_mfma_f32_16x16x32_bf16 v[108:111], v[142:145], v[190:193], v[108:111]
	v_mfma_f32_16x16x32_bf16 v[104:107], v[150:153], v[190:193], v[104:107]
	v_mfma_f32_16x16x32_bf16 v[92:95], v[142:145], v[198:201], v[92:95]
	v_mfma_f32_16x16x32_bf16 v[88:91], v[150:153], v[198:201], v[88:91]
	v_mfma_f32_16x16x32_bf16 v[76:79], v[142:145], v[206:209], v[76:79]
	v_mfma_f32_16x16x32_bf16 v[72:75], v[150:153], v[206:209], v[72:75]
	v_mfma_f32_16x16x32_bf16 v[124:127], v[146:149], v[186:189], v[124:127]
	v_mfma_f32_16x16x32_bf16 v[120:123], v[154:157], v[186:189], v[120:123]
	v_mfma_f32_16x16x32_bf16 v[108:111], v[146:149], v[194:197], v[108:111]
	v_mfma_f32_16x16x32_bf16 v[104:107], v[154:157], v[194:197], v[104:107]
	v_mfma_f32_16x16x32_bf16 v[92:95], v[146:149], v[202:205], v[92:95]
	v_mfma_f32_16x16x32_bf16 v[88:91], v[154:157], v[202:205], v[88:91]
	v_mfma_f32_16x16x32_bf16 v[76:79], v[146:149], v[210:213], v[76:79]
	v_mfma_f32_16x16x32_bf16 v[72:75], v[154:157], v[210:213], v[72:75]
	v_mfma_f32_16x16x32_bf16 v[116:119], v[158:161], v[182:185], v[116:119]
	v_mfma_f32_16x16x32_bf16 v[112:115], v[166:169], v[182:185], v[112:115]
	v_mfma_f32_16x16x32_bf16 v[100:103], v[158:161], v[190:193], v[100:103]
	v_mfma_f32_16x16x32_bf16 v[96:99], v[166:169], v[190:193], v[96:99]
	v_mfma_f32_16x16x32_bf16 v[84:87], v[158:161], v[198:201], v[84:87]
	v_mfma_f32_16x16x32_bf16 v[80:83], v[166:169], v[198:201], v[80:83]
	v_mfma_f32_16x16x32_bf16 v[68:71], v[158:161], v[206:209], v[68:71]
	v_mfma_f32_16x16x32_bf16 v[64:67], v[166:169], v[206:209], v[64:67]
	v_mfma_f32_16x16x32_bf16 v[116:119], v[162:165], v[186:189], v[116:119]
	v_mfma_f32_16x16x32_bf16 v[112:115], v[170:173], v[186:189], v[112:115]
	v_mfma_f32_16x16x32_bf16 v[100:103], v[162:165], v[194:197], v[100:103]
	v_mfma_f32_16x16x32_bf16 v[96:99], v[170:173], v[194:197], v[96:99]
	v_mfma_f32_16x16x32_bf16 v[84:87], v[162:165], v[202:205], v[84:87]
	v_mfma_f32_16x16x32_bf16 v[80:83], v[170:173], v[202:205], v[80:83]
	v_mfma_f32_16x16x32_bf16 v[68:71], v[162:165], v[210:213], v[68:71]
	v_mfma_f32_16x16x32_bf16 v[64:67], v[170:173], v[210:213], v[64:67]
	s_barrier
	s_add_i32 s48, s48, s18
	v_lshl_add_u64 v[174:175], s[38:39], 0, v[176:177]
	s_mov_b32 m0, s48
	ds_read_b128 v[182:185], v141 offset:16384
	ds_read_b128 v[186:189], v141 offset:17408
	ds_read_b128 v[190:193], v141 offset:18432
	ds_read_b128 v[194:197], v141 offset:19456
	ds_read_b128 v[198:201], v141 offset:20480
	ds_read_b128 v[202:205], v141 offset:21504
	ds_read_b128 v[206:209], v141 offset:22528
	ds_read_b128 v[210:213], v141 offset:23552
	global_load_lds_dwordx4 v[174:175], off
	s_add_i32 m0, s48, 0x2000
	v_lshl_add_u64 v[214:215], s[38:39], 0, v[128:129]
	s_add_u32 s38, s38, s0
	s_addc_u32 s39, s39, s1
	s_add_i32 s28, s28, s18
	global_load_lds_dwordx4 v[214:215], off
	v_lshl_add_u64 v[216:217], s[38:39], 0, v[176:177]
	s_mov_b32 m0, s28
	v_lshl_add_u64 v[218:219], s[38:39], 0, v[128:129]
	global_load_lds_dwordx4 v[216:217], off
	s_add_i32 m0, s28, 0x2000
	v_lshl_add_u64 v[220:221], s[4:5], 0, v[132:133]
	global_load_lds_dwordx4 v[218:219], off
	s_mov_b32 m0, s19
	v_lshl_add_u64 v[222:223], s[4:5], 0, v[130:131]
	global_load_lds_dwordx4 v[220:221], off
	s_mov_b32 m0, s24
	s_nop 0
	global_load_lds_dwordx4 v[222:223], off
	s_waitcnt vmcnt(8)
	s_waitcnt lgkmcnt(0)
	s_barrier
; #define PG8_STAGE(bufoff, gbase, voff) do { _Pragma("unroll") for (int _i = 0; _i < 2; ++_i) \
;         __builtin_amdgcn_global_load_lds((const unsigned*)((const char*)(gbase) + (voff)[_i]), (PG8_LAS unsigned*)(lds + (bufoff) + ldsw + _i * 8192), 16, 0, 0); } while (0)
; #define PG8_LDA(dst, b, h) do { _Pragma("unroll") for (int m = 0; m < 4; ++m) _Pragma("unroll") for (int k = 0; k < 2; ++k) dst[m][k] = *(const PG8_LAS bf16x8*)(lds + PG8_SA(b, h) + aoff + m * 2048 + k * 1024); } while (0)
; #define PG8_LDB(dst, b, h) do { _Pragma("unroll") for (int n = 0; n < 2; ++n) _Pragma("unroll") for (int k = 0; k < 2; ++k) dst[n][k] = *(const PG8_LAS bf16x8*)(lds + PG8_SB(b, h) + boff + n * 2048 + k * 1024); } while (0)
; #define PG8_MMA(ai, bj, At, Bt) do { __builtin_amdgcn_s_setprio(1); _Pragma("unroll") for (int m = 0; m < 4; ++m) _Pragma("unroll") for (int n = 0; n < 2; ++n) _Pragma("unroll") for (int k = 0; k < 2; ++k) \
;         acc[ai][bj][m][n] = __builtin_amdgcn_mfma_f32_16x16x32_bf16(Bt[n][k], At[m][k], acc[ai][bj][m][n], 0, 0, 0); __builtin_amdgcn_s_setprio(0); } while (0)
; #define PG8_WAIT_V(n) asm volatile("s_waitcnt vmcnt(" #n ")" ::: "memory")
; #define PG8_WAIT_L(n) asm volatile("s_waitcnt lgkmcnt(" #n ")" ::: "memory")
; #define PG8_BAR __builtin_amdgcn_s_barrier()
; #define PG8_SCHED __builtin_amdgcn_sched_barrier(0)
; template <class Epi, class Sched, bool ALIGN_EPI = false, bool SP2 = false>
; __device__ __forceinline__ void gemm_phase(PG8_LAS unsigned char* lds, const Gemm g, const Sched& S, const Epi& E) {
;     ...
;             PG8_WAIT_V(8); PG8_WAIT_L(0); PG8_BAR; PG8_MMA(1, 0, At, B0); PG8_MMA(1, 1, At, B1); PG8_BAR; PG8_SCHED;
;             PG8_LDB(B0, 1, 0); PG8_LDB(B1, 1, 1); PG8_SCHED; PG8_LDA(At, 1, 0); PG8_STAGE(PG8_SA(0, 1), a2 + hstep, voffA);
;             PG8_WAIT_V(8); PG8_WAIT_L(0); PG8_BAR; PG8_MMA(0, 0, At, B0); PG8_MMA(0, 1, At, B1); PG8_BAR; PG8_SCHED;
	s_waitcnt lgkmcnt(0)
	v_mfma_f32_16x16x32_bf16 v[60:63], v[142:145], v[182:185], v[60:63]
	v_mfma_f32_16x16x32_bf16 v[56:59], v[150:153], v[182:185], v[56:59]
	v_mfma_f32_16x16x32_bf16 v[44:47], v[142:145], v[190:193], v[44:47]
	v_mfma_f32_16x16x32_bf16 v[40:43], v[150:153], v[190:193], v[40:43]
	v_mfma_f32_16x16x32_bf16 v[28:31], v[142:145], v[198:201], v[28:31]
	v_mfma_f32_16x16x32_bf16 v[24:27], v[150:153], v[198:201], v[24:27]
	v_mfma_f32_16x16x32_bf16 v[12:15], v[142:145], v[206:209], v[12:15]
	v_mfma_f32_16x16x32_bf16 v[8:11], v[150:153], v[206:209], v[8:11]
	v_mfma_f32_16x16x32_bf16 v[60:63], v[146:149], v[186:189], v[60:63]
	v_mfma_f32_16x16x32_bf16 v[56:59], v[154:157], v[186:189], v[56:59]
	v_mfma_f32_16x16x32_bf16 v[44:47], v[146:149], v[194:197], v[44:47]
	v_mfma_f32_16x16x32_bf16 v[40:43], v[154:157], v[194:197], v[40:43]
	v_mfma_f32_16x16x32_bf16 v[28:31], v[146:149], v[202:205], v[28:31]
	v_mfma_f32_16x16x32_bf16 v[24:27], v[154:157], v[202:205], v[24:27]
	v_mfma_f32_16x16x32_bf16 v[12:15], v[146:149], v[210:213], v[12:15]
	v_mfma_f32_16x16x32_bf16 v[8:11], v[154:157], v[210:213], v[8:11]
	v_mfma_f32_16x16x32_bf16 v[52:55], v[158:161], v[182:185], v[52:55]
	v_mfma_f32_16x16x32_bf16 v[48:51], v[166:169], v[182:185], v[48:51]
	v_mfma_f32_16x16x32_bf16 v[36:39], v[158:161], v[190:193], v[36:39]
	v_mfma_f32_16x16x32_bf16 v[32:35], v[166:169], v[190:193], v[32:35]
	v_mfma_f32_16x16x32_bf16 v[20:23], v[158:161], v[198:201], v[20:23]
	v_mfma_f32_16x16x32_bf16 v[16:19], v[166:169], v[198:201], v[16:19]
	v_mfma_f32_16x16x32_bf16 v[4:7], v[158:161], v[206:209], v[4:7]
	v_mfma_f32_16x16x32_bf16 v[0:3], v[166:169], v[206:209], v[0:3]
	v_mfma_f32_16x16x32_bf16 v[52:55], v[162:165], v[186:189], v[52:55]
	v_mfma_f32_16x16x32_bf16 v[48:51], v[170:173], v[186:189], v[48:51]
	v_mfma_f32_16x16x32_bf16 v[36:39], v[162:165], v[194:197], v[36:39]
	v_mfma_f32_16x16x32_bf16 v[32:35], v[170:173], v[194:197], v[32:35]
	v_mfma_f32_16x16x32_bf16 v[20:23], v[162:165], v[202:205], v[20:23]
	v_mfma_f32_16x16x32_bf16 v[16:19], v[170:173], v[202:205], v[16:19]
	v_mfma_f32_16x16x32_bf16 v[4:7], v[162:165], v[210:213], v[4:7]
	v_mfma_f32_16x16x32_bf16 v[0:3], v[170:173], v[210:213], v[0:3]
	s_barrier
	s_add_i32 s28, 0, 0x18000
	s_add_i32 s38, 0, 0x1c000
	v_add_u32_e32 v154, s28, v140
	v_add_u32_e32 v170, s38, v140
	ds_read_b128 v[142:145], v154
	ds_read_b128 v[146:149], v154 offset:1024
	ds_read_b128 v[150:153], v154 offset:2048
	ds_read_b128 v[154:157], v154 offset:3072
	ds_read_b128 v[158:161], v170
	ds_read_b128 v[162:165], v170 offset:1024
	ds_read_b128 v[166:169], v170 offset:2048
	ds_read_b128 v[170:173], v170 offset:3072
	s_add_u32 s4, s4, s0
	s_addc_u32 s5, s5, s1
	s_mov_b32 m0, s25
	v_lshl_add_u64 v[224:225], s[4:5], 0, v[132:133]
	ds_read_b128 v[182:185], v141 offset:32768
	ds_read_b128 v[186:189], v141 offset:33792
	ds_read_b128 v[190:193], v141 offset:34816
	ds_read_b128 v[194:197], v141 offset:35840
	ds_read_b128 v[198:201], v141 offset:36864
	ds_read_b128 v[202:205], v141 offset:37888
	ds_read_b128 v[206:209], v141 offset:38912
	ds_read_b128 v[210:213], v141 offset:39936
	global_load_lds_dwordx4 v[224:225], off
	v_lshl_add_u64 v[224:225], s[4:5], 0, v[130:131]
	s_mov_b32 m0, s30
	s_nop 0
	global_load_lds_dwordx4 v[224:225], off
	s_waitcnt vmcnt(8)
	s_waitcnt lgkmcnt(0)
	s_barrier
	s_waitcnt lgkmcnt(0)
	v_mfma_f32_16x16x32_bf16 v[124:127], v[142:145], v[182:185], v[124:127]
	v_mfma_f32_16x16x32_bf16 v[120:123], v[150:153], v[182:185], v[120:123]
	v_mfma_f32_16x16x32_bf16 v[108:111], v[142:145], v[190:193], v[108:111]
	v_mfma_f32_16x16x32_bf16 v[104:107], v[150:153], v[190:193], v[104:107]
	v_mfma_f32_16x16x32_bf16 v[92:95], v[142:145], v[198:201], v[92:95]
	v_mfma_f32_16x16x32_bf16 v[88:91], v[150:153], v[198:201], v[88:91]
	v_mfma_f32_16x16x32_bf16 v[76:79], v[142:145], v[206:209], v[76:79]
	v_mfma_f32_16x16x32_bf16 v[72:75], v[150:153], v[206:209], v[72:75]
	v_mfma_f32_16x16x32_bf16 v[124:127], v[146:149], v[186:189], v[124:127]
	v_mfma_f32_16x16x32_bf16 v[120:123], v[154:157], v[186:189], v[120:123]
	v_mfma_f32_16x16x32_bf16 v[108:111], v[146:149], v[194:197], v[108:111]
	v_mfma_f32_16x16x32_bf16 v[104:107], v[154:157], v[194:197], v[104:107]
	v_mfma_f32_16x16x32_bf16 v[92:95], v[146:149], v[202:205], v[92:95]
	v_mfma_f32_16x16x32_bf16 v[88:91], v[154:157], v[202:205], v[88:91]
	v_mfma_f32_16x16x32_bf16 v[76:79], v[146:149], v[210:213], v[76:79]
	v_mfma_f32_16x16x32_bf16 v[72:75], v[154:157], v[210:213], v[72:75]
	v_mfma_f32_16x16x32_bf16 v[116:119], v[158:161], v[182:185], v[116:119]
	v_mfma_f32_16x16x32_bf16 v[112:115], v[166:169], v[182:185], v[112:115]
	v_mfma_f32_16x16x32_bf16 v[100:103], v[158:161], v[190:193], v[100:103]
	v_mfma_f32_16x16x32_bf16 v[96:99], v[166:169], v[190:193], v[96:99]
	v_mfma_f32_16x16x32_bf16 v[84:87], v[158:161], v[198:201], v[84:87]
	v_mfma_f32_16x16x32_bf16 v[80:83], v[166:169], v[198:201], v[80:83]
	v_mfma_f32_16x16x32_bf16 v[68:71], v[158:161], v[206:209], v[68:71]
	v_mfma_f32_16x16x32_bf16 v[64:67], v[166:169], v[206:209], v[64:67]
	v_mfma_f32_16x16x32_bf16 v[116:119], v[162:165], v[186:189], v[116:119]
	v_mfma_f32_16x16x32_bf16 v[112:115], v[170:173], v[186:189], v[112:115]
	v_mfma_f32_16x16x32_bf16 v[100:103], v[162:165], v[194:197], v[100:103]
	v_mfma_f32_16x16x32_bf16 v[96:99], v[170:173], v[194:197], v[96:99]
	v_mfma_f32_16x16x32_bf16 v[84:87], v[162:165], v[202:205], v[84:87]
	v_mfma_f32_16x16x32_bf16 v[80:83], v[170:173], v[202:205], v[80:83]
	v_mfma_f32_16x16x32_bf16 v[68:71], v[162:165], v[210:213], v[68:71]
	v_mfma_f32_16x16x32_bf16 v[64:67], v[170:173], v[210:213], v[64:67]
	s_barrier
; #define PG8_STAGE(bufoff, gbase, voff) do { _Pragma("unroll") for (int _i = 0; _i < 2; ++_i) \
;         __builtin_amdgcn_global_load_lds((const unsigned*)((const char*)(gbase) + (voff)[_i]), (PG8_LAS unsigned*)(lds + (bufoff) + ldsw + _i * 8192), 16, 0, 0); } while (0)
; #define PG8_LDA(dst, b, h) do { _Pragma("unroll") for (int m = 0; m < 4; ++m) _Pragma("unroll") for (int k = 0; k < 2; ++k) dst[m][k] = *(const PG8_LAS bf16x8*)(lds + PG8_SA(b, h) + aoff + m * 2048 + k * 1024); } while (0)
; #define PG8_MMA(ai, bj, At, Bt) do { __builtin_amdgcn_s_setprio(1); _Pragma("unroll") for (int m = 0; m < 4; ++m) _Pragma("unroll") for (int n = 0; n < 2; ++n) _Pragma("unroll") for (int k = 0; k < 2; ++k) \
;         acc[ai][bj][m][n] = __builtin_amdgcn_mfma_f32_16x16x32_bf16(Bt[n][k], At[m][k], acc[ai][bj][m][n], 0, 0, 0); __builtin_amdgcn_s_setprio(0); } while (0)
; #define PG8_WAIT_V(n) asm volatile("s_waitcnt vmcnt(" #n ")" ::: "memory")
; #define PG8_WAIT_L(n) asm volatile("s_waitcnt lgkmcnt(" #n ")" ::: "memory")
; #define PG8_BAR __builtin_amdgcn_s_barrier()
; #define PG8_SCHED __builtin_amdgcn_sched_barrier(0)
; template <class Epi, class Sched, bool ALIGN_EPI = false, bool SP2 = false>
; __device__ __forceinline__ void gemm_phase(PG8_LAS unsigned char* lds, const Gemm g, const Sched& S, const Epi& E) {
;     ...
;             PG8_LDA(At, 1, 1); PG8_STAGE(PG8_SB(1, 0), b3, voffB); PG8_STAGE(PG8_SB(1, 1), b3 + hstep, voffB); PG8_STAGE(PG8_SA(1, 0), a3, voffA);
;             PG8_WAIT_V(8); PG8_WAIT_L(0); PG8_BAR; PG8_MMA(1, 0, At, B0); PG8_MMA(1, 1, At, B1); PG8_BAR; PG8_SCHED;
	s_add_i32 s4, s28, s18
	v_lshl_add_u64 v[174:175], v[174:175], 0, s[44:45]
	s_mov_b32 m0, s4
	ds_read_b128 v[182:185], v141 offset:49152
	ds_read_b128 v[186:189], v141 offset:50176
	ds_read_b128 v[190:193], v141 offset:51200
	ds_read_b128 v[194:197], v141 offset:52224
	ds_read_b128 v[198:201], v141 offset:53248
	ds_read_b128 v[202:205], v141 offset:54272
	ds_read_b128 v[206:209], v141 offset:55296
	ds_read_b128 v[210:213], v141 offset:56320
	global_load_lds_dwordx4 v[174:175], off
	v_lshl_add_u64 v[174:175], v[214:215], 0, s[44:45]
	s_add_i32 m0, s4, 0x2000
	s_add_i32 s4, s38, s18
	global_load_lds_dwordx4 v[174:175], off
	v_lshl_add_u64 v[174:175], v[216:217], 0, s[44:45]
	s_mov_b32 m0, s4
	s_nop 0
	global_load_lds_dwordx4 v[174:175], off
	v_lshl_add_u64 v[174:175], v[218:219], 0, s[44:45]
	s_add_i32 m0, s4, 0x2000
	s_nop 0
	global_load_lds_dwordx4 v[174:175], off
	v_lshl_add_u64 v[174:175], v[220:221], 0, s[44:45]
	s_mov_b32 m0, s43
	s_nop 0
	global_load_lds_dwordx4 v[174:175], off
	v_lshl_add_u64 v[174:175], v[222:223], 0, s[44:45]
	s_mov_b32 m0, s46
	s_nop 0
	global_load_lds_dwordx4 v[174:175], off
	s_waitcnt vmcnt(8)
	s_waitcnt lgkmcnt(0)
	s_barrier
	s_waitcnt lgkmcnt(0)
	v_mfma_f32_16x16x32_bf16 v[60:63], v[142:145], v[182:185], v[60:63]
	v_mfma_f32_16x16x32_bf16 v[56:59], v[150:153], v[182:185], v[56:59]
	v_mfma_f32_16x16x32_bf16 v[44:47], v[142:145], v[190:193], v[44:47]
	v_mfma_f32_16x16x32_bf16 v[40:43], v[150:153], v[190:193], v[40:43]
	v_mfma_f32_16x16x32_bf16 v[28:31], v[142:145], v[198:201], v[28:31]
	v_mfma_f32_16x16x32_bf16 v[24:27], v[150:153], v[198:201], v[24:27]
	v_mfma_f32_16x16x32_bf16 v[12:15], v[142:145], v[206:209], v[12:15]
	v_mfma_f32_16x16x32_bf16 v[8:11], v[150:153], v[206:209], v[8:11]
	v_mfma_f32_16x16x32_bf16 v[60:63], v[146:149], v[186:189], v[60:63]
	v_mfma_f32_16x16x32_bf16 v[56:59], v[154:157], v[186:189], v[56:59]
	v_mfma_f32_16x16x32_bf16 v[44:47], v[146:149], v[194:197], v[44:47]
	v_mfma_f32_16x16x32_bf16 v[40:43], v[154:157], v[194:197], v[40:43]
	v_mfma_f32_16x16x32_bf16 v[28:31], v[146:149], v[202:205], v[28:31]
	v_mfma_f32_16x16x32_bf16 v[24:27], v[154:157], v[202:205], v[24:27]
	v_mfma_f32_16x16x32_bf16 v[12:15], v[146:149], v[210:213], v[12:15]
	v_mfma_f32_16x16x32_bf16 v[8:11], v[154:157], v[210:213], v[8:11]
	v_mfma_f32_16x16x32_bf16 v[52:55], v[158:161], v[182:185], v[52:55]
	v_mfma_f32_16x16x32_bf16 v[48:51], v[166:169], v[182:185], v[48:51]
	v_mfma_f32_16x16x32_bf16 v[36:39], v[158:161], v[190:193], v[36:39]
	v_mfma_f32_16x16x32_bf16 v[32:35], v[166:169], v[190:193], v[32:35]
	v_mfma_f32_16x16x32_bf16 v[20:23], v[158:161], v[198:201], v[20:23]
	v_mfma_f32_16x16x32_bf16 v[16:19], v[166:169], v[198:201], v[16:19]
	v_mfma_f32_16x16x32_bf16 v[4:7], v[158:161], v[206:209], v[4:7]
	v_mfma_f32_16x16x32_bf16 v[0:3], v[166:169], v[206:209], v[0:3]
	v_mfma_f32_16x16x32_bf16 v[52:55], v[162:165], v[186:189], v[52:55]
	v_mfma_f32_16x16x32_bf16 v[48:51], v[170:173], v[186:189], v[48:51]
	s_add_u32 s66, s66, 0x100
	v_mfma_f32_16x16x32_bf16 v[36:39], v[162:165], v[194:197], v[36:39]
	s_addc_u32 s67, s67, 0
	v_mfma_f32_16x16x32_bf16 v[32:35], v[170:173], v[194:197], v[32:35]
	s_add_u32 s68, s68, 0x100
	v_mfma_f32_16x16x32_bf16 v[20:23], v[162:165], v[202:205], v[20:23]
	s_addc_u32 s69, s69, 0
	v_mfma_f32_16x16x32_bf16 v[16:19], v[170:173], v[202:205], v[16:19]
	s_cmp_ge_i32 s81, s31
	v_mfma_f32_16x16x32_bf16 v[4:7], v[162:165], v[210:213], v[4:7]
	s_mov_b32 s4, s81
	v_mfma_f32_16x16x32_bf16 v[0:3], v[170:173], v[210:213], v[0:3]
	s_barrier
	s_cbranch_scc0 .LBB0_592

; #define PG8_STAGE(bufoff, gbase, voff) do { _Pragma("unroll") for (int _i = 0; _i < 2; ++_i) \
;         __builtin_amdgcn_global_load_lds((const unsigned*)((const char*)(gbase) + (voff)[_i]), (PG8_LAS unsigned*)(lds + (bufoff) + ldsw + _i * 8192), 16, 0, 0); } while (0)
; #define PG8_LDA(dst, b, h) do { _Pragma("unroll") for (int m = 0; m < 4; ++m) _Pragma("unroll") for (int k = 0; k < 2; ++k) dst[m][k] = *(const PG8_LAS bf16x8*)(lds + PG8_SA(b, h) + aoff + m * 2048 + k * 1024); } while (0)
; #define PG8_LDB(dst, b, h) do { _Pragma("unroll") for (int n = 0; n < 2; ++n) _Pragma("unroll") for (int k = 0; k < 2; ++k) dst[n][k] = *(const PG8_LAS bf16x8*)(lds + PG8_SB(b, h) + boff + n * 2048 + k * 1024); } while (0)
; #define PG8_MMA(ai, bj, At, Bt) do { __builtin_amdgcn_s_setprio(1); _Pragma("unroll") for (int m = 0; m < 4; ++m) _Pragma("unroll") for (int n = 0; n < 2; ++n) _Pragma("unroll") for (int k = 0; k < 2; ++k) \
;         acc[ai][bj][m][n] = __builtin_amdgcn_mfma_f32_16x16x32_bf16(Bt[n][k], At[m][k], acc[ai][bj][m][n], 0, 0, 0); __builtin_amdgcn_s_setprio(0); } while (0)
; #define PG8_WAIT_V(n) asm volatile("s_waitcnt vmcnt(" #n ")" ::: "memory")
; #define PG8_WAIT_L(n) asm volatile("s_waitcnt lgkmcnt(" #n ")" ::: "memory")
; template <class Epi, class Sched, bool ALIGN_EPI = false, bool SP2 = false>
; __device__ __forceinline__ void gemm_phase(PG8_LAS unsigned char* lds, const Gemm g, const Sched& S, const Epi& E) {
;     ...
;             const bool last = (t == nt - 2);
;             const char* a1 = cA + (size_t)(t + 1) * kstep;
;             const char* a2 = last ? nA : cA + (size_t)(t + 2) * kstep; const char* b2 = last ? nB : cB + (size_t)(t + 2) * kstep;
;             const char* a3 = a2 + kstep; const char* b3 = b2 + kstep;
;             if (last && has_next) S.a_ready(nxt);
;             if constexpr (SP2) {
;             PG8_LDB(B0, 0, 0); PG8_LDB(B1, 0, 1); PG8_SCHED; PG8_LDA(At, 0, 0); PG8_STAGE(PG8_SA(1, 1), a1 + hstep, voffA);
;             PG8_WAIT_V(8); PG8_WAIT_L(0); PG8_BAR; PG8_MMA(0, 0, At, B0); PG8_MMA(0, 1, At, B1); PG8_BAR; PG8_SCHED;
;             PG8_LDA(At, 0, 1); PG8_STAGE(PG8_SB(0, 0), b2, voffB); PG8_STAGE(PG8_SB(0, 1), b2 + hstep, voffB); PG8_STAGE(PG8_SA(0, 0), a2, voffA);
;             PG8_WAIT_V(8); PG8_WAIT_L(0); PG8_BAR; PG8_MMA(1, 0, At, B0); PG8_MMA(1, 1, At, B1); PG8_BAR; PG8_SCHED;
.LBB0_718:
	s_add_u32 s28, vcc_lo, 0xfffc0080
	s_addc_u32 s38, vcc_hi, -1
	s_add_i32 s39, 0, 0x10000
	s_cmp_eq_u32 s80, 12
	s_cselect_b32 s67, s41, s38
	s_cselect_b32 s66, s76, s28
	v_add_u32_e32 v138, s39, v142
	s_cselect_b32 s65, s37, s79
	s_cselect_b32 s64, s77, s78
	s_add_i32 s28, 0, 0x14000
	ds_read_b128 v[144:147], v138
	ds_read_b128 v[148:151], v138 offset:1024
	ds_read_b128 v[152:155], v138 offset:2048
	ds_read_b128 v[156:159], v138 offset:3072
	v_add_u32_e32 v138, s28, v142
	ds_read_b128 v[160:163], v138
	ds_read_b128 v[164:167], v138 offset:1024
	ds_read_b128 v[168:171], v138 offset:2048
	ds_read_b128 v[172:175], v138 offset:3072
	v_lshl_add_u64 v[138:139], vcc, 0, v[134:135]
	s_add_i32 m0, s30, 0xc000
	ds_read_b128 v[182:185], v143
	ds_read_b128 v[186:189], v143 offset:1024
	ds_read_b128 v[190:193], v143 offset:2048
	ds_read_b128 v[194:197], v143 offset:3072
	ds_read_b128 v[198:201], v143 offset:4096
	ds_read_b128 v[202:205], v143 offset:5120
	ds_read_b128 v[206:209], v143 offset:6144
	ds_read_b128 v[210:213], v143 offset:7168
	global_load_lds_dwordx4 v[138:139], off
	v_lshl_add_u64 v[138:139], vcc, 0, v[136:137]
	s_add_i32 m0, s30, 0xe000
	s_nop 0
	global_load_lds_dwordx4 v[138:139], off
	s_waitcnt vmcnt(8)
	s_waitcnt lgkmcnt(0)
	s_barrier
	s_waitcnt lgkmcnt(0)
	v_mfma_f32_16x16x32_bf16 v[124:127], v[144:147], v[182:185], v[124:127]
	v_mfma_f32_16x16x32_bf16 v[120:123], v[152:155], v[182:185], v[120:123]
	v_mfma_f32_16x16x32_bf16 v[108:111], v[144:147], v[190:193], v[108:111]
	v_mfma_f32_16x16x32_bf16 v[104:107], v[152:155], v[190:193], v[104:107]
	v_mfma_f32_16x16x32_bf16 v[92:95], v[144:147], v[198:201], v[92:95]
	v_mfma_f32_16x16x32_bf16 v[88:91], v[152:155], v[198:201], v[88:91]
	v_mfma_f32_16x16x32_bf16 v[76:79], v[144:147], v[206:209], v[76:79]
	v_mfma_f32_16x16x32_bf16 v[72:75], v[152:155], v[206:209], v[72:75]
	v_mfma_f32_16x16x32_bf16 v[124:127], v[148:151], v[186:189], v[124:127]
	v_mfma_f32_16x16x32_bf16 v[120:123], v[156:159], v[186:189], v[120:123]
	v_mfma_f32_16x16x32_bf16 v[108:111], v[148:151], v[194:197], v[108:111]
	v_mfma_f32_16x16x32_bf16 v[104:107], v[156:159], v[194:197], v[104:107]
	v_mfma_f32_16x16x32_bf16 v[92:95], v[148:151], v[202:205], v[92:95]
	v_mfma_f32_16x16x32_bf16 v[88:91], v[156:159], v[202:205], v[88:91]
	v_mfma_f32_16x16x32_bf16 v[76:79], v[148:151], v[210:213], v[76:79]
	v_mfma_f32_16x16x32_bf16 v[72:75], v[156:159], v[210:213], v[72:75]
	v_mfma_f32_16x16x32_bf16 v[116:119], v[160:163], v[182:185], v[116:119]
	v_mfma_f32_16x16x32_bf16 v[112:115], v[168:171], v[182:185], v[112:115]
	v_mfma_f32_16x16x32_bf16 v[100:103], v[160:163], v[190:193], v[100:103]
	v_mfma_f32_16x16x32_bf16 v[96:99], v[168:171], v[190:193], v[96:99]
	v_mfma_f32_16x16x32_bf16 v[84:87], v[160:163], v[198:201], v[84:87]
	v_mfma_f32_16x16x32_bf16 v[80:83], v[168:171], v[198:201], v[80:83]
	v_mfma_f32_16x16x32_bf16 v[68:71], v[160:163], v[206:209], v[68:71]
	v_mfma_f32_16x16x32_bf16 v[64:67], v[168:171], v[206:209], v[64:67]
	v_mfma_f32_16x16x32_bf16 v[116:119], v[164:167], v[186:189], v[116:119]
	v_mfma_f32_16x16x32_bf16 v[112:115], v[172:175], v[186:189], v[112:115]
	v_mfma_f32_16x16x32_bf16 v[100:103], v[164:167], v[194:197], v[100:103]
	v_mfma_f32_16x16x32_bf16 v[96:99], v[172:175], v[194:197], v[96:99]
	v_mfma_f32_16x16x32_bf16 v[84:87], v[164:167], v[202:205], v[84:87]
	v_mfma_f32_16x16x32_bf16 v[80:83], v[172:175], v[202:205], v[80:83]
	v_mfma_f32_16x16x32_bf16 v[68:71], v[164:167], v[210:213], v[68:71]
	v_mfma_f32_16x16x32_bf16 v[64:67], v[172:175], v[210:213], v[64:67]
	s_barrier
	s_add_i32 s38, s39, s23
	v_lshl_add_u64 v[138:139], s[64:65], 0, v[176:177]
	s_mov_b32 m0, s38
	ds_read_b128 v[182:185], v143 offset:16384
	ds_read_b128 v[186:189], v143 offset:17408
	ds_read_b128 v[190:193], v143 offset:18432
	ds_read_b128 v[194:197], v143 offset:19456
	ds_read_b128 v[198:201], v143 offset:20480
	ds_read_b128 v[202:205], v143 offset:21504
	ds_read_b128 v[206:209], v143 offset:22528
	ds_read_b128 v[210:213], v143 offset:23552
	global_load_lds_dwordx4 v[138:139], off
	s_add_i32 m0, s38, 0x2000
	s_add_u32 s38, s64, 0x40000
	v_lshl_add_u64 v[214:215], s[64:65], 0, v[128:129]
	s_addc_u32 s39, s65, 0
	s_add_i32 s28, s28, s23
	global_load_lds_dwordx4 v[214:215], off
	v_lshl_add_u64 v[216:217], s[38:39], 0, v[176:177]
	s_mov_b32 m0, s28
	v_lshl_add_u64 v[218:219], s[66:67], 0, v[130:131]
	global_load_lds_dwordx4 v[216:217], off
	v_lshl_add_u64 v[216:217], s[38:39], 0, v[128:129]
	s_add_i32 m0, s28, 0x2000
	s_nop 0
	global_load_lds_dwordx4 v[216:217], off
	v_lshl_add_u64 v[216:217], s[66:67], 0, v[132:133]
	s_mov_b32 m0, s30
	s_nop 0
	global_load_lds_dwordx4 v[216:217], off
	s_mov_b32 m0, s31
	s_nop 0
	global_load_lds_dwordx4 v[218:219], off
	s_waitcnt vmcnt(8)
	s_waitcnt lgkmcnt(0)
	s_barrier
; #define PG8_STAGE(bufoff, gbase, voff) do { _Pragma("unroll") for (int _i = 0; _i < 2; ++_i) \
;         __builtin_amdgcn_global_load_lds((const unsigned*)((const char*)(gbase) + (voff)[_i]), (PG8_LAS unsigned*)(lds + (bufoff) + ldsw + _i * 8192), 16, 0, 0); } while (0)
; #define PG8_LDA(dst, b, h) do { _Pragma("unroll") for (int m = 0; m < 4; ++m) _Pragma("unroll") for (int k = 0; k < 2; ++k) dst[m][k] = *(const PG8_LAS bf16x8*)(lds + PG8_SA(b, h) + aoff + m * 2048 + k * 1024); } while (0)
; #define PG8_LDB(dst, b, h) do { _Pragma("unroll") for (int n = 0; n < 2; ++n) _Pragma("unroll") for (int k = 0; k < 2; ++k) dst[n][k] = *(const PG8_LAS bf16x8*)(lds + PG8_SB(b, h) + boff + n * 2048 + k * 1024); } while (0)
; #define PG8_MMA(ai, bj, At, Bt) do { __builtin_amdgcn_s_setprio(1); _Pragma("unroll") for (int m = 0; m < 4; ++m) _Pragma("unroll") for (int n = 0; n < 2; ++n) _Pragma("unroll") for (int k = 0; k < 2; ++k) \
;         acc[ai][bj][m][n] = __builtin_amdgcn_mfma_f32_16x16x32_bf16(Bt[n][k], At[m][k], acc[ai][bj][m][n], 0, 0, 0); __builtin_amdgcn_s_setprio(0); } while (0)
; #define PG8_WAIT_V(n) asm volatile("s_waitcnt vmcnt(" #n ")" ::: "memory")
; #define PG8_WAIT_L(n) asm volatile("s_waitcnt lgkmcnt(" #n ")" ::: "memory")
; #define PG8_BAR __builtin_amdgcn_s_barrier()
; #define PG8_SCHED __builtin_amdgcn_sched_barrier(0)
; template <class Epi, class Sched, bool ALIGN_EPI = false, bool SP2 = false>
; __device__ __forceinline__ void gemm_phase(PG8_LAS unsigned char* lds, const Gemm g, const Sched& S, const Epi& E) {
;     ...
;             PG8_WAIT_V(8); PG8_WAIT_L(0); PG8_BAR; PG8_MMA(1, 0, At, B0); PG8_MMA(1, 1, At, B1); PG8_BAR; PG8_SCHED;
;             PG8_LDB(B0, 1, 0); PG8_LDB(B1, 1, 1); PG8_SCHED; PG8_LDA(At, 1, 0); PG8_STAGE(PG8_SA(0, 1), a2 + hstep, voffA);
;             PG8_WAIT_V(8); PG8_WAIT_L(0); PG8_BAR; PG8_MMA(0, 0, At, B0); PG8_MMA(0, 1, At, B1); PG8_BAR; PG8_SCHED;
	s_waitcnt lgkmcnt(0)
	v_mfma_f32_16x16x32_bf16 v[60:63], v[144:147], v[182:185], v[60:63]
	v_mfma_f32_16x16x32_bf16 v[56:59], v[152:155], v[182:185], v[56:59]
	v_mfma_f32_16x16x32_bf16 v[44:47], v[144:147], v[190:193], v[44:47]
	v_mfma_f32_16x16x32_bf16 v[40:43], v[152:155], v[190:193], v[40:43]
	v_mfma_f32_16x16x32_bf16 v[28:31], v[144:147], v[198:201], v[28:31]
	v_mfma_f32_16x16x32_bf16 v[24:27], v[152:155], v[198:201], v[24:27]
	v_mfma_f32_16x16x32_bf16 v[12:15], v[144:147], v[206:209], v[12:15]
	v_mfma_f32_16x16x32_bf16 v[8:11], v[152:155], v[206:209], v[8:11]
	v_mfma_f32_16x16x32_bf16 v[60:63], v[148:151], v[186:189], v[60:63]
	v_mfma_f32_16x16x32_bf16 v[56:59], v[156:159], v[186:189], v[56:59]
	v_mfma_f32_16x16x32_bf16 v[44:47], v[148:151], v[194:197], v[44:47]
	v_mfma_f32_16x16x32_bf16 v[40:43], v[156:159], v[194:197], v[40:43]
	v_mfma_f32_16x16x32_bf16 v[28:31], v[148:151], v[202:205], v[28:31]
	v_mfma_f32_16x16x32_bf16 v[24:27], v[156:159], v[202:205], v[24:27]
	v_mfma_f32_16x16x32_bf16 v[12:15], v[148:151], v[210:213], v[12:15]
	v_mfma_f32_16x16x32_bf16 v[8:11], v[156:159], v[210:213], v[8:11]
	v_mfma_f32_16x16x32_bf16 v[52:55], v[160:163], v[182:185], v[52:55]
	v_mfma_f32_16x16x32_bf16 v[48:51], v[168:171], v[182:185], v[48:51]
	v_mfma_f32_16x16x32_bf16 v[36:39], v[160:163], v[190:193], v[36:39]
	v_mfma_f32_16x16x32_bf16 v[32:35], v[168:171], v[190:193], v[32:35]
	v_mfma_f32_16x16x32_bf16 v[20:23], v[160:163], v[198:201], v[20:23]
	v_mfma_f32_16x16x32_bf16 v[16:19], v[168:171], v[198:201], v[16:19]
	v_mfma_f32_16x16x32_bf16 v[4:7], v[160:163], v[206:209], v[4:7]
	v_mfma_f32_16x16x32_bf16 v[0:3], v[168:171], v[206:209], v[0:3]
	v_mfma_f32_16x16x32_bf16 v[52:55], v[164:167], v[186:189], v[52:55]
	v_mfma_f32_16x16x32_bf16 v[48:51], v[172:175], v[186:189], v[48:51]
	v_mfma_f32_16x16x32_bf16 v[36:39], v[164:167], v[194:197], v[36:39]
	v_mfma_f32_16x16x32_bf16 v[32:35], v[172:175], v[194:197], v[32:35]
	v_mfma_f32_16x16x32_bf16 v[20:23], v[164:167], v[202:205], v[20:23]
	v_mfma_f32_16x16x32_bf16 v[16:19], v[172:175], v[202:205], v[16:19]
	v_mfma_f32_16x16x32_bf16 v[4:7], v[164:167], v[210:213], v[4:7]
	v_mfma_f32_16x16x32_bf16 v[0:3], v[172:175], v[210:213], v[0:3]
	s_barrier
	s_add_i32 s28, 0, 0x18000
	s_add_i32 s48, 0, 0x1c000
	v_add_u32_e32 v156, s28, v142
	v_add_u32_e32 v172, s48, v142
	ds_read_b128 v[144:147], v156
	ds_read_b128 v[148:151], v156 offset:1024
	ds_read_b128 v[152:155], v156 offset:2048
	ds_read_b128 v[156:159], v156 offset:3072
	ds_read_b128 v[160:163], v172
	ds_read_b128 v[164:167], v172 offset:1024
	ds_read_b128 v[168:171], v172 offset:2048
	ds_read_b128 v[172:175], v172 offset:3072
	s_add_u32 s38, s66, 0x40000
	s_addc_u32 s39, s67, 0
	s_mov_b32 m0, s63
	v_lshl_add_u64 v[220:221], s[38:39], 0, v[132:133]
	ds_read_b128 v[182:185], v143 offset:32768
	ds_read_b128 v[186:189], v143 offset:33792
	ds_read_b128 v[190:193], v143 offset:34816
	ds_read_b128 v[194:197], v143 offset:35840
	ds_read_b128 v[198:201], v143 offset:36864
	ds_read_b128 v[202:205], v143 offset:37888
	ds_read_b128 v[206:209], v143 offset:38912
	ds_read_b128 v[210:213], v143 offset:39936
	global_load_lds_dwordx4 v[220:221], off
	v_lshl_add_u64 v[220:221], s[38:39], 0, v[130:131]
	s_mov_b32 m0, s69
	s_nop 0
	global_load_lds_dwordx4 v[220:221], off
	s_waitcnt vmcnt(8)
	s_waitcnt lgkmcnt(0)
	s_barrier
	s_waitcnt lgkmcnt(0)
	v_mfma_f32_16x16x32_bf16 v[124:127], v[144:147], v[182:185], v[124:127]
	v_mfma_f32_16x16x32_bf16 v[120:123], v[152:155], v[182:185], v[120:123]
	v_mfma_f32_16x16x32_bf16 v[108:111], v[144:147], v[190:193], v[108:111]
	v_mfma_f32_16x16x32_bf16 v[104:107], v[152:155], v[190:193], v[104:107]
	v_mfma_f32_16x16x32_bf16 v[92:95], v[144:147], v[198:201], v[92:95]
	v_mfma_f32_16x16x32_bf16 v[88:91], v[152:155], v[198:201], v[88:91]
	v_mfma_f32_16x16x32_bf16 v[76:79], v[144:147], v[206:209], v[76:79]
	v_mfma_f32_16x16x32_bf16 v[72:75], v[152:155], v[206:209], v[72:75]
	v_mfma_f32_16x16x32_bf16 v[124:127], v[148:151], v[186:189], v[124:127]
	v_mfma_f32_16x16x32_bf16 v[120:123], v[156:159], v[186:189], v[120:123]
	v_mfma_f32_16x16x32_bf16 v[108:111], v[148:151], v[194:197], v[108:111]
	v_mfma_f32_16x16x32_bf16 v[104:107], v[156:159], v[194:197], v[104:107]
	v_mfma_f32_16x16x32_bf16 v[92:95], v[148:151], v[202:205], v[92:95]
	v_mfma_f32_16x16x32_bf16 v[88:91], v[156:159], v[202:205], v[88:91]
	v_mfma_f32_16x16x32_bf16 v[76:79], v[148:151], v[210:213], v[76:79]
	v_mfma_f32_16x16x32_bf16 v[72:75], v[156:159], v[210:213], v[72:75]
	v_mfma_f32_16x16x32_bf16 v[116:119], v[160:163], v[182:185], v[116:119]
	v_mfma_f32_16x16x32_bf16 v[112:115], v[168:171], v[182:185], v[112:115]
	v_mfma_f32_16x16x32_bf16 v[100:103], v[160:163], v[190:193], v[100:103]
	v_mfma_f32_16x16x32_bf16 v[96:99], v[168:171], v[190:193], v[96:99]
	v_mfma_f32_16x16x32_bf16 v[84:87], v[160:163], v[198:201], v[84:87]
	v_mfma_f32_16x16x32_bf16 v[80:83], v[168:171], v[198:201], v[80:83]
	v_mfma_f32_16x16x32_bf16 v[68:71], v[160:163], v[206:209], v[68:71]
	v_mfma_f32_16x16x32_bf16 v[64:67], v[168:171], v[206:209], v[64:67]
	v_mfma_f32_16x16x32_bf16 v[116:119], v[164:167], v[186:189], v[116:119]
	v_mfma_f32_16x16x32_bf16 v[112:115], v[172:175], v[186:189], v[112:115]
	v_mfma_f32_16x16x32_bf16 v[100:103], v[164:167], v[194:197], v[100:103]
	v_mfma_f32_16x16x32_bf16 v[96:99], v[172:175], v[194:197], v[96:99]
	v_mfma_f32_16x16x32_bf16 v[84:87], v[164:167], v[202:205], v[84:87]
	v_mfma_f32_16x16x32_bf16 v[80:83], v[172:175], v[202:205], v[80:83]
	v_mfma_f32_16x16x32_bf16 v[68:71], v[164:167], v[210:213], v[68:71]
	v_mfma_f32_16x16x32_bf16 v[64:67], v[172:175], v[210:213], v[64:67]
	s_barrier
; #define PG8_STAGE(bufoff, gbase, voff) do { _Pragma("unroll") for (int _i = 0; _i < 2; ++_i) \
;         __builtin_amdgcn_global_load_lds((const unsigned*)((const char*)(gbase) + (voff)[_i]), (PG8_LAS unsigned*)(lds + (bufoff) + ldsw + _i * 8192), 16, 0, 0); } while (0)
; #define PG8_LDA(dst, b, h) do { _Pragma("unroll") for (int m = 0; m < 4; ++m) _Pragma("unroll") for (int k = 0; k < 2; ++k) dst[m][k] = *(const PG8_LAS bf16x8*)(lds + PG8_SA(b, h) + aoff + m * 2048 + k * 1024); } while (0)
; #define PG8_MMA(ai, bj, At, Bt) do { __builtin_amdgcn_s_setprio(1); _Pragma("unroll") for (int m = 0; m < 4; ++m) _Pragma("unroll") for (int n = 0; n < 2; ++n) _Pragma("unroll") for (int k = 0; k < 2; ++k) \
;         acc[ai][bj][m][n] = __builtin_amdgcn_mfma_f32_16x16x32_bf16(Bt[n][k], At[m][k], acc[ai][bj][m][n], 0, 0, 0); __builtin_amdgcn_s_setprio(0); } while (0)
; #define PG8_WAIT_V(n) asm volatile("s_waitcnt vmcnt(" #n ")" ::: "memory")
; #define PG8_WAIT_L(n) asm volatile("s_waitcnt lgkmcnt(" #n ")" ::: "memory")
; #define PG8_BAR __builtin_amdgcn_s_barrier()
; #define PG8_SCHED __builtin_amdgcn_sched_barrier(0)
; template <class Epi, class Sched, bool ALIGN_EPI = false, bool SP2 = false>
; __device__ __forceinline__ void gemm_phase(PG8_LAS unsigned char* lds, const Gemm g, const Sched& S, const Epi& E) {
;     ...
;             PG8_LDA(At, 1, 1); PG8_STAGE(PG8_SB(1, 0), b3, voffB); PG8_STAGE(PG8_SB(1, 1), b3 + hstep, voffB); PG8_STAGE(PG8_SA(1, 0), a3, voffA);
;             PG8_WAIT_V(8); PG8_WAIT_L(0); PG8_BAR; PG8_MMA(1, 0, At, B0); PG8_MMA(1, 1, At, B1); PG8_BAR; PG8_SCHED;
	s_add_i32 s28, s28, s23
	v_lshl_add_u64 v[138:139], v[138:139], 0, s[44:45]
	s_mov_b32 m0, s28
	ds_read_b128 v[182:185], v143 offset:49152
	ds_read_b128 v[186:189], v143 offset:50176
	ds_read_b128 v[190:193], v143 offset:51200
	ds_read_b128 v[194:197], v143 offset:52224
	ds_read_b128 v[198:201], v143 offset:53248
	ds_read_b128 v[202:205], v143 offset:54272
	ds_read_b128 v[206:209], v143 offset:55296
	ds_read_b128 v[210:213], v143 offset:56320
	global_load_lds_dwordx4 v[138:139], off
	s_add_i32 m0, s28, 0x2000
	s_add_u32 s38, s64, 0x40080
	v_lshl_add_u64 v[138:139], v[214:215], 0, s[44:45]
	s_addc_u32 s39, s65, 0
	s_add_i32 s28, s48, s23
	global_load_lds_dwordx4 v[138:139], off
	v_lshl_add_u64 v[138:139], s[38:39], 0, v[176:177]
	s_mov_b32 m0, s28
	s_nop 0
	global_load_lds_dwordx4 v[138:139], off
	v_lshl_add_u64 v[138:139], s[38:39], 0, v[128:129]
	s_add_i32 m0, s28, 0x2000
	s_nop 0
	global_load_lds_dwordx4 v[138:139], off
	v_lshl_add_u64 v[138:139], v[216:217], 0, s[44:45]
	s_mov_b32 m0, s73
	s_nop 0
	global_load_lds_dwordx4 v[138:139], off
	v_lshl_add_u64 v[138:139], v[218:219], 0, s[44:45]
	s_mov_b32 m0, s74
	s_nop 0
	global_load_lds_dwordx4 v[138:139], off
	s_waitcnt vmcnt(8)
	s_waitcnt lgkmcnt(0)
	s_barrier
	s_waitcnt lgkmcnt(0)
	v_mfma_f32_16x16x32_bf16 v[60:63], v[144:147], v[182:185], v[60:63]
	v_mfma_f32_16x16x32_bf16 v[56:59], v[152:155], v[182:185], v[56:59]
	v_mfma_f32_16x16x32_bf16 v[44:47], v[144:147], v[190:193], v[44:47]
	v_mfma_f32_16x16x32_bf16 v[40:43], v[152:155], v[190:193], v[40:43]
	v_mfma_f32_16x16x32_bf16 v[28:31], v[144:147], v[198:201], v[28:31]
	v_mfma_f32_16x16x32_bf16 v[24:27], v[152:155], v[198:201], v[24:27]
	v_mfma_f32_16x16x32_bf16 v[12:15], v[144:147], v[206:209], v[12:15]
	v_mfma_f32_16x16x32_bf16 v[8:11], v[152:155], v[206:209], v[8:11]
	v_mfma_f32_16x16x32_bf16 v[60:63], v[148:151], v[186:189], v[60:63]
	v_mfma_f32_16x16x32_bf16 v[56:59], v[156:159], v[186:189], v[56:59]
	v_mfma_f32_16x16x32_bf16 v[44:47], v[148:151], v[194:197], v[44:47]
	v_mfma_f32_16x16x32_bf16 v[40:43], v[156:159], v[194:197], v[40:43]
	v_mfma_f32_16x16x32_bf16 v[28:31], v[148:151], v[202:205], v[28:31]
	v_mfma_f32_16x16x32_bf16 v[24:27], v[156:159], v[202:205], v[24:27]
	v_mfma_f32_16x16x32_bf16 v[12:15], v[148:151], v[210:213], v[12:15]
	v_mfma_f32_16x16x32_bf16 v[8:11], v[156:159], v[210:213], v[8:11]
	v_mfma_f32_16x16x32_bf16 v[52:55], v[160:163], v[182:185], v[52:55]
	v_mfma_f32_16x16x32_bf16 v[48:51], v[168:171], v[182:185], v[48:51]
	v_mfma_f32_16x16x32_bf16 v[36:39], v[160:163], v[190:193], v[36:39]
	v_mfma_f32_16x16x32_bf16 v[32:35], v[168:171], v[190:193], v[32:35]
	v_mfma_f32_16x16x32_bf16 v[20:23], v[160:163], v[198:201], v[20:23]
	v_mfma_f32_16x16x32_bf16 v[16:19], v[168:171], v[198:201], v[16:19]
	v_mfma_f32_16x16x32_bf16 v[4:7], v[160:163], v[206:209], v[4:7]
	v_mfma_f32_16x16x32_bf16 v[0:3], v[168:171], v[206:209], v[0:3]
	v_mfma_f32_16x16x32_bf16 v[52:55], v[164:167], v[186:189], v[52:55]
	v_mfma_f32_16x16x32_bf16 v[48:51], v[172:175], v[186:189], v[48:51]
	s_add_i32 s80, s80, 2
	v_mfma_f32_16x16x32_bf16 v[36:39], v[164:167], v[194:197], v[36:39]
	s_add_u32 vcc_lo, vcc_lo, 0x100
	v_mfma_f32_16x16x32_bf16 v[32:35], v[172:175], v[194:197], v[32:35]
	s_addc_u32 vcc_hi, vcc_hi, 0
	v_mfma_f32_16x16x32_bf16 v[20:23], v[164:167], v[202:205], v[20:23]
	s_add_u32 s78, s78, 0x100
	v_mfma_f32_16x16x32_bf16 v[16:19], v[172:175], v[202:205], v[16:19]
	s_addc_u32 s79, s79, 0
	v_mfma_f32_16x16x32_bf16 v[4:7], v[164:167], v[210:213], v[4:7]
	s_cmp_gt_u32 s80, 13
	v_mfma_f32_16x16x32_bf16 v[0:3], v[172:175], v[210:213], v[0:3]
	s_barrier
	s_cbranch_scc0 .LBB0_718

; #define PG8_STAGE(bufoff, gbase, voff) do { _Pragma("unroll") for (int _i = 0; _i < 2; ++_i) \
;         __builtin_amdgcn_global_load_lds((const unsigned*)((const char*)(gbase) + (voff)[_i]), (PG8_LAS unsigned*)(lds + (bufoff) + ldsw + _i * 8192), 16, 0, 0); } while (0)
; #define PG8_LDA(dst, b, h) do { _Pragma("unroll") for (int m = 0; m < 4; ++m) _Pragma("unroll") for (int k = 0; k < 2; ++k) dst[m][k] = *(const PG8_LAS bf16x8*)(lds + PG8_SA(b, h) + aoff + m * 2048 + k * 1024); } while (0)
; #define PG8_LDB(dst, b, h) do { _Pragma("unroll") for (int n = 0; n < 2; ++n) _Pragma("unroll") for (int k = 0; k < 2; ++k) dst[n][k] = *(const PG8_LAS bf16x8*)(lds + PG8_SB(b, h) + boff + n * 2048 + k * 1024); } while (0)
; #define PG8_MMA(ai, bj, At, Bt) do { __builtin_amdgcn_s_setprio(1); _Pragma("unroll") for (int m = 0; m < 4; ++m) _Pragma("unroll") for (int n = 0; n < 2; ++n) _Pragma("unroll") for (int k = 0; k < 2; ++k) \
;         acc[ai][bj][m][n] = __builtin_amdgcn_mfma_f32_16x16x32_bf16(Bt[n][k], At[m][k], acc[ai][bj][m][n], 0, 0, 0); __builtin_amdgcn_s_setprio(0); } while (0)
; #define PG8_WAIT_V(n) asm volatile("s_waitcnt vmcnt(" #n ")" ::: "memory")
; #define PG8_WAIT_L(n) asm volatile("s_waitcnt lgkmcnt(" #n ")" ::: "memory")
; template <class Epi, class Sched, bool ALIGN_EPI = false, bool SP2 = false>
; __device__ __forceinline__ void gemm_phase(PG8_LAS unsigned char* lds, const Gemm g, const Sched& S, const Epi& E) {
;     ...
;             const bool last = (t == nt - 2);
;             const char* a1 = cA + (size_t)(t + 1) * kstep;
;             const char* a2 = last ? nA : cA + (size_t)(t + 2) * kstep; const char* b2 = last ? nB : cB + (size_t)(t + 2) * kstep;
;             const char* a3 = a2 + kstep; const char* b3 = b2 + kstep;
;             if (last && has_next) S.a_ready(nxt);
;             if constexpr (SP2) {
;             PG8_LDB(B0, 0, 0); PG8_LDB(B1, 0, 1); PG8_SCHED; PG8_LDA(At, 0, 0); PG8_STAGE(PG8_SA(1, 1), a1 + hstep, voffA);
;             PG8_WAIT_V(8); PG8_WAIT_L(0); PG8_BAR; PG8_MMA(0, 0, At, B0); PG8_MMA(0, 1, At, B1); PG8_BAR; PG8_SCHED;
;             PG8_LDA(At, 0, 1); PG8_STAGE(PG8_SB(0, 0), b2, voffB); PG8_STAGE(PG8_SB(0, 1), b2 + hstep, voffB); PG8_STAGE(PG8_SA(0, 0), a2, voffA);
;             PG8_WAIT_V(8); PG8_WAIT_L(0); PG8_BAR; PG8_MMA(1, 0, At, B0); PG8_MMA(1, 1, At, B1); PG8_BAR; PG8_SCHED;
.Lg3_peel:
	s_add_u32 s28, vcc_lo, 0xfffc0080
	s_addc_u32 s38, vcc_hi, -1
	s_add_i32 s39, 0, 0x10000
	s_cmp_eq_u32 s80, 12
	s_cselect_b32 s67, s41, s38
	s_cselect_b32 s66, s76, s28
	v_add_u32_e32 v138, s39, v142
	s_cselect_b32 s65, s37, s79
	s_cselect_b32 s64, s77, s78
	s_add_i32 s28, 0, 0x14000
	ds_read_b128 v[144:147], v138
	ds_read_b128 v[148:151], v138 offset:1024
	ds_read_b128 v[152:155], v138 offset:2048
	ds_read_b128 v[156:159], v138 offset:3072
	v_add_u32_e32 v138, s28, v142
	ds_read_b128 v[160:163], v138
	ds_read_b128 v[164:167], v138 offset:1024
	ds_read_b128 v[168:171], v138 offset:2048
	ds_read_b128 v[172:175], v138 offset:3072
	v_lshl_add_u64 v[138:139], vcc, 0, v[134:135]
	s_add_i32 m0, s30, 0xc000
	ds_read_b128 v[182:185], v143
	ds_read_b128 v[186:189], v143 offset:1024
	ds_read_b128 v[190:193], v143 offset:2048
	ds_read_b128 v[194:197], v143 offset:3072
	ds_read_b128 v[198:201], v143 offset:4096
	ds_read_b128 v[202:205], v143 offset:5120
	ds_read_b128 v[206:209], v143 offset:6144
	ds_read_b128 v[210:213], v143 offset:7168
	global_load_lds_dwordx4 v[138:139], off
	v_lshl_add_u64 v[138:139], vcc, 0, v[136:137]
	s_add_i32 m0, s30, 0xe000
	s_nop 0
	global_load_lds_dwordx4 v[138:139], off
	s_waitcnt vmcnt(24)
	s_waitcnt lgkmcnt(0)
	s_barrier
	s_waitcnt lgkmcnt(0)
	v_mfma_f32_16x16x32_bf16 v[124:127], v[144:147], v[182:185], 0
	v_mfma_f32_16x16x32_bf16 v[120:123], v[152:155], v[182:185], 0
	v_mfma_f32_16x16x32_bf16 v[108:111], v[144:147], v[190:193], 0
	v_mfma_f32_16x16x32_bf16 v[104:107], v[152:155], v[190:193], 0
	v_mfma_f32_16x16x32_bf16 v[92:95], v[144:147], v[198:201], 0
	v_mfma_f32_16x16x32_bf16 v[88:91], v[152:155], v[198:201], 0
	v_mfma_f32_16x16x32_bf16 v[76:79], v[144:147], v[206:209], 0
	v_mfma_f32_16x16x32_bf16 v[72:75], v[152:155], v[206:209], 0
	v_mfma_f32_16x16x32_bf16 v[124:127], v[148:151], v[186:189], v[124:127]
	v_mfma_f32_16x16x32_bf16 v[120:123], v[156:159], v[186:189], v[120:123]
	v_mfma_f32_16x16x32_bf16 v[108:111], v[148:151], v[194:197], v[108:111]
	v_mfma_f32_16x16x32_bf16 v[104:107], v[156:159], v[194:197], v[104:107]
	v_mfma_f32_16x16x32_bf16 v[92:95], v[148:151], v[202:205], v[92:95]
	v_mfma_f32_16x16x32_bf16 v[88:91], v[156:159], v[202:205], v[88:91]
	v_mfma_f32_16x16x32_bf16 v[76:79], v[148:151], v[210:213], v[76:79]
	v_mfma_f32_16x16x32_bf16 v[72:75], v[156:159], v[210:213], v[72:75]
	v_mfma_f32_16x16x32_bf16 v[116:119], v[160:163], v[182:185], 0
	v_mfma_f32_16x16x32_bf16 v[112:115], v[168:171], v[182:185], 0
	v_mfma_f32_16x16x32_bf16 v[100:103], v[160:163], v[190:193], 0
	v_mfma_f32_16x16x32_bf16 v[96:99], v[168:171], v[190:193], 0
	v_mfma_f32_16x16x32_bf16 v[84:87], v[160:163], v[198:201], 0
	v_mfma_f32_16x16x32_bf16 v[80:83], v[168:171], v[198:201], 0
	v_mfma_f32_16x16x32_bf16 v[68:71], v[160:163], v[206:209], 0
	v_mfma_f32_16x16x32_bf16 v[64:67], v[168:171], v[206:209], 0
	v_mfma_f32_16x16x32_bf16 v[116:119], v[164:167], v[186:189], v[116:119]
	v_mfma_f32_16x16x32_bf16 v[112:115], v[172:175], v[186:189], v[112:115]
	v_mfma_f32_16x16x32_bf16 v[100:103], v[164:167], v[194:197], v[100:103]
	v_mfma_f32_16x16x32_bf16 v[96:99], v[172:175], v[194:197], v[96:99]
	v_mfma_f32_16x16x32_bf16 v[84:87], v[164:167], v[202:205], v[84:87]
	v_mfma_f32_16x16x32_bf16 v[80:83], v[172:175], v[202:205], v[80:83]
	v_mfma_f32_16x16x32_bf16 v[68:71], v[164:167], v[210:213], v[68:71]
	v_mfma_f32_16x16x32_bf16 v[64:67], v[172:175], v[210:213], v[64:67]
	s_barrier
	s_add_i32 s38, s39, s23
	v_lshl_add_u64 v[138:139], s[64:65], 0, v[176:177]
	s_mov_b32 m0, s38
	ds_read_b128 v[182:185], v143 offset:16384
	ds_read_b128 v[186:189], v143 offset:17408
	ds_read_b128 v[190:193], v143 offset:18432
	ds_read_b128 v[194:197], v143 offset:19456
	ds_read_b128 v[198:201], v143 offset:20480
	ds_read_b128 v[202:205], v143 offset:21504
	ds_read_b128 v[206:209], v143 offset:22528
	ds_read_b128 v[210:213], v143 offset:23552
	global_load_lds_dwordx4 v[138:139], off
	s_add_i32 m0, s38, 0x2000
	s_add_u32 s38, s64, 0x40000
	v_lshl_add_u64 v[214:215], s[64:65], 0, v[128:129]
	s_addc_u32 s39, s65, 0
	s_add_i32 s28, s28, s23
	global_load_lds_dwordx4 v[214:215], off
	v_lshl_add_u64 v[216:217], s[38:39], 0, v[176:177]
	s_mov_b32 m0, s28
	v_lshl_add_u64 v[218:219], s[66:67], 0, v[130:131]
	global_load_lds_dwordx4 v[216:217], off
	v_lshl_add_u64 v[216:217], s[38:39], 0, v[128:129]
	s_add_i32 m0, s28, 0x2000
	s_nop 0
	global_load_lds_dwordx4 v[216:217], off
	v_lshl_add_u64 v[216:217], s[66:67], 0, v[132:133]
	s_mov_b32 m0, s30
	s_nop 0
	global_load_lds_dwordx4 v[216:217], off
	s_mov_b32 m0, s31
	s_nop 0
	global_load_lds_dwordx4 v[218:219], off
	s_waitcnt vmcnt(24)
	s_waitcnt lgkmcnt(0)
	s_barrier
; #define PG8_STAGE(bufoff, gbase, voff) do { _Pragma("unroll") for (int _i = 0; _i < 2; ++_i) \
;         __builtin_amdgcn_global_load_lds((const unsigned*)((const char*)(gbase) + (voff)[_i]), (PG8_LAS unsigned*)(lds + (bufoff) + ldsw + _i * 8192), 16, 0, 0); } while (0)
; #define PG8_LDA(dst, b, h) do { _Pragma("unroll") for (int m = 0; m < 4; ++m) _Pragma("unroll") for (int k = 0; k < 2; ++k) dst[m][k] = *(const PG8_LAS bf16x8*)(lds + PG8_SA(b, h) + aoff + m * 2048 + k * 1024); } while (0)
; #define PG8_LDB(dst, b, h) do { _Pragma("unroll") for (int n = 0; n < 2; ++n) _Pragma("unroll") for (int k = 0; k < 2; ++k) dst[n][k] = *(const PG8_LAS bf16x8*)(lds + PG8_SB(b, h) + boff + n * 2048 + k * 1024); } while (0)
; #define PG8_MMA(ai, bj, At, Bt) do { __builtin_amdgcn_s_setprio(1); _Pragma("unroll") for (int m = 0; m < 4; ++m) _Pragma("unroll") for (int n = 0; n < 2; ++n) _Pragma("unroll") for (int k = 0; k < 2; ++k) \
;         acc[ai][bj][m][n] = __builtin_amdgcn_mfma_f32_16x16x32_bf16(Bt[n][k], At[m][k], acc[ai][bj][m][n], 0, 0, 0); __builtin_amdgcn_s_setprio(0); } while (0)
; #define PG8_WAIT_V(n) asm volatile("s_waitcnt vmcnt(" #n ")" ::: "memory")
; #define PG8_WAIT_L(n) asm volatile("s_waitcnt lgkmcnt(" #n ")" ::: "memory")
; #define PG8_BAR __builtin_amdgcn_s_barrier()
; #define PG8_SCHED __builtin_amdgcn_sched_barrier(0)
; template <class Epi, class Sched, bool ALIGN_EPI = false, bool SP2 = false>
; __device__ __forceinline__ void gemm_phase(PG8_LAS unsigned char* lds, const Gemm g, const Sched& S, const Epi& E) {
;     ...
;             PG8_WAIT_V(8); PG8_WAIT_L(0); PG8_BAR; PG8_MMA(1, 0, At, B0); PG8_MMA(1, 1, At, B1); PG8_BAR; PG8_SCHED;
;             PG8_LDB(B0, 1, 0); PG8_LDB(B1, 1, 1); PG8_SCHED; PG8_LDA(At, 1, 0); PG8_STAGE(PG8_SA(0, 1), a2 + hstep, voffA);
;             PG8_WAIT_V(8); PG8_WAIT_L(0); PG8_BAR; PG8_MMA(0, 0, At, B0); PG8_MMA(0, 1, At, B1); PG8_BAR; PG8_SCHED;
	s_waitcnt lgkmcnt(0)
	v_mfma_f32_16x16x32_bf16 v[60:63], v[144:147], v[182:185], 0
	v_mfma_f32_16x16x32_bf16 v[56:59], v[152:155], v[182:185], 0
	v_mfma_f32_16x16x32_bf16 v[44:47], v[144:147], v[190:193], 0
	v_mfma_f32_16x16x32_bf16 v[40:43], v[152:155], v[190:193], 0
	v_mfma_f32_16x16x32_bf16 v[28:31], v[144:147], v[198:201], 0
	v_mfma_f32_16x16x32_bf16 v[24:27], v[152:155], v[198:201], 0
	v_mfma_f32_16x16x32_bf16 v[12:15], v[144:147], v[206:209], 0
	v_mfma_f32_16x16x32_bf16 v[8:11], v[152:155], v[206:209], 0
	v_mfma_f32_16x16x32_bf16 v[60:63], v[148:151], v[186:189], v[60:63]
	v_mfma_f32_16x16x32_bf16 v[56:59], v[156:159], v[186:189], v[56:59]
	v_mfma_f32_16x16x32_bf16 v[44:47], v[148:151], v[194:197], v[44:47]
	v_mfma_f32_16x16x32_bf16 v[40:43], v[156:159], v[194:197], v[40:43]
	v_mfma_f32_16x16x32_bf16 v[28:31], v[148:151], v[202:205], v[28:31]
	v_mfma_f32_16x16x32_bf16 v[24:27], v[156:159], v[202:205], v[24:27]
	v_mfma_f32_16x16x32_bf16 v[12:15], v[148:151], v[210:213], v[12:15]
	v_mfma_f32_16x16x32_bf16 v[8:11], v[156:159], v[210:213], v[8:11]
	v_mfma_f32_16x16x32_bf16 v[52:55], v[160:163], v[182:185], 0
	v_mfma_f32_16x16x32_bf16 v[48:51], v[168:171], v[182:185], 0
	v_mfma_f32_16x16x32_bf16 v[36:39], v[160:163], v[190:193], 0
	v_mfma_f32_16x16x32_bf16 v[32:35], v[168:171], v[190:193], 0
	v_mfma_f32_16x16x32_bf16 v[20:23], v[160:163], v[198:201], 0
	v_mfma_f32_16x16x32_bf16 v[16:19], v[168:171], v[198:201], 0
	v_mfma_f32_16x16x32_bf16 v[4:7], v[160:163], v[206:209], 0
	v_mfma_f32_16x16x32_bf16 v[0:3], v[168:171], v[206:209], 0
	v_mfma_f32_16x16x32_bf16 v[52:55], v[164:167], v[186:189], v[52:55]
	v_mfma_f32_16x16x32_bf16 v[48:51], v[172:175], v[186:189], v[48:51]
	v_mfma_f32_16x16x32_bf16 v[36:39], v[164:167], v[194:197], v[36:39]
	v_mfma_f32_16x16x32_bf16 v[32:35], v[172:175], v[194:197], v[32:35]
	v_mfma_f32_16x16x32_bf16 v[20:23], v[164:167], v[202:205], v[20:23]
	v_mfma_f32_16x16x32_bf16 v[16:19], v[172:175], v[202:205], v[16:19]
	v_mfma_f32_16x16x32_bf16 v[4:7], v[164:167], v[210:213], v[4:7]
	v_mfma_f32_16x16x32_bf16 v[0:3], v[172:175], v[210:213], v[0:3]
	s_barrier
	s_add_i32 s28, 0, 0x18000
	s_add_i32 s48, 0, 0x1c000
	v_add_u32_e32 v156, s28, v142
	v_add_u32_e32 v172, s48, v142
	ds_read_b128 v[144:147], v156
	ds_read_b128 v[148:151], v156 offset:1024
	ds_read_b128 v[152:155], v156 offset:2048
	ds_read_b128 v[156:159], v156 offset:3072
	ds_read_b128 v[160:163], v172
	ds_read_b128 v[164:167], v172 offset:1024
	ds_read_b128 v[168:171], v172 offset:2048
	ds_read_b128 v[172:175], v172 offset:3072
	s_add_u32 s38, s66, 0x40000
	s_addc_u32 s39, s67, 0
	s_mov_b32 m0, s63
	v_lshl_add_u64 v[220:221], s[38:39], 0, v[132:133]
	ds_read_b128 v[182:185], v143 offset:32768
	ds_read_b128 v[186:189], v143 offset:33792
	ds_read_b128 v[190:193], v143 offset:34816
	ds_read_b128 v[194:197], v143 offset:35840
	ds_read_b128 v[198:201], v143 offset:36864
	ds_read_b128 v[202:205], v143 offset:37888
	ds_read_b128 v[206:209], v143 offset:38912
	ds_read_b128 v[210:213], v143 offset:39936
	global_load_lds_dwordx4 v[220:221], off
	v_lshl_add_u64 v[220:221], s[38:39], 0, v[130:131]
	s_mov_b32 m0, s69
	s_nop 0
	global_load_lds_dwordx4 v[220:221], off
	s_waitcnt vmcnt(8)
	s_waitcnt lgkmcnt(0)
	s_barrier
	s_waitcnt lgkmcnt(0)
	v_mfma_f32_16x16x32_bf16 v[124:127], v[144:147], v[182:185], v[124:127]
	v_mfma_f32_16x16x32_bf16 v[120:123], v[152:155], v[182:185], v[120:123]
	v_mfma_f32_16x16x32_bf16 v[108:111], v[144:147], v[190:193], v[108:111]
	v_mfma_f32_16x16x32_bf16 v[104:107], v[152:155], v[190:193], v[104:107]
	v_mfma_f32_16x16x32_bf16 v[92:95], v[144:147], v[198:201], v[92:95]
	v_mfma_f32_16x16x32_bf16 v[88:91], v[152:155], v[198:201], v[88:91]
	v_mfma_f32_16x16x32_bf16 v[76:79], v[144:147], v[206:209], v[76:79]
	v_mfma_f32_16x16x32_bf16 v[72:75], v[152:155], v[206:209], v[72:75]
	v_mfma_f32_16x16x32_bf16 v[124:127], v[148:151], v[186:189], v[124:127]
	v_mfma_f32_16x16x32_bf16 v[120:123], v[156:159], v[186:189], v[120:123]
	v_mfma_f32_16x16x32_bf16 v[108:111], v[148:151], v[194:197], v[108:111]
	v_mfma_f32_16x16x32_bf16 v[104:107], v[156:159], v[194:197], v[104:107]
	v_mfma_f32_16x16x32_bf16 v[92:95], v[148:151], v[202:205], v[92:95]
	v_mfma_f32_16x16x32_bf16 v[88:91], v[156:159], v[202:205], v[88:91]
	v_mfma_f32_16x16x32_bf16 v[76:79], v[148:151], v[210:213], v[76:79]
	v_mfma_f32_16x16x32_bf16 v[72:75], v[156:159], v[210:213], v[72:75]
	v_mfma_f32_16x16x32_bf16 v[116:119], v[160:163], v[182:185], v[116:119]
	v_mfma_f32_16x16x32_bf16 v[112:115], v[168:171], v[182:185], v[112:115]
	v_mfma_f32_16x16x32_bf16 v[100:103], v[160:163], v[190:193], v[100:103]
	v_mfma_f32_16x16x32_bf16 v[96:99], v[168:171], v[190:193], v[96:99]
	v_mfma_f32_16x16x32_bf16 v[84:87], v[160:163], v[198:201], v[84:87]
	v_mfma_f32_16x16x32_bf16 v[80:83], v[168:171], v[198:201], v[80:83]
	v_mfma_f32_16x16x32_bf16 v[68:71], v[160:163], v[206:209], v[68:71]
	v_mfma_f32_16x16x32_bf16 v[64:67], v[168:171], v[206:209], v[64:67]
	v_mfma_f32_16x16x32_bf16 v[116:119], v[164:167], v[186:189], v[116:119]
	v_mfma_f32_16x16x32_bf16 v[112:115], v[172:175], v[186:189], v[112:115]
	v_mfma_f32_16x16x32_bf16 v[100:103], v[164:167], v[194:197], v[100:103]
	v_mfma_f32_16x16x32_bf16 v[96:99], v[172:175], v[194:197], v[96:99]
	v_mfma_f32_16x16x32_bf16 v[84:87], v[164:167], v[202:205], v[84:87]
	v_mfma_f32_16x16x32_bf16 v[80:83], v[172:175], v[202:205], v[80:83]
	v_mfma_f32_16x16x32_bf16 v[68:71], v[164:167], v[210:213], v[68:71]
	v_mfma_f32_16x16x32_bf16 v[64:67], v[172:175], v[210:213], v[64:67]
	s_barrier
; #define PG8_STAGE(bufoff, gbase, voff) do { _Pragma("unroll") for (int _i = 0; _i < 2; ++_i) \
;         __builtin_amdgcn_global_load_lds((const unsigned*)((const char*)(gbase) + (voff)[_i]), (PG8_LAS unsigned*)(lds + (bufoff) + ldsw + _i * 8192), 16, 0, 0); } while (0)
; #define PG8_LDA(dst, b, h) do { _Pragma("unroll") for (int m = 0; m < 4; ++m) _Pragma("unroll") for (int k = 0; k < 2; ++k) dst[m][k] = *(const PG8_LAS bf16x8*)(lds + PG8_SA(b, h) + aoff + m * 2048 + k * 1024); } while (0)
; #define PG8_MMA(ai, bj, At, Bt) do { __builtin_amdgcn_s_setprio(1); _Pragma("unroll") for (int m = 0; m < 4; ++m) _Pragma("unroll") for (int n = 0; n < 2; ++n) _Pragma("unroll") for (int k = 0; k < 2; ++k) \
;         acc[ai][bj][m][n] = __builtin_amdgcn_mfma_f32_16x16x32_bf16(Bt[n][k], At[m][k], acc[ai][bj][m][n], 0, 0, 0); __builtin_amdgcn_s_setprio(0); } while (0)
; #define PG8_WAIT_V(n) asm volatile("s_waitcnt vmcnt(" #n ")" ::: "memory")
; #define PG8_WAIT_L(n) asm volatile("s_waitcnt lgkmcnt(" #n ")" ::: "memory")
; #define PG8_BAR __builtin_amdgcn_s_barrier()
; #define PG8_SCHED __builtin_amdgcn_sched_barrier(0)
; template <class Epi, class Sched, bool ALIGN_EPI = false, bool SP2 = false>
; __device__ __forceinline__ void gemm_phase(PG8_LAS unsigned char* lds, const Gemm g, const Sched& S, const Epi& E) {
;     ...
;             PG8_LDA(At, 1, 1); PG8_STAGE(PG8_SB(1, 0), b3, voffB); PG8_STAGE(PG8_SB(1, 1), b3 + hstep, voffB); PG8_STAGE(PG8_SA(1, 0), a3, voffA);
;             PG8_WAIT_V(8); PG8_WAIT_L(0); PG8_BAR; PG8_MMA(1, 0, At, B0); PG8_MMA(1, 1, At, B1); PG8_BAR; PG8_SCHED;
	s_add_i32 s28, s28, s23
	v_lshl_add_u64 v[138:139], v[138:139], 0, s[44:45]
	s_mov_b32 m0, s28
	ds_read_b128 v[182:185], v143 offset:49152
	ds_read_b128 v[186:189], v143 offset:50176
	ds_read_b128 v[190:193], v143 offset:51200
	ds_read_b128 v[194:197], v143 offset:52224
	ds_read_b128 v[198:201], v143 offset:53248
	ds_read_b128 v[202:205], v143 offset:54272
	ds_read_b128 v[206:209], v143 offset:55296
	ds_read_b128 v[210:213], v143 offset:56320
	global_load_lds_dwordx4 v[138:139], off
	s_add_i32 m0, s28, 0x2000
	s_add_u32 s38, s64, 0x40080
	v_lshl_add_u64 v[138:139], v[214:215], 0, s[44:45]
	s_addc_u32 s39, s65, 0
	s_add_i32 s28, s48, s23
	global_load_lds_dwordx4 v[138:139], off
	v_lshl_add_u64 v[138:139], s[38:39], 0, v[176:177]
	s_mov_b32 m0, s28
	s_nop 0
	global_load_lds_dwordx4 v[138:139], off
	v_lshl_add_u64 v[138:139], s[38:39], 0, v[128:129]
	s_add_i32 m0, s28, 0x2000
	s_nop 0
	global_load_lds_dwordx4 v[138:139], off
	v_lshl_add_u64 v[138:139], v[216:217], 0, s[44:45]
	s_mov_b32 m0, s73
	s_nop 0
	global_load_lds_dwordx4 v[138:139], off
	v_lshl_add_u64 v[138:139], v[218:219], 0, s[44:45]
	s_mov_b32 m0, s74
	s_nop 0
	global_load_lds_dwordx4 v[138:139], off
	s_waitcnt vmcnt(8)
	s_waitcnt lgkmcnt(0)
	s_barrier
	s_waitcnt lgkmcnt(0)
	v_mfma_f32_16x16x32_bf16 v[60:63], v[144:147], v[182:185], v[60:63]
	v_mfma_f32_16x16x32_bf16 v[56:59], v[152:155], v[182:185], v[56:59]
	v_mfma_f32_16x16x32_bf16 v[44:47], v[144:147], v[190:193], v[44:47]
	v_mfma_f32_16x16x32_bf16 v[40:43], v[152:155], v[190:193], v[40:43]
	v_mfma_f32_16x16x32_bf16 v[28:31], v[144:147], v[198:201], v[28:31]
	v_mfma_f32_16x16x32_bf16 v[24:27], v[152:155], v[198:201], v[24:27]
	v_mfma_f32_16x16x32_bf16 v[12:15], v[144:147], v[206:209], v[12:15]
	v_mfma_f32_16x16x32_bf16 v[8:11], v[152:155], v[206:209], v[8:11]
	v_mfma_f32_16x16x32_bf16 v[60:63], v[148:151], v[186:189], v[60:63]
	v_mfma_f32_16x16x32_bf16 v[56:59], v[156:159], v[186:189], v[56:59]
	v_mfma_f32_16x16x32_bf16 v[44:47], v[148:151], v[194:197], v[44:47]
	v_mfma_f32_16x16x32_bf16 v[40:43], v[156:159], v[194:197], v[40:43]
	v_mfma_f32_16x16x32_bf16 v[28:31], v[148:151], v[202:205], v[28:31]
	v_mfma_f32_16x16x32_bf16 v[24:27], v[156:159], v[202:205], v[24:27]
	v_mfma_f32_16x16x32_bf16 v[12:15], v[148:151], v[210:213], v[12:15]
	v_mfma_f32_16x16x32_bf16 v[8:11], v[156:159], v[210:213], v[8:11]
	v_mfma_f32_16x16x32_bf16 v[52:55], v[160:163], v[182:185], v[52:55]
	v_mfma_f32_16x16x32_bf16 v[48:51], v[168:171], v[182:185], v[48:51]
	v_mfma_f32_16x16x32_bf16 v[36:39], v[160:163], v[190:193], v[36:39]
	v_mfma_f32_16x16x32_bf16 v[32:35], v[168:171], v[190:193], v[32:35]
	v_mfma_f32_16x16x32_bf16 v[20:23], v[160:163], v[198:201], v[20:23]
	v_mfma_f32_16x16x32_bf16 v[16:19], v[168:171], v[198:201], v[16:19]
	v_mfma_f32_16x16x32_bf16 v[4:7], v[160:163], v[206:209], v[4:7]
	v_mfma_f32_16x16x32_bf16 v[0:3], v[168:171], v[206:209], v[0:3]
	v_mfma_f32_16x16x32_bf16 v[52:55], v[164:167], v[186:189], v[52:55]
	v_mfma_f32_16x16x32_bf16 v[48:51], v[172:175], v[186:189], v[48:51]
	s_add_i32 s80, s80, 2
	v_mfma_f32_16x16x32_bf16 v[36:39], v[164:167], v[194:197], v[36:39]
	s_add_u32 vcc_lo, vcc_lo, 0x100
	v_mfma_f32_16x16x32_bf16 v[32:35], v[172:175], v[194:197], v[32:35]
	s_addc_u32 vcc_hi, vcc_hi, 0
	v_mfma_f32_16x16x32_bf16 v[20:23], v[164:167], v[202:205], v[20:23]
	s_add_u32 s78, s78, 0x100
	v_mfma_f32_16x16x32_bf16 v[16:19], v[172:175], v[202:205], v[16:19]
	s_addc_u32 s79, s79, 0
	v_mfma_f32_16x16x32_bf16 v[4:7], v[164:167], v[210:213], v[4:7]
	s_cmp_gt_u32 s80, 13
	v_mfma_f32_16x16x32_bf16 v[0:3], v[172:175], v[210:213], v[0:3]
	s_barrier
	s_cbranch_scc0 .LBB0_718
	s_branch .Lg3_post

; #define PG8_STAGE(bufoff, gbase, voff) do { _Pragma("unroll") for (int _i = 0; _i < 2; ++_i) \
;         __builtin_amdgcn_global_load_lds((const unsigned*)((const char*)(gbase) + (voff)[_i]), (PG8_LAS unsigned*)(lds + (bufoff) + ldsw + _i * 8192), 16, 0, 0); } while (0)
; #define PG8_LDA(dst, b, h) do { _Pragma("unroll") for (int m = 0; m < 4; ++m) _Pragma("unroll") for (int k = 0; k < 2; ++k) dst[m][k] = *(const PG8_LAS bf16x8*)(lds + PG8_SA(b, h) + aoff + m * 2048 + k * 1024); } while (0)
; #define PG8_LDB(dst, b, h) do { _Pragma("unroll") for (int n = 0; n < 2; ++n) _Pragma("unroll") for (int k = 0; k < 2; ++k) dst[n][k] = *(const PG8_LAS bf16x8*)(lds + PG8_SB(b, h) + boff + n * 2048 + k * 1024); } while (0)
; #define PG8_MMA(ai, bj, At, Bt) do { __builtin_amdgcn_s_setprio(1); _Pragma("unroll") for (int m = 0; m < 4; ++m) _Pragma("unroll") for (int n = 0; n < 2; ++n) _Pragma("unroll") for (int k = 0; k < 2; ++k) \
;         acc[ai][bj][m][n] = __builtin_amdgcn_mfma_f32_16x16x32_bf16(Bt[n][k], At[m][k], acc[ai][bj][m][n], 0, 0, 0); __builtin_amdgcn_s_setprio(0); } while (0)
; #define PG8_WAIT_V(n) asm volatile("s_waitcnt vmcnt(" #n ")" ::: "memory")
; #define PG8_WAIT_L(n) asm volatile("s_waitcnt lgkmcnt(" #n ")" ::: "memory")
; template <class Epi, class Sched, bool ALIGN_EPI = false, bool SP2 = false>
; __device__ __forceinline__ void gemm_phase(PG8_LAS unsigned char* lds, const Gemm g, const Sched& S, const Epi& E) {
;     ...
;             const bool last = (t == nt - 2);
;             const char* a1 = cA + (size_t)(t + 1) * kstep;
;             const char* a2 = last ? nA : cA + (size_t)(t + 2) * kstep; const char* b2 = last ? nB : cB + (size_t)(t + 2) * kstep;
;             const char* a3 = a2 + kstep; const char* b3 = b2 + kstep;
;             if (last && has_next) S.a_ready(nxt);
;             if constexpr (SP2) {
;             PG8_LDB(B0, 0, 0); PG8_LDB(B1, 0, 1); PG8_SCHED; PG8_LDA(At, 0, 0); PG8_STAGE(PG8_SA(1, 1), a1 + hstep, voffA);
;             PG8_WAIT_V(8); PG8_WAIT_L(0); PG8_BAR; PG8_MMA(0, 0, At, B0); PG8_MMA(0, 1, At, B1); PG8_BAR; PG8_SCHED;
;             PG8_LDA(At, 0, 1); PG8_STAGE(PG8_SB(0, 0), b2, voffB); PG8_STAGE(PG8_SB(0, 1), b2 + hstep, voffB); PG8_STAGE(PG8_SA(0, 0), a2, voffA);
;             PG8_WAIT_V(8); PG8_WAIT_L(0); PG8_BAR; PG8_MMA(1, 0, At, B0); PG8_MMA(1, 1, At, B1); PG8_BAR; PG8_SCHED;
.LBB0_790:
	s_add_u32 s4, s64, 0xfff00080
	s_addc_u32 s5, s65, -1
	s_add_i32 s28, 0, 0x10000
	s_cmp_eq_u32 s74, 60
	s_cselect_b32 s7, s35, s5
	s_cselect_b32 s6, s72, s4
	v_add_u32_e32 v138, s28, v142
	s_cselect_b32 s5, s27, s67
	s_cselect_b32 s4, s73, s66
	s_add_i32 s48, 0, 0x14000
	ds_read_b128 v[144:147], v138
	ds_read_b128 v[148:151], v138 offset:1024
	ds_read_b128 v[152:155], v138 offset:2048
	ds_read_b128 v[156:159], v138 offset:3072
	v_add_u32_e32 v138, s48, v142
	ds_read_b128 v[160:163], v138
	ds_read_b128 v[164:167], v138 offset:1024
	ds_read_b128 v[168:171], v138 offset:2048
	ds_read_b128 v[172:175], v138 offset:3072
	v_lshl_add_u64 v[138:139], s[64:65], 0, v[134:135]
	s_add_i32 m0, s23, 0xc000
	ds_read_b128 v[182:185], v143
	ds_read_b128 v[186:189], v143 offset:1024
	ds_read_b128 v[190:193], v143 offset:2048
	ds_read_b128 v[194:197], v143 offset:3072
	ds_read_b128 v[198:201], v143 offset:4096
	ds_read_b128 v[202:205], v143 offset:5120
	ds_read_b128 v[206:209], v143 offset:6144
	ds_read_b128 v[210:213], v143 offset:7168
	global_load_lds_dwordx4 v[138:139], off
	v_lshl_add_u64 v[138:139], s[64:65], 0, v[136:137]
	s_add_i32 m0, s23, 0xe000
	s_nop 0
	global_load_lds_dwordx4 v[138:139], off
	s_waitcnt vmcnt(8)
	s_waitcnt lgkmcnt(0)
	s_barrier
	s_waitcnt lgkmcnt(0)
	v_mfma_f32_16x16x32_bf16 v[124:127], v[144:147], v[182:185], v[124:127]
	v_mfma_f32_16x16x32_bf16 v[120:123], v[152:155], v[182:185], v[120:123]
	v_mfma_f32_16x16x32_bf16 v[116:119], v[144:147], v[190:193], v[116:119]
	v_mfma_f32_16x16x32_bf16 v[108:111], v[152:155], v[190:193], v[108:111]
	v_mfma_f32_16x16x32_bf16 v[100:103], v[144:147], v[198:201], v[100:103]
	v_mfma_f32_16x16x32_bf16 v[92:95], v[152:155], v[198:201], v[92:95]
	v_mfma_f32_16x16x32_bf16 v[84:87], v[144:147], v[206:209], v[84:87]
	v_mfma_f32_16x16x32_bf16 v[76:79], v[152:155], v[206:209], v[76:79]
	v_mfma_f32_16x16x32_bf16 v[124:127], v[148:151], v[186:189], v[124:127]
	v_mfma_f32_16x16x32_bf16 v[120:123], v[156:159], v[186:189], v[120:123]
	v_mfma_f32_16x16x32_bf16 v[116:119], v[148:151], v[194:197], v[116:119]
	v_mfma_f32_16x16x32_bf16 v[108:111], v[156:159], v[194:197], v[108:111]
	v_mfma_f32_16x16x32_bf16 v[100:103], v[148:151], v[202:205], v[100:103]
	v_mfma_f32_16x16x32_bf16 v[92:95], v[156:159], v[202:205], v[92:95]
	v_mfma_f32_16x16x32_bf16 v[84:87], v[148:151], v[210:213], v[84:87]
	v_mfma_f32_16x16x32_bf16 v[76:79], v[156:159], v[210:213], v[76:79]
	v_mfma_f32_16x16x32_bf16 v[112:115], v[160:163], v[182:185], v[112:115]
	v_mfma_f32_16x16x32_bf16 v[104:107], v[168:171], v[182:185], v[104:107]
	v_mfma_f32_16x16x32_bf16 v[96:99], v[160:163], v[190:193], v[96:99]
	v_mfma_f32_16x16x32_bf16 v[88:91], v[168:171], v[190:193], v[88:91]
	v_mfma_f32_16x16x32_bf16 v[80:83], v[160:163], v[198:201], v[80:83]
	v_mfma_f32_16x16x32_bf16 v[72:75], v[168:171], v[198:201], v[72:75]
	v_mfma_f32_16x16x32_bf16 v[68:71], v[160:163], v[206:209], v[68:71]
	v_mfma_f32_16x16x32_bf16 v[64:67], v[168:171], v[206:209], v[64:67]
	v_mfma_f32_16x16x32_bf16 v[112:115], v[164:167], v[186:189], v[112:115]
	v_mfma_f32_16x16x32_bf16 v[104:107], v[172:175], v[186:189], v[104:107]
	v_mfma_f32_16x16x32_bf16 v[96:99], v[164:167], v[194:197], v[96:99]
	v_mfma_f32_16x16x32_bf16 v[88:91], v[172:175], v[194:197], v[88:91]
	v_mfma_f32_16x16x32_bf16 v[80:83], v[164:167], v[202:205], v[80:83]
	v_mfma_f32_16x16x32_bf16 v[72:75], v[172:175], v[202:205], v[72:75]
	v_mfma_f32_16x16x32_bf16 v[68:71], v[164:167], v[210:213], v[68:71]
	v_mfma_f32_16x16x32_bf16 v[64:67], v[172:175], v[210:213], v[64:67]
	s_barrier
	s_add_i32 s28, s28, s22
	v_lshl_add_u64 v[138:139], s[4:5], 0, v[176:177]
	s_mov_b32 m0, s28
	ds_read_b128 v[182:185], v143 offset:16384
	ds_read_b128 v[186:189], v143 offset:17408
	ds_read_b128 v[190:193], v143 offset:18432
	ds_read_b128 v[194:197], v143 offset:19456
	ds_read_b128 v[198:201], v143 offset:20480
	ds_read_b128 v[202:205], v143 offset:21504
	ds_read_b128 v[206:209], v143 offset:22528
	ds_read_b128 v[210:213], v143 offset:23552
	global_load_lds_dwordx4 v[138:139], off
	s_add_i32 m0, s28, 0x2000
	s_add_u32 s38, s4, 0x100000
	v_lshl_add_u64 v[214:215], s[4:5], 0, v[128:129]
	s_addc_u32 s39, s5, 0
	s_add_i32 s28, s48, s22
	global_load_lds_dwordx4 v[214:215], off
	v_lshl_add_u64 v[216:217], s[38:39], 0, v[176:177]
	s_mov_b32 m0, s28
	v_lshl_add_u64 v[218:219], s[6:7], 0, v[130:131]
	global_load_lds_dwordx4 v[216:217], off
	v_lshl_add_u64 v[216:217], s[38:39], 0, v[128:129]
	s_add_i32 m0, s28, 0x2000
	s_nop 0
	global_load_lds_dwordx4 v[216:217], off
	v_lshl_add_u64 v[216:217], s[6:7], 0, v[132:133]
	s_mov_b32 m0, s23
	s_nop 0
	global_load_lds_dwordx4 v[216:217], off
	s_mov_b32 m0, s24
	s_nop 0
	global_load_lds_dwordx4 v[218:219], off
	s_waitcnt vmcnt(8)
	s_waitcnt lgkmcnt(0)
	s_barrier
; #define PG8_STAGE(bufoff, gbase, voff) do { _Pragma("unroll") for (int _i = 0; _i < 2; ++_i) \
;         __builtin_amdgcn_global_load_lds((const unsigned*)((const char*)(gbase) + (voff)[_i]), (PG8_LAS unsigned*)(lds + (bufoff) + ldsw + _i * 8192), 16, 0, 0); } while (0)
; #define PG8_LDA(dst, b, h) do { _Pragma("unroll") for (int m = 0; m < 4; ++m) _Pragma("unroll") for (int k = 0; k < 2; ++k) dst[m][k] = *(const PG8_LAS bf16x8*)(lds + PG8_SA(b, h) + aoff + m * 2048 + k * 1024); } while (0)
; #define PG8_LDB(dst, b, h) do { _Pragma("unroll") for (int n = 0; n < 2; ++n) _Pragma("unroll") for (int k = 0; k < 2; ++k) dst[n][k] = *(const PG8_LAS bf16x8*)(lds + PG8_SB(b, h) + boff + n * 2048 + k * 1024); } while (0)
; #define PG8_MMA(ai, bj, At, Bt) do { __builtin_amdgcn_s_setprio(1); _Pragma("unroll") for (int m = 0; m < 4; ++m) _Pragma("unroll") for (int n = 0; n < 2; ++n) _Pragma("unroll") for (int k = 0; k < 2; ++k) \
;         acc[ai][bj][m][n] = __builtin_amdgcn_mfma_f32_16x16x32_bf16(Bt[n][k], At[m][k], acc[ai][bj][m][n], 0, 0, 0); __builtin_amdgcn_s_setprio(0); } while (0)
; #define PG8_WAIT_V(n) asm volatile("s_waitcnt vmcnt(" #n ")" ::: "memory")
; #define PG8_WAIT_L(n) asm volatile("s_waitcnt lgkmcnt(" #n ")" ::: "memory")
; #define PG8_BAR __builtin_amdgcn_s_barrier()
; #define PG8_SCHED __builtin_amdgcn_sched_barrier(0)
; template <class Epi, class Sched, bool ALIGN_EPI = false, bool SP2 = false>
; __device__ __forceinline__ void gemm_phase(PG8_LAS unsigned char* lds, const Gemm g, const Sched& S, const Epi& E) {
;     ...
;             PG8_WAIT_V(8); PG8_WAIT_L(0); PG8_BAR; PG8_MMA(1, 0, At, B0); PG8_MMA(1, 1, At, B1); PG8_BAR; PG8_SCHED;
;             PG8_LDB(B0, 1, 0); PG8_LDB(B1, 1, 1); PG8_SCHED; PG8_LDA(At, 1, 0); PG8_STAGE(PG8_SA(0, 1), a2 + hstep, voffA);
;             PG8_WAIT_V(8); PG8_WAIT_L(0); PG8_BAR; PG8_MMA(0, 0, At, B0); PG8_MMA(0, 1, At, B1); PG8_BAR; PG8_SCHED;
	s_waitcnt lgkmcnt(0)
	v_mfma_f32_16x16x32_bf16 v[60:63], v[144:147], v[182:185], v[60:63]
	v_mfma_f32_16x16x32_bf16 v[56:59], v[152:155], v[182:185], v[56:59]
	v_mfma_f32_16x16x32_bf16 v[52:55], v[144:147], v[190:193], v[52:55]
	v_mfma_f32_16x16x32_bf16 v[44:47], v[152:155], v[190:193], v[44:47]
	v_mfma_f32_16x16x32_bf16 v[36:39], v[144:147], v[198:201], v[36:39]
	v_mfma_f32_16x16x32_bf16 v[28:31], v[152:155], v[198:201], v[28:31]
	v_mfma_f32_16x16x32_bf16 v[20:23], v[144:147], v[206:209], v[20:23]
	v_mfma_f32_16x16x32_bf16 v[12:15], v[152:155], v[206:209], v[12:15]
	v_mfma_f32_16x16x32_bf16 v[60:63], v[148:151], v[186:189], v[60:63]
	v_mfma_f32_16x16x32_bf16 v[56:59], v[156:159], v[186:189], v[56:59]
	v_mfma_f32_16x16x32_bf16 v[52:55], v[148:151], v[194:197], v[52:55]
	v_mfma_f32_16x16x32_bf16 v[44:47], v[156:159], v[194:197], v[44:47]
	v_mfma_f32_16x16x32_bf16 v[36:39], v[148:151], v[202:205], v[36:39]
	v_mfma_f32_16x16x32_bf16 v[28:31], v[156:159], v[202:205], v[28:31]
	v_mfma_f32_16x16x32_bf16 v[20:23], v[148:151], v[210:213], v[20:23]
	v_mfma_f32_16x16x32_bf16 v[12:15], v[156:159], v[210:213], v[12:15]
	v_mfma_f32_16x16x32_bf16 v[48:51], v[160:163], v[182:185], v[48:51]
	v_mfma_f32_16x16x32_bf16 v[40:43], v[168:171], v[182:185], v[40:43]
	v_mfma_f32_16x16x32_bf16 v[32:35], v[160:163], v[190:193], v[32:35]
	v_mfma_f32_16x16x32_bf16 v[24:27], v[168:171], v[190:193], v[24:27]
	v_mfma_f32_16x16x32_bf16 v[16:19], v[160:163], v[198:201], v[16:19]
	v_mfma_f32_16x16x32_bf16 v[8:11], v[168:171], v[198:201], v[8:11]
	v_mfma_f32_16x16x32_bf16 v[4:7], v[160:163], v[206:209], v[4:7]
	v_mfma_f32_16x16x32_bf16 v[0:3], v[168:171], v[206:209], v[0:3]
	v_mfma_f32_16x16x32_bf16 v[48:51], v[164:167], v[186:189], v[48:51]
	v_mfma_f32_16x16x32_bf16 v[40:43], v[172:175], v[186:189], v[40:43]
	v_mfma_f32_16x16x32_bf16 v[32:35], v[164:167], v[194:197], v[32:35]
	v_mfma_f32_16x16x32_bf16 v[24:27], v[172:175], v[194:197], v[24:27]
	v_mfma_f32_16x16x32_bf16 v[16:19], v[164:167], v[202:205], v[16:19]
	v_mfma_f32_16x16x32_bf16 v[8:11], v[172:175], v[202:205], v[8:11]
	v_mfma_f32_16x16x32_bf16 v[4:7], v[164:167], v[210:213], v[4:7]
	v_mfma_f32_16x16x32_bf16 v[0:3], v[172:175], v[210:213], v[0:3]
	s_barrier
	s_add_i32 s28, 0, 0x18000
	s_add_i32 s38, 0, 0x1c000
	v_add_u32_e32 v156, s28, v142
	v_add_u32_e32 v172, s38, v142
	ds_read_b128 v[144:147], v156
	ds_read_b128 v[148:151], v156 offset:1024
	ds_read_b128 v[152:155], v156 offset:2048
	ds_read_b128 v[156:159], v156 offset:3072
	ds_read_b128 v[160:163], v172
	ds_read_b128 v[164:167], v172 offset:1024
	ds_read_b128 v[168:171], v172 offset:2048
	ds_read_b128 v[172:175], v172 offset:3072
	s_add_u32 s6, s6, 0x100000
	s_addc_u32 s7, s7, 0
	s_mov_b32 m0, s25
	v_lshl_add_u64 v[220:221], s[6:7], 0, v[132:133]
	ds_read_b128 v[182:185], v143 offset:32768
	ds_read_b128 v[186:189], v143 offset:33792
	ds_read_b128 v[190:193], v143 offset:34816
	ds_read_b128 v[194:197], v143 offset:35840
	ds_read_b128 v[198:201], v143 offset:36864
	ds_read_b128 v[202:205], v143 offset:37888
	ds_read_b128 v[206:209], v143 offset:38912
	ds_read_b128 v[210:213], v143 offset:39936
	global_load_lds_dwordx4 v[220:221], off
	v_lshl_add_u64 v[220:221], s[6:7], 0, v[130:131]
	s_mov_b32 m0, s30
	s_nop 0
	global_load_lds_dwordx4 v[220:221], off
	s_waitcnt vmcnt(8)
	s_waitcnt lgkmcnt(0)
	s_barrier
	s_waitcnt lgkmcnt(0)
	v_mfma_f32_16x16x32_bf16 v[124:127], v[144:147], v[182:185], v[124:127]
	v_mfma_f32_16x16x32_bf16 v[120:123], v[152:155], v[182:185], v[120:123]
	v_mfma_f32_16x16x32_bf16 v[116:119], v[144:147], v[190:193], v[116:119]
	v_mfma_f32_16x16x32_bf16 v[108:111], v[152:155], v[190:193], v[108:111]
	v_mfma_f32_16x16x32_bf16 v[100:103], v[144:147], v[198:201], v[100:103]
	v_mfma_f32_16x16x32_bf16 v[92:95], v[152:155], v[198:201], v[92:95]
	v_mfma_f32_16x16x32_bf16 v[84:87], v[144:147], v[206:209], v[84:87]
	v_mfma_f32_16x16x32_bf16 v[76:79], v[152:155], v[206:209], v[76:79]
	v_mfma_f32_16x16x32_bf16 v[124:127], v[148:151], v[186:189], v[124:127]
	v_mfma_f32_16x16x32_bf16 v[120:123], v[156:159], v[186:189], v[120:123]
	v_mfma_f32_16x16x32_bf16 v[116:119], v[148:151], v[194:197], v[116:119]
	v_mfma_f32_16x16x32_bf16 v[108:111], v[156:159], v[194:197], v[108:111]
	v_mfma_f32_16x16x32_bf16 v[100:103], v[148:151], v[202:205], v[100:103]
	v_mfma_f32_16x16x32_bf16 v[92:95], v[156:159], v[202:205], v[92:95]
	v_mfma_f32_16x16x32_bf16 v[84:87], v[148:151], v[210:213], v[84:87]
	v_mfma_f32_16x16x32_bf16 v[76:79], v[156:159], v[210:213], v[76:79]
	v_mfma_f32_16x16x32_bf16 v[112:115], v[160:163], v[182:185], v[112:115]
	v_mfma_f32_16x16x32_bf16 v[104:107], v[168:171], v[182:185], v[104:107]
	v_mfma_f32_16x16x32_bf16 v[96:99], v[160:163], v[190:193], v[96:99]
	v_mfma_f32_16x16x32_bf16 v[88:91], v[168:171], v[190:193], v[88:91]
	v_mfma_f32_16x16x32_bf16 v[80:83], v[160:163], v[198:201], v[80:83]
	v_mfma_f32_16x16x32_bf16 v[72:75], v[168:171], v[198:201], v[72:75]
	v_mfma_f32_16x16x32_bf16 v[68:71], v[160:163], v[206:209], v[68:71]
	v_mfma_f32_16x16x32_bf16 v[64:67], v[168:171], v[206:209], v[64:67]
	v_mfma_f32_16x16x32_bf16 v[112:115], v[164:167], v[186:189], v[112:115]
	v_mfma_f32_16x16x32_bf16 v[104:107], v[172:175], v[186:189], v[104:107]
	v_mfma_f32_16x16x32_bf16 v[96:99], v[164:167], v[194:197], v[96:99]
	v_mfma_f32_16x16x32_bf16 v[88:91], v[172:175], v[194:197], v[88:91]
	v_mfma_f32_16x16x32_bf16 v[80:83], v[164:167], v[202:205], v[80:83]
	v_mfma_f32_16x16x32_bf16 v[72:75], v[172:175], v[202:205], v[72:75]
	v_mfma_f32_16x16x32_bf16 v[68:71], v[164:167], v[210:213], v[68:71]
	v_mfma_f32_16x16x32_bf16 v[64:67], v[172:175], v[210:213], v[64:67]
	s_barrier
; #define PG8_STAGE(bufoff, gbase, voff) do { _Pragma("unroll") for (int _i = 0; _i < 2; ++_i) \
;         __builtin_amdgcn_global_load_lds((const unsigned*)((const char*)(gbase) + (voff)[_i]), (PG8_LAS unsigned*)(lds + (bufoff) + ldsw + _i * 8192), 16, 0, 0); } while (0)
; #define PG8_LDA(dst, b, h) do { _Pragma("unroll") for (int m = 0; m < 4; ++m) _Pragma("unroll") for (int k = 0; k < 2; ++k) dst[m][k] = *(const PG8_LAS bf16x8*)(lds + PG8_SA(b, h) + aoff + m * 2048 + k * 1024); } while (0)
; #define PG8_MMA(ai, bj, At, Bt) do { __builtin_amdgcn_s_setprio(1); _Pragma("unroll") for (int m = 0; m < 4; ++m) _Pragma("unroll") for (int n = 0; n < 2; ++n) _Pragma("unroll") for (int k = 0; k < 2; ++k) \
;         acc[ai][bj][m][n] = __builtin_amdgcn_mfma_f32_16x16x32_bf16(Bt[n][k], At[m][k], acc[ai][bj][m][n], 0, 0, 0); __builtin_amdgcn_s_setprio(0); } while (0)
; #define PG8_WAIT_V(n) asm volatile("s_waitcnt vmcnt(" #n ")" ::: "memory")
; #define PG8_WAIT_L(n) asm volatile("s_waitcnt lgkmcnt(" #n ")" ::: "memory")
; #define PG8_BAR __builtin_amdgcn_s_barrier()
; #define PG8_SCHED __builtin_amdgcn_sched_barrier(0)
; template <class Epi, class Sched, bool ALIGN_EPI = false, bool SP2 = false>
; __device__ __forceinline__ void gemm_phase(PG8_LAS unsigned char* lds, const Gemm g, const Sched& S, const Epi& E) {
;     ...
;             PG8_LDA(At, 1, 1); PG8_STAGE(PG8_SB(1, 0), b3, voffB); PG8_STAGE(PG8_SB(1, 1), b3 + hstep, voffB); PG8_STAGE(PG8_SA(1, 0), a3, voffA);
;             PG8_WAIT_V(8); PG8_WAIT_L(0); PG8_BAR; PG8_MMA(1, 0, At, B0); PG8_MMA(1, 1, At, B1); PG8_BAR; PG8_SCHED;
	s_add_i32 s6, s28, s22
	v_lshl_add_u64 v[138:139], v[138:139], 0, s[44:45]
	s_mov_b32 m0, s6
	ds_read_b128 v[182:185], v143 offset:49152
	ds_read_b128 v[186:189], v143 offset:50176
	ds_read_b128 v[190:193], v143 offset:51200
	ds_read_b128 v[194:197], v143 offset:52224
	ds_read_b128 v[198:201], v143 offset:53248
	ds_read_b128 v[202:205], v143 offset:54272
	ds_read_b128 v[206:209], v143 offset:55296
	ds_read_b128 v[210:213], v143 offset:56320
	global_load_lds_dwordx4 v[138:139], off
	s_add_i32 m0, s6, 0x2000
	s_add_u32 s4, s4, 0x100080
	v_lshl_add_u64 v[138:139], v[214:215], 0, s[44:45]
	s_addc_u32 s5, s5, 0
	s_add_i32 s6, s38, s22
	global_load_lds_dwordx4 v[138:139], off
	v_lshl_add_u64 v[138:139], s[4:5], 0, v[176:177]
	s_mov_b32 m0, s6
	s_nop 0
	global_load_lds_dwordx4 v[138:139], off
	v_lshl_add_u64 v[138:139], s[4:5], 0, v[128:129]
	s_add_i32 m0, s6, 0x2000
	s_nop 0
	global_load_lds_dwordx4 v[138:139], off
	v_lshl_add_u64 v[138:139], v[216:217], 0, s[44:45]
	s_mov_b32 m0, s63
	s_nop 0
	global_load_lds_dwordx4 v[138:139], off
	v_lshl_add_u64 v[138:139], v[218:219], 0, s[44:45]
	s_mov_b32 m0, s68
	s_nop 0
	global_load_lds_dwordx4 v[138:139], off
	s_waitcnt vmcnt(8)
	s_waitcnt lgkmcnt(0)
	s_barrier
	s_waitcnt lgkmcnt(0)
	v_mfma_f32_16x16x32_bf16 v[60:63], v[144:147], v[182:185], v[60:63]
	v_mfma_f32_16x16x32_bf16 v[56:59], v[152:155], v[182:185], v[56:59]
	v_mfma_f32_16x16x32_bf16 v[52:55], v[144:147], v[190:193], v[52:55]
	v_mfma_f32_16x16x32_bf16 v[44:47], v[152:155], v[190:193], v[44:47]
	v_mfma_f32_16x16x32_bf16 v[36:39], v[144:147], v[198:201], v[36:39]
	v_mfma_f32_16x16x32_bf16 v[28:31], v[152:155], v[198:201], v[28:31]
	v_mfma_f32_16x16x32_bf16 v[20:23], v[144:147], v[206:209], v[20:23]
	v_mfma_f32_16x16x32_bf16 v[12:15], v[152:155], v[206:209], v[12:15]
	v_mfma_f32_16x16x32_bf16 v[60:63], v[148:151], v[186:189], v[60:63]
	v_mfma_f32_16x16x32_bf16 v[56:59], v[156:159], v[186:189], v[56:59]
	v_mfma_f32_16x16x32_bf16 v[52:55], v[148:151], v[194:197], v[52:55]
	v_mfma_f32_16x16x32_bf16 v[44:47], v[156:159], v[194:197], v[44:47]
	v_mfma_f32_16x16x32_bf16 v[36:39], v[148:151], v[202:205], v[36:39]
	v_mfma_f32_16x16x32_bf16 v[28:31], v[156:159], v[202:205], v[28:31]
	v_mfma_f32_16x16x32_bf16 v[20:23], v[148:151], v[210:213], v[20:23]
	v_mfma_f32_16x16x32_bf16 v[12:15], v[156:159], v[210:213], v[12:15]
	v_mfma_f32_16x16x32_bf16 v[48:51], v[160:163], v[182:185], v[48:51]
	v_mfma_f32_16x16x32_bf16 v[40:43], v[168:171], v[182:185], v[40:43]
	v_mfma_f32_16x16x32_bf16 v[32:35], v[160:163], v[190:193], v[32:35]
	v_mfma_f32_16x16x32_bf16 v[24:27], v[168:171], v[190:193], v[24:27]
	v_mfma_f32_16x16x32_bf16 v[16:19], v[160:163], v[198:201], v[16:19]
	v_mfma_f32_16x16x32_bf16 v[8:11], v[168:171], v[198:201], v[8:11]
	v_mfma_f32_16x16x32_bf16 v[4:7], v[160:163], v[206:209], v[4:7]
	v_mfma_f32_16x16x32_bf16 v[0:3], v[168:171], v[206:209], v[0:3]
	v_mfma_f32_16x16x32_bf16 v[48:51], v[164:167], v[186:189], v[48:51]
	v_mfma_f32_16x16x32_bf16 v[40:43], v[172:175], v[186:189], v[40:43]
	s_add_i32 s74, s74, 2
	v_mfma_f32_16x16x32_bf16 v[32:35], v[164:167], v[194:197], v[32:35]
	s_add_u32 s64, s64, 0x100
	v_mfma_f32_16x16x32_bf16 v[24:27], v[172:175], v[194:197], v[24:27]
	s_addc_u32 s65, s65, 0
	v_mfma_f32_16x16x32_bf16 v[16:19], v[164:167], v[202:205], v[16:19]
	s_add_u32 s66, s66, 0x100
	v_mfma_f32_16x16x32_bf16 v[8:11], v[172:175], v[202:205], v[8:11]
	s_addc_u32 s67, s67, 0
	v_mfma_f32_16x16x32_bf16 v[4:7], v[164:167], v[210:213], v[4:7]
	s_cmp_gt_u32 s74, 61
	v_mfma_f32_16x16x32_bf16 v[0:3], v[172:175], v[210:213], v[0:3]
	s_barrier
	s_cbranch_scc0 .LBB0_790

; #define PG8_STAGE(bufoff, gbase, voff) do { _Pragma("unroll") for (int _i = 0; _i < 2; ++_i) \
;         __builtin_amdgcn_global_load_lds((const unsigned*)((const char*)(gbase) + (voff)[_i]), (PG8_LAS unsigned*)(lds + (bufoff) + ldsw + _i * 8192), 16, 0, 0); } while (0)
; #define PG8_LDA(dst, b, h) do { _Pragma("unroll") for (int m = 0; m < 4; ++m) _Pragma("unroll") for (int k = 0; k < 2; ++k) dst[m][k] = *(const PG8_LAS bf16x8*)(lds + PG8_SA(b, h) + aoff + m * 2048 + k * 1024); } while (0)
; #define PG8_LDB(dst, b, h) do { _Pragma("unroll") for (int n = 0; n < 2; ++n) _Pragma("unroll") for (int k = 0; k < 2; ++k) dst[n][k] = *(const PG8_LAS bf16x8*)(lds + PG8_SB(b, h) + boff + n * 2048 + k * 1024); } while (0)
; #define PG8_MMA(ai, bj, At, Bt) do { __builtin_amdgcn_s_setprio(1); _Pragma("unroll") for (int m = 0; m < 4; ++m) _Pragma("unroll") for (int n = 0; n < 2; ++n) _Pragma("unroll") for (int k = 0; k < 2; ++k) \
;         acc[ai][bj][m][n] = __builtin_amdgcn_mfma_f32_16x16x32_bf16(Bt[n][k], At[m][k], acc[ai][bj][m][n], 0, 0, 0); __builtin_amdgcn_s_setprio(0); } while (0)
; #define PG8_WAIT_V(n) asm volatile("s_waitcnt vmcnt(" #n ")" ::: "memory")
; #define PG8_WAIT_L(n) asm volatile("s_waitcnt lgkmcnt(" #n ")" ::: "memory")
; template <class Epi, class Sched, bool ALIGN_EPI = false, bool SP2 = false>
; __device__ __forceinline__ void gemm_phase(PG8_LAS unsigned char* lds, const Gemm g, const Sched& S, const Epi& E) {
;     ...
;             const bool last = (t == nt - 2);
;             const char* a1 = cA + (size_t)(t + 1) * kstep;
;             const char* a2 = last ? nA : cA + (size_t)(t + 2) * kstep; const char* b2 = last ? nB : cB + (size_t)(t + 2) * kstep;
;             const char* a3 = a2 + kstep; const char* b3 = b2 + kstep;
;             if (last && has_next) S.a_ready(nxt);
;             if constexpr (SP2) {
;             PG8_LDB(B0, 0, 0); PG8_LDB(B1, 0, 1); PG8_SCHED; PG8_LDA(At, 0, 0); PG8_STAGE(PG8_SA(1, 1), a1 + hstep, voffA);
;             PG8_WAIT_V(8); PG8_WAIT_L(0); PG8_BAR; PG8_MMA(0, 0, At, B0); PG8_MMA(0, 1, At, B1); PG8_BAR; PG8_SCHED;
;             PG8_LDA(At, 0, 1); PG8_STAGE(PG8_SB(0, 0), b2, voffB); PG8_STAGE(PG8_SB(0, 1), b2 + hstep, voffB); PG8_STAGE(PG8_SA(0, 0), a2, voffA);
;             PG8_WAIT_V(8); PG8_WAIT_L(0); PG8_BAR; PG8_MMA(1, 0, At, B0); PG8_MMA(1, 1, At, B1); PG8_BAR; PG8_SCHED;
.Lg4_peel:
	s_add_u32 s4, s64, 0xfff00080
	s_addc_u32 s5, s65, -1
	s_add_i32 s28, 0, 0x10000
	s_cmp_eq_u32 s74, 60
	s_cselect_b32 s7, s35, s5
	s_cselect_b32 s6, s72, s4
	v_add_u32_e32 v138, s28, v142
	s_cselect_b32 s5, s27, s67
	s_cselect_b32 s4, s73, s66
	s_add_i32 s48, 0, 0x14000
	ds_read_b128 v[144:147], v138
	ds_read_b128 v[148:151], v138 offset:1024
	ds_read_b128 v[152:155], v138 offset:2048
	ds_read_b128 v[156:159], v138 offset:3072
	v_add_u32_e32 v138, s48, v142
	ds_read_b128 v[160:163], v138
	ds_read_b128 v[164:167], v138 offset:1024
	ds_read_b128 v[168:171], v138 offset:2048
	ds_read_b128 v[172:175], v138 offset:3072
	v_lshl_add_u64 v[138:139], s[64:65], 0, v[134:135]
	s_add_i32 m0, s23, 0xc000
	ds_read_b128 v[182:185], v143
	ds_read_b128 v[186:189], v143 offset:1024
	ds_read_b128 v[190:193], v143 offset:2048
	ds_read_b128 v[194:197], v143 offset:3072
	ds_read_b128 v[198:201], v143 offset:4096
	ds_read_b128 v[202:205], v143 offset:5120
	ds_read_b128 v[206:209], v143 offset:6144
	ds_read_b128 v[210:213], v143 offset:7168
	global_load_lds_dwordx4 v[138:139], off
	v_lshl_add_u64 v[138:139], s[64:65], 0, v[136:137]
	s_add_i32 m0, s23, 0xe000
	s_nop 0
	global_load_lds_dwordx4 v[138:139], off
	s_waitcnt vmcnt(24)
	s_waitcnt lgkmcnt(0)
	s_barrier
	s_waitcnt lgkmcnt(0)
	v_mfma_f32_16x16x32_bf16 v[124:127], v[144:147], v[182:185], 0
	v_mfma_f32_16x16x32_bf16 v[120:123], v[152:155], v[182:185], 0
	v_mfma_f32_16x16x32_bf16 v[116:119], v[144:147], v[190:193], 0
	v_mfma_f32_16x16x32_bf16 v[108:111], v[152:155], v[190:193], 0
	v_mfma_f32_16x16x32_bf16 v[100:103], v[144:147], v[198:201], 0
	v_mfma_f32_16x16x32_bf16 v[92:95], v[152:155], v[198:201], 0
	v_mfma_f32_16x16x32_bf16 v[84:87], v[144:147], v[206:209], 0
	v_mfma_f32_16x16x32_bf16 v[76:79], v[152:155], v[206:209], 0
	v_mfma_f32_16x16x32_bf16 v[124:127], v[148:151], v[186:189], v[124:127]
	v_mfma_f32_16x16x32_bf16 v[120:123], v[156:159], v[186:189], v[120:123]
	v_mfma_f32_16x16x32_bf16 v[116:119], v[148:151], v[194:197], v[116:119]
	v_mfma_f32_16x16x32_bf16 v[108:111], v[156:159], v[194:197], v[108:111]
	v_mfma_f32_16x16x32_bf16 v[100:103], v[148:151], v[202:205], v[100:103]
	v_mfma_f32_16x16x32_bf16 v[92:95], v[156:159], v[202:205], v[92:95]
	v_mfma_f32_16x16x32_bf16 v[84:87], v[148:151], v[210:213], v[84:87]
	v_mfma_f32_16x16x32_bf16 v[76:79], v[156:159], v[210:213], v[76:79]
	v_mfma_f32_16x16x32_bf16 v[112:115], v[160:163], v[182:185], 0
	v_mfma_f32_16x16x32_bf16 v[104:107], v[168:171], v[182:185], 0
	v_mfma_f32_16x16x32_bf16 v[96:99], v[160:163], v[190:193], 0
	v_mfma_f32_16x16x32_bf16 v[88:91], v[168:171], v[190:193], 0
	v_mfma_f32_16x16x32_bf16 v[80:83], v[160:163], v[198:201], 0
	v_mfma_f32_16x16x32_bf16 v[72:75], v[168:171], v[198:201], 0
	v_mfma_f32_16x16x32_bf16 v[68:71], v[160:163], v[206:209], 0
	v_mfma_f32_16x16x32_bf16 v[64:67], v[168:171], v[206:209], 0
	v_mfma_f32_16x16x32_bf16 v[112:115], v[164:167], v[186:189], v[112:115]
	v_mfma_f32_16x16x32_bf16 v[104:107], v[172:175], v[186:189], v[104:107]
	v_mfma_f32_16x16x32_bf16 v[96:99], v[164:167], v[194:197], v[96:99]
	v_mfma_f32_16x16x32_bf16 v[88:91], v[172:175], v[194:197], v[88:91]
	v_mfma_f32_16x16x32_bf16 v[80:83], v[164:167], v[202:205], v[80:83]
	v_mfma_f32_16x16x32_bf16 v[72:75], v[172:175], v[202:205], v[72:75]
	v_mfma_f32_16x16x32_bf16 v[68:71], v[164:167], v[210:213], v[68:71]
	v_mfma_f32_16x16x32_bf16 v[64:67], v[172:175], v[210:213], v[64:67]
	s_barrier
	s_add_i32 s28, s28, s22
	v_lshl_add_u64 v[138:139], s[4:5], 0, v[176:177]
	s_mov_b32 m0, s28
	ds_read_b128 v[182:185], v143 offset:16384
	ds_read_b128 v[186:189], v143 offset:17408
	ds_read_b128 v[190:193], v143 offset:18432
	ds_read_b128 v[194:197], v143 offset:19456
	ds_read_b128 v[198:201], v143 offset:20480
	ds_read_b128 v[202:205], v143 offset:21504
	ds_read_b128 v[206:209], v143 offset:22528
	ds_read_b128 v[210:213], v143 offset:23552
	global_load_lds_dwordx4 v[138:139], off
	s_add_i32 m0, s28, 0x2000
	s_add_u32 s38, s4, 0x100000
	v_lshl_add_u64 v[214:215], s[4:5], 0, v[128:129]
	s_addc_u32 s39, s5, 0
	s_add_i32 s28, s48, s22
	global_load_lds_dwordx4 v[214:215], off
	v_lshl_add_u64 v[216:217], s[38:39], 0, v[176:177]
	s_mov_b32 m0, s28
	v_lshl_add_u64 v[218:219], s[6:7], 0, v[130:131]
	global_load_lds_dwordx4 v[216:217], off
	v_lshl_add_u64 v[216:217], s[38:39], 0, v[128:129]
	s_add_i32 m0, s28, 0x2000
	s_nop 0
	global_load_lds_dwordx4 v[216:217], off
	v_lshl_add_u64 v[216:217], s[6:7], 0, v[132:133]
	s_mov_b32 m0, s23
	s_nop 0
	global_load_lds_dwordx4 v[216:217], off
	s_mov_b32 m0, s24
	s_nop 0
	global_load_lds_dwordx4 v[218:219], off
	s_waitcnt vmcnt(24)
	s_waitcnt lgkmcnt(0)
	s_barrier
; #define PG8_STAGE(bufoff, gbase, voff) do { _Pragma("unroll") for (int _i = 0; _i < 2; ++_i) \
;         __builtin_amdgcn_global_load_lds((const unsigned*)((const char*)(gbase) + (voff)[_i]), (PG8_LAS unsigned*)(lds + (bufoff) + ldsw + _i * 8192), 16, 0, 0); } while (0)
; #define PG8_LDA(dst, b, h) do { _Pragma("unroll") for (int m = 0; m < 4; ++m) _Pragma("unroll") for (int k = 0; k < 2; ++k) dst[m][k] = *(const PG8_LAS bf16x8*)(lds + PG8_SA(b, h) + aoff + m * 2048 + k * 1024); } while (0)
; #define PG8_LDB(dst, b, h) do { _Pragma("unroll") for (int n = 0; n < 2; ++n) _Pragma("unroll") for (int k = 0; k < 2; ++k) dst[n][k] = *(const PG8_LAS bf16x8*)(lds + PG8_SB(b, h) + boff + n * 2048 + k * 1024); } while (0)
; #define PG8_MMA(ai, bj, At, Bt) do { __builtin_amdgcn_s_setprio(1); _Pragma("unroll") for (int m = 0; m < 4; ++m) _Pragma("unroll") for (int n = 0; n < 2; ++n) _Pragma("unroll") for (int k = 0; k < 2; ++k) \
;         acc[ai][bj][m][n] = __builtin_amdgcn_mfma_f32_16x16x32_bf16(Bt[n][k], At[m][k], acc[ai][bj][m][n], 0, 0, 0); __builtin_amdgcn_s_setprio(0); } while (0)
; #define PG8_WAIT_V(n) asm volatile("s_waitcnt vmcnt(" #n ")" ::: "memory")
; #define PG8_WAIT_L(n) asm volatile("s_waitcnt lgkmcnt(" #n ")" ::: "memory")
; #define PG8_BAR __builtin_amdgcn_s_barrier()
; #define PG8_SCHED __builtin_amdgcn_sched_barrier(0)
; template <class Epi, class Sched, bool ALIGN_EPI = false, bool SP2 = false>
; __device__ __forceinline__ void gemm_phase(PG8_LAS unsigned char* lds, const Gemm g, const Sched& S, const Epi& E) {
;     ...
;             PG8_WAIT_V(8); PG8_WAIT_L(0); PG8_BAR; PG8_MMA(1, 0, At, B0); PG8_MMA(1, 1, At, B1); PG8_BAR; PG8_SCHED;
;             PG8_LDB(B0, 1, 0); PG8_LDB(B1, 1, 1); PG8_SCHED; PG8_LDA(At, 1, 0); PG8_STAGE(PG8_SA(0, 1), a2 + hstep, voffA);
;             PG8_WAIT_V(8); PG8_WAIT_L(0); PG8_BAR; PG8_MMA(0, 0, At, B0); PG8_MMA(0, 1, At, B1); PG8_BAR; PG8_SCHED;
	s_waitcnt lgkmcnt(0)
	v_mfma_f32_16x16x32_bf16 v[60:63], v[144:147], v[182:185], 0
	v_mfma_f32_16x16x32_bf16 v[56:59], v[152:155], v[182:185], 0
	v_mfma_f32_16x16x32_bf16 v[52:55], v[144:147], v[190:193], 0
	v_mfma_f32_16x16x32_bf16 v[44:47], v[152:155], v[190:193], 0
	v_mfma_f32_16x16x32_bf16 v[36:39], v[144:147], v[198:201], 0
	v_mfma_f32_16x16x32_bf16 v[28:31], v[152:155], v[198:201], 0
	v_mfma_f32_16x16x32_bf16 v[20:23], v[144:147], v[206:209], 0
	v_mfma_f32_16x16x32_bf16 v[12:15], v[152:155], v[206:209], 0
	v_mfma_f32_16x16x32_bf16 v[60:63], v[148:151], v[186:189], v[60:63]
	v_mfma_f32_16x16x32_bf16 v[56:59], v[156:159], v[186:189], v[56:59]
	v_mfma_f32_16x16x32_bf16 v[52:55], v[148:151], v[194:197], v[52:55]
	v_mfma_f32_16x16x32_bf16 v[44:47], v[156:159], v[194:197], v[44:47]
	v_mfma_f32_16x16x32_bf16 v[36:39], v[148:151], v[202:205], v[36:39]
	v_mfma_f32_16x16x32_bf16 v[28:31], v[156:159], v[202:205], v[28:31]
	v_mfma_f32_16x16x32_bf16 v[20:23], v[148:151], v[210:213], v[20:23]
	v_mfma_f32_16x16x32_bf16 v[12:15], v[156:159], v[210:213], v[12:15]
	v_mfma_f32_16x16x32_bf16 v[48:51], v[160:163], v[182:185], 0
	v_mfma_f32_16x16x32_bf16 v[40:43], v[168:171], v[182:185], 0
	v_mfma_f32_16x16x32_bf16 v[32:35], v[160:163], v[190:193], 0
	v_mfma_f32_16x16x32_bf16 v[24:27], v[168:171], v[190:193], 0
	v_mfma_f32_16x16x32_bf16 v[16:19], v[160:163], v[198:201], 0
	v_mfma_f32_16x16x32_bf16 v[8:11], v[168:171], v[198:201], 0
	v_mfma_f32_16x16x32_bf16 v[4:7], v[160:163], v[206:209], 0
	v_mfma_f32_16x16x32_bf16 v[0:3], v[168:171], v[206:209], 0
	v_mfma_f32_16x16x32_bf16 v[48:51], v[164:167], v[186:189], v[48:51]
	v_mfma_f32_16x16x32_bf16 v[40:43], v[172:175], v[186:189], v[40:43]
	v_mfma_f32_16x16x32_bf16 v[32:35], v[164:167], v[194:197], v[32:35]
	v_mfma_f32_16x16x32_bf16 v[24:27], v[172:175], v[194:197], v[24:27]
	v_mfma_f32_16x16x32_bf16 v[16:19], v[164:167], v[202:205], v[16:19]
	v_mfma_f32_16x16x32_bf16 v[8:11], v[172:175], v[202:205], v[8:11]
	v_mfma_f32_16x16x32_bf16 v[4:7], v[164:167], v[210:213], v[4:7]
	v_mfma_f32_16x16x32_bf16 v[0:3], v[172:175], v[210:213], v[0:3]
	s_barrier
	s_add_i32 s28, 0, 0x18000
	s_add_i32 s38, 0, 0x1c000
	v_add_u32_e32 v156, s28, v142
	v_add_u32_e32 v172, s38, v142
	ds_read_b128 v[144:147], v156
	ds_read_b128 v[148:151], v156 offset:1024
	ds_read_b128 v[152:155], v156 offset:2048
	ds_read_b128 v[156:159], v156 offset:3072
	ds_read_b128 v[160:163], v172
	ds_read_b128 v[164:167], v172 offset:1024
	ds_read_b128 v[168:171], v172 offset:2048
	ds_read_b128 v[172:175], v172 offset:3072
	s_add_u32 s6, s6, 0x100000
	s_addc_u32 s7, s7, 0
	s_mov_b32 m0, s25
	v_lshl_add_u64 v[220:221], s[6:7], 0, v[132:133]
	ds_read_b128 v[182:185], v143 offset:32768
	ds_read_b128 v[186:189], v143 offset:33792
	ds_read_b128 v[190:193], v143 offset:34816
	ds_read_b128 v[194:197], v143 offset:35840
	ds_read_b128 v[198:201], v143 offset:36864
	ds_read_b128 v[202:205], v143 offset:37888
	ds_read_b128 v[206:209], v143 offset:38912
	ds_read_b128 v[210:213], v143 offset:39936
	global_load_lds_dwordx4 v[220:221], off
	v_lshl_add_u64 v[220:221], s[6:7], 0, v[130:131]
	s_mov_b32 m0, s30
	s_nop 0
	global_load_lds_dwordx4 v[220:221], off
	s_waitcnt vmcnt(8)
	s_waitcnt lgkmcnt(0)
	s_barrier
	s_waitcnt lgkmcnt(0)
	v_mfma_f32_16x16x32_bf16 v[124:127], v[144:147], v[182:185], v[124:127]
	v_mfma_f32_16x16x32_bf16 v[120:123], v[152:155], v[182:185], v[120:123]
	v_mfma_f32_16x16x32_bf16 v[116:119], v[144:147], v[190:193], v[116:119]
	v_mfma_f32_16x16x32_bf16 v[108:111], v[152:155], v[190:193], v[108:111]
	v_mfma_f32_16x16x32_bf16 v[100:103], v[144:147], v[198:201], v[100:103]
	v_mfma_f32_16x16x32_bf16 v[92:95], v[152:155], v[198:201], v[92:95]
	v_mfma_f32_16x16x32_bf16 v[84:87], v[144:147], v[206:209], v[84:87]
	v_mfma_f32_16x16x32_bf16 v[76:79], v[152:155], v[206:209], v[76:79]
	v_mfma_f32_16x16x32_bf16 v[124:127], v[148:151], v[186:189], v[124:127]
	v_mfma_f32_16x16x32_bf16 v[120:123], v[156:159], v[186:189], v[120:123]
	v_mfma_f32_16x16x32_bf16 v[116:119], v[148:151], v[194:197], v[116:119]
	v_mfma_f32_16x16x32_bf16 v[108:111], v[156:159], v[194:197], v[108:111]
	v_mfma_f32_16x16x32_bf16 v[100:103], v[148:151], v[202:205], v[100:103]
	v_mfma_f32_16x16x32_bf16 v[92:95], v[156:159], v[202:205], v[92:95]
	v_mfma_f32_16x16x32_bf16 v[84:87], v[148:151], v[210:213], v[84:87]
	v_mfma_f32_16x16x32_bf16 v[76:79], v[156:159], v[210:213], v[76:79]
	v_mfma_f32_16x16x32_bf16 v[112:115], v[160:163], v[182:185], v[112:115]
	v_mfma_f32_16x16x32_bf16 v[104:107], v[168:171], v[182:185], v[104:107]
	v_mfma_f32_16x16x32_bf16 v[96:99], v[160:163], v[190:193], v[96:99]
	v_mfma_f32_16x16x32_bf16 v[88:91], v[168:171], v[190:193], v[88:91]
	v_mfma_f32_16x16x32_bf16 v[80:83], v[160:163], v[198:201], v[80:83]
	v_mfma_f32_16x16x32_bf16 v[72:75], v[168:171], v[198:201], v[72:75]
	v_mfma_f32_16x16x32_bf16 v[68:71], v[160:163], v[206:209], v[68:71]
	v_mfma_f32_16x16x32_bf16 v[64:67], v[168:171], v[206:209], v[64:67]
	v_mfma_f32_16x16x32_bf16 v[112:115], v[164:167], v[186:189], v[112:115]
	v_mfma_f32_16x16x32_bf16 v[104:107], v[172:175], v[186:189], v[104:107]
	v_mfma_f32_16x16x32_bf16 v[96:99], v[164:167], v[194:197], v[96:99]
	v_mfma_f32_16x16x32_bf16 v[88:91], v[172:175], v[194:197], v[88:91]
	v_mfma_f32_16x16x32_bf16 v[80:83], v[164:167], v[202:205], v[80:83]
	v_mfma_f32_16x16x32_bf16 v[72:75], v[172:175], v[202:205], v[72:75]
	v_mfma_f32_16x16x32_bf16 v[68:71], v[164:167], v[210:213], v[68:71]
	v_mfma_f32_16x16x32_bf16 v[64:67], v[172:175], v[210:213], v[64:67]
	s_barrier
; #define PG8_STAGE(bufoff, gbase, voff) do { _Pragma("unroll") for (int _i = 0; _i < 2; ++_i) \
;         __builtin_amdgcn_global_load_lds((const unsigned*)((const char*)(gbase) + (voff)[_i]), (PG8_LAS unsigned*)(lds + (bufoff) + ldsw + _i * 8192), 16, 0, 0); } while (0)
; #define PG8_LDA(dst, b, h) do { _Pragma("unroll") for (int m = 0; m < 4; ++m) _Pragma("unroll") for (int k = 0; k < 2; ++k) dst[m][k] = *(const PG8_LAS bf16x8*)(lds + PG8_SA(b, h) + aoff + m * 2048 + k * 1024); } while (0)
; #define PG8_MMA(ai, bj, At, Bt) do { __builtin_amdgcn_s_setprio(1); _Pragma("unroll") for (int m = 0; m < 4; ++m) _Pragma("unroll") for (int n = 0; n < 2; ++n) _Pragma("unroll") for (int k = 0; k < 2; ++k) \
;         acc[ai][bj][m][n] = __builtin_amdgcn_mfma_f32_16x16x32_bf16(Bt[n][k], At[m][k], acc[ai][bj][m][n], 0, 0, 0); __builtin_amdgcn_s_setprio(0); } while (0)
; #define PG8_WAIT_V(n) asm volatile("s_waitcnt vmcnt(" #n ")" ::: "memory")
; #define PG8_WAIT_L(n) asm volatile("s_waitcnt lgkmcnt(" #n ")" ::: "memory")
; #define PG8_BAR __builtin_amdgcn_s_barrier()
; #define PG8_SCHED __builtin_amdgcn_sched_barrier(0)
; template <class Epi, class Sched, bool ALIGN_EPI = false, bool SP2 = false>
; __device__ __forceinline__ void gemm_phase(PG8_LAS unsigned char* lds, const Gemm g, const Sched& S, const Epi& E) {
;     ...
;             PG8_LDA(At, 1, 1); PG8_STAGE(PG8_SB(1, 0), b3, voffB); PG8_STAGE(PG8_SB(1, 1), b3 + hstep, voffB); PG8_STAGE(PG8_SA(1, 0), a3, voffA);
;             PG8_WAIT_V(8); PG8_WAIT_L(0); PG8_BAR; PG8_MMA(1, 0, At, B0); PG8_MMA(1, 1, At, B1); PG8_BAR; PG8_SCHED;
	s_add_i32 s6, s28, s22
	v_lshl_add_u64 v[138:139], v[138:139], 0, s[44:45]
	s_mov_b32 m0, s6
	ds_read_b128 v[182:185], v143 offset:49152
	ds_read_b128 v[186:189], v143 offset:50176
	ds_read_b128 v[190:193], v143 offset:51200
	ds_read_b128 v[194:197], v143 offset:52224
	ds_read_b128 v[198:201], v143 offset:53248
	ds_read_b128 v[202:205], v143 offset:54272
	ds_read_b128 v[206:209], v143 offset:55296
	ds_read_b128 v[210:213], v143 offset:56320
	global_load_lds_dwordx4 v[138:139], off
	s_add_i32 m0, s6, 0x2000
	s_add_u32 s4, s4, 0x100080
	v_lshl_add_u64 v[138:139], v[214:215], 0, s[44:45]
	s_addc_u32 s5, s5, 0
	s_add_i32 s6, s38, s22
	global_load_lds_dwordx4 v[138:139], off
	v_lshl_add_u64 v[138:139], s[4:5], 0, v[176:177]
	s_mov_b32 m0, s6
	s_nop 0
	global_load_lds_dwordx4 v[138:139], off
	v_lshl_add_u64 v[138:139], s[4:5], 0, v[128:129]
	s_add_i32 m0, s6, 0x2000
	s_nop 0
	global_load_lds_dwordx4 v[138:139], off
	v_lshl_add_u64 v[138:139], v[216:217], 0, s[44:45]
	s_mov_b32 m0, s63
	s_nop 0
	global_load_lds_dwordx4 v[138:139], off
	v_lshl_add_u64 v[138:139], v[218:219], 0, s[44:45]
	s_mov_b32 m0, s68
	s_nop 0
	global_load_lds_dwordx4 v[138:139], off
	s_waitcnt vmcnt(8)
	s_waitcnt lgkmcnt(0)
	s_barrier
	s_waitcnt lgkmcnt(0)
	v_mfma_f32_16x16x32_bf16 v[60:63], v[144:147], v[182:185], v[60:63]
	v_mfma_f32_16x16x32_bf16 v[56:59], v[152:155], v[182:185], v[56:59]
	v_mfma_f32_16x16x32_bf16 v[52:55], v[144:147], v[190:193], v[52:55]
	v_mfma_f32_16x16x32_bf16 v[44:47], v[152:155], v[190:193], v[44:47]
	v_mfma_f32_16x16x32_bf16 v[36:39], v[144:147], v[198:201], v[36:39]
	v_mfma_f32_16x16x32_bf16 v[28:31], v[152:155], v[198:201], v[28:31]
	v_mfma_f32_16x16x32_bf16 v[20:23], v[144:147], v[206:209], v[20:23]
	v_mfma_f32_16x16x32_bf16 v[12:15], v[152:155], v[206:209], v[12:15]
	v_mfma_f32_16x16x32_bf16 v[60:63], v[148:151], v[186:189], v[60:63]
	v_mfma_f32_16x16x32_bf16 v[56:59], v[156:159], v[186:189], v[56:59]
	v_mfma_f32_16x16x32_bf16 v[52:55], v[148:151], v[194:197], v[52:55]
	v_mfma_f32_16x16x32_bf16 v[44:47], v[156:159], v[194:197], v[44:47]
	v_mfma_f32_16x16x32_bf16 v[36:39], v[148:151], v[202:205], v[36:39]
	v_mfma_f32_16x16x32_bf16 v[28:31], v[156:159], v[202:205], v[28:31]
	v_mfma_f32_16x16x32_bf16 v[20:23], v[148:151], v[210:213], v[20:23]
	v_mfma_f32_16x16x32_bf16 v[12:15], v[156:159], v[210:213], v[12:15]
	v_mfma_f32_16x16x32_bf16 v[48:51], v[160:163], v[182:185], v[48:51]
	v_mfma_f32_16x16x32_bf16 v[40:43], v[168:171], v[182:185], v[40:43]
	v_mfma_f32_16x16x32_bf16 v[32:35], v[160:163], v[190:193], v[32:35]
	v_mfma_f32_16x16x32_bf16 v[24:27], v[168:171], v[190:193], v[24:27]
	v_mfma_f32_16x16x32_bf16 v[16:19], v[160:163], v[198:201], v[16:19]
	v_mfma_f32_16x16x32_bf16 v[8:11], v[168:171], v[198:201], v[8:11]
	v_mfma_f32_16x16x32_bf16 v[4:7], v[160:163], v[206:209], v[4:7]
	v_mfma_f32_16x16x32_bf16 v[0:3], v[168:171], v[206:209], v[0:3]
	v_mfma_f32_16x16x32_bf16 v[48:51], v[164:167], v[186:189], v[48:51]
	v_mfma_f32_16x16x32_bf16 v[40:43], v[172:175], v[186:189], v[40:43]
	s_add_i32 s74, s74, 2
	v_mfma_f32_16x16x32_bf16 v[32:35], v[164:167], v[194:197], v[32:35]
	s_add_u32 s64, s64, 0x100
	v_mfma_f32_16x16x32_bf16 v[24:27], v[172:175], v[194:197], v[24:27]
	s_addc_u32 s65, s65, 0
	v_mfma_f32_16x16x32_bf16 v[16:19], v[164:167], v[202:205], v[16:19]
	s_add_u32 s66, s66, 0x100
	v_mfma_f32_16x16x32_bf16 v[8:11], v[172:175], v[202:205], v[8:11]
	s_addc_u32 s67, s67, 0
	v_mfma_f32_16x16x32_bf16 v[4:7], v[164:167], v[210:213], v[4:7]
	s_cmp_gt_u32 s74, 61
	v_mfma_f32_16x16x32_bf16 v[0:3], v[172:175], v[210:213], v[0:3]
	s_barrier
	s_cbranch_scc0 .LBB0_790
	s_branch .Lg4_post

; #define PG8_STAGE(bufoff, gbase, voff) do { _Pragma("unroll") for (int _i = 0; _i < 2; ++_i) \
;         __builtin_amdgcn_global_load_lds((const unsigned*)((const char*)(gbase) + (voff)[_i]), (PG8_LAS unsigned*)(lds + (bufoff) + ldsw + _i * 8192), 16, 0, 0); } while (0)
; #define PG8_LDA(dst, b, h) do { _Pragma("unroll") for (int m = 0; m < 4; ++m) _Pragma("unroll") for (int k = 0; k < 2; ++k) dst[m][k] = *(const PG8_LAS bf16x8*)(lds + PG8_SA(b, h) + aoff + m * 2048 + k * 1024); } while (0)
; #define PG8_LDB(dst, b, h) do { _Pragma("unroll") for (int n = 0; n < 2; ++n) _Pragma("unroll") for (int k = 0; k < 2; ++k) dst[n][k] = *(const PG8_LAS bf16x8*)(lds + PG8_SB(b, h) + boff + n * 2048 + k * 1024); } while (0)
; #define PG8_MMA(ai, bj, At, Bt) do { __builtin_amdgcn_s_setprio(1); _Pragma("unroll") for (int m = 0; m < 4; ++m) _Pragma("unroll") for (int n = 0; n < 2; ++n) _Pragma("unroll") for (int k = 0; k < 2; ++k) \
;         acc[ai][bj][m][n] = __builtin_amdgcn_mfma_f32_16x16x32_bf16(Bt[n][k], At[m][k], acc[ai][bj][m][n], 0, 0, 0); __builtin_amdgcn_s_setprio(0); } while (0)
; #define PG8_WAIT_V(n) asm volatile("s_waitcnt vmcnt(" #n ")" ::: "memory")
; #define PG8_WAIT_L(n) asm volatile("s_waitcnt lgkmcnt(" #n ")" ::: "memory")
; template <class Epi, class Sched, bool ALIGN_EPI = false, bool SP2 = false>
; __device__ __forceinline__ void gemm_phase(PG8_LAS unsigned char* lds, const Gemm g, const Sched& S, const Epi& E) {
;     ...
;             const bool last = (t == nt - 2);
;             const char* a1 = cA + (size_t)(t + 1) * kstep;
;             const char* a2 = last ? nA : cA + (size_t)(t + 2) * kstep; const char* b2 = last ? nB : cB + (size_t)(t + 2) * kstep;
;             const char* a3 = a2 + kstep; const char* b3 = b2 + kstep;
;             if (last && has_next) S.a_ready(nxt);
;             if constexpr (SP2) {
;             PG8_LDB(B0, 0, 0); PG8_LDB(B1, 0, 1); PG8_SCHED; PG8_LDA(At, 0, 0); PG8_STAGE(PG8_SA(1, 1), a1 + hstep, voffA);
;             PG8_WAIT_V(8); PG8_WAIT_L(0); PG8_BAR; PG8_MMA(0, 0, At, B0); PG8_MMA(0, 1, At, B1); PG8_BAR; PG8_SCHED;
;             PG8_LDA(At, 0, 1); PG8_STAGE(PG8_SB(0, 0), b2, voffB); PG8_STAGE(PG8_SB(0, 1), b2 + hstep, voffB); PG8_STAGE(PG8_SA(0, 0), a2, voffA);
;             PG8_WAIT_V(8); PG8_WAIT_L(0); PG8_BAR; PG8_MMA(1, 0, At, B0); PG8_MMA(1, 1, At, B1); PG8_BAR; PG8_SCHED;
.LBB0_812:
	s_add_i32 s83, s4, 2
	s_add_u32 s28, s64, 0x80
	s_addc_u32 s5, s65, 0
	s_add_i32 s48, 0, 0x10000
	s_cmp_eq_u32 s72, s4
	s_cselect_b32 s5, s37, s5
	s_cselect_b32 s4, s36, s28
	s_cselect_b32 s39, s41, s67
	s_cselect_b32 s38, s40, s66
	s_add_i32 s28, 0, 0x14000
	v_add_u32_e32 v154, s48, v140
	v_add_u32_e32 v170, s28, v140
	ds_read_b128 v[142:145], v154
	ds_read_b128 v[146:149], v154 offset:1024
	ds_read_b128 v[150:153], v154 offset:2048
	ds_read_b128 v[154:157], v154 offset:3072
	ds_read_b128 v[158:161], v170
	ds_read_b128 v[162:165], v170 offset:1024
	ds_read_b128 v[166:169], v170 offset:2048
	ds_read_b128 v[170:173], v170 offset:3072
	v_lshl_add_u64 v[174:175], s[64:65], 0, v[134:135]
	s_add_i32 m0, s25, 0xc000
	ds_read_b128 v[182:185], v141
	ds_read_b128 v[186:189], v141 offset:1024
	ds_read_b128 v[190:193], v141 offset:2048
	ds_read_b128 v[194:197], v141 offset:3072
	ds_read_b128 v[198:201], v141 offset:4096
	ds_read_b128 v[202:205], v141 offset:5120
	ds_read_b128 v[206:209], v141 offset:6144
	ds_read_b128 v[210:213], v141 offset:7168
	global_load_lds_dwordx4 v[174:175], off
	v_lshl_add_u64 v[174:175], s[64:65], 0, v[136:137]
	s_add_i32 m0, s25, 0xe000
	s_nop 0
	global_load_lds_dwordx4 v[174:175], off
	s_waitcnt vmcnt(8)
	s_waitcnt lgkmcnt(0)
	s_barrier
	s_waitcnt lgkmcnt(0)
	v_mfma_f32_16x16x32_bf16 v[124:127], v[142:145], v[182:185], v[124:127]
	v_mfma_f32_16x16x32_bf16 v[120:123], v[150:153], v[182:185], v[120:123]
	v_mfma_f32_16x16x32_bf16 v[108:111], v[142:145], v[190:193], v[108:111]
	v_mfma_f32_16x16x32_bf16 v[104:107], v[150:153], v[190:193], v[104:107]
	v_mfma_f32_16x16x32_bf16 v[92:95], v[142:145], v[198:201], v[92:95]
	v_mfma_f32_16x16x32_bf16 v[88:91], v[150:153], v[198:201], v[88:91]
	v_mfma_f32_16x16x32_bf16 v[76:79], v[142:145], v[206:209], v[76:79]
	v_mfma_f32_16x16x32_bf16 v[72:75], v[150:153], v[206:209], v[72:75]
	v_mfma_f32_16x16x32_bf16 v[124:127], v[146:149], v[186:189], v[124:127]
	v_mfma_f32_16x16x32_bf16 v[120:123], v[154:157], v[186:189], v[120:123]
	v_mfma_f32_16x16x32_bf16 v[108:111], v[146:149], v[194:197], v[108:111]
	v_mfma_f32_16x16x32_bf16 v[104:107], v[154:157], v[194:197], v[104:107]
	v_mfma_f32_16x16x32_bf16 v[92:95], v[146:149], v[202:205], v[92:95]
	v_mfma_f32_16x16x32_bf16 v[88:91], v[154:157], v[202:205], v[88:91]
	v_mfma_f32_16x16x32_bf16 v[76:79], v[146:149], v[210:213], v[76:79]
	v_mfma_f32_16x16x32_bf16 v[72:75], v[154:157], v[210:213], v[72:75]
	v_mfma_f32_16x16x32_bf16 v[116:119], v[158:161], v[182:185], v[116:119]
	v_mfma_f32_16x16x32_bf16 v[112:115], v[166:169], v[182:185], v[112:115]
	v_mfma_f32_16x16x32_bf16 v[100:103], v[158:161], v[190:193], v[100:103]
	v_mfma_f32_16x16x32_bf16 v[96:99], v[166:169], v[190:193], v[96:99]
	v_mfma_f32_16x16x32_bf16 v[84:87], v[158:161], v[198:201], v[84:87]
	v_mfma_f32_16x16x32_bf16 v[80:83], v[166:169], v[198:201], v[80:83]
	v_mfma_f32_16x16x32_bf16 v[68:71], v[158:161], v[206:209], v[68:71]
	v_mfma_f32_16x16x32_bf16 v[64:67], v[166:169], v[206:209], v[64:67]
	v_mfma_f32_16x16x32_bf16 v[116:119], v[162:165], v[186:189], v[116:119]
	v_mfma_f32_16x16x32_bf16 v[112:115], v[170:173], v[186:189], v[112:115]
	v_mfma_f32_16x16x32_bf16 v[100:103], v[162:165], v[194:197], v[100:103]
	v_mfma_f32_16x16x32_bf16 v[96:99], v[170:173], v[194:197], v[96:99]
	v_mfma_f32_16x16x32_bf16 v[84:87], v[162:165], v[202:205], v[84:87]
	v_mfma_f32_16x16x32_bf16 v[80:83], v[170:173], v[202:205], v[80:83]
	v_mfma_f32_16x16x32_bf16 v[68:71], v[162:165], v[210:213], v[68:71]
	v_mfma_f32_16x16x32_bf16 v[64:67], v[170:173], v[210:213], v[64:67]
	s_barrier
	s_add_i32 s48, s48, s24
	v_lshl_add_u64 v[174:175], s[38:39], 0, v[176:177]
	s_mov_b32 m0, s48
	ds_read_b128 v[182:185], v141 offset:16384
	ds_read_b128 v[186:189], v141 offset:17408
	ds_read_b128 v[190:193], v141 offset:18432
	ds_read_b128 v[194:197], v141 offset:19456
	ds_read_b128 v[198:201], v141 offset:20480
	ds_read_b128 v[202:205], v141 offset:21504
	ds_read_b128 v[206:209], v141 offset:22528
	ds_read_b128 v[210:213], v141 offset:23552
	global_load_lds_dwordx4 v[174:175], off
	s_add_i32 m0, s48, 0x2000
	v_lshl_add_u64 v[214:215], s[38:39], 0, v[128:129]
	s_add_u32 s38, s38, s0
	s_addc_u32 s39, s39, s1
	s_add_i32 s28, s28, s24
	global_load_lds_dwordx4 v[214:215], off
	v_lshl_add_u64 v[216:217], s[38:39], 0, v[176:177]
	s_mov_b32 m0, s28
	v_lshl_add_u64 v[218:219], s[38:39], 0, v[128:129]
	global_load_lds_dwordx4 v[216:217], off
	s_add_i32 m0, s28, 0x2000
	v_lshl_add_u64 v[220:221], s[4:5], 0, v[132:133]
	global_load_lds_dwordx4 v[218:219], off
	s_mov_b32 m0, s25
	v_lshl_add_u64 v[222:223], s[4:5], 0, v[130:131]
	global_load_lds_dwordx4 v[220:221], off
	s_mov_b32 m0, s30
	s_nop 0
	global_load_lds_dwordx4 v[222:223], off
	s_waitcnt vmcnt(8)
	s_waitcnt lgkmcnt(0)
	s_barrier
; #define PG8_STAGE(bufoff, gbase, voff) do { _Pragma("unroll") for (int _i = 0; _i < 2; ++_i) \
;         __builtin_amdgcn_global_load_lds((const unsigned*)((const char*)(gbase) + (voff)[_i]), (PG8_LAS unsigned*)(lds + (bufoff) + ldsw + _i * 8192), 16, 0, 0); } while (0)
; #define PG8_LDA(dst, b, h) do { _Pragma("unroll") for (int m = 0; m < 4; ++m) _Pragma("unroll") for (int k = 0; k < 2; ++k) dst[m][k] = *(const PG8_LAS bf16x8*)(lds + PG8_SA(b, h) + aoff + m * 2048 + k * 1024); } while (0)
; #define PG8_LDB(dst, b, h) do { _Pragma("unroll") for (int n = 0; n < 2; ++n) _Pragma("unroll") for (int k = 0; k < 2; ++k) dst[n][k] = *(const PG8_LAS bf16x8*)(lds + PG8_SB(b, h) + boff + n * 2048 + k * 1024); } while (0)
; #define PG8_MMA(ai, bj, At, Bt) do { __builtin_amdgcn_s_setprio(1); _Pragma("unroll") for (int m = 0; m < 4; ++m) _Pragma("unroll") for (int n = 0; n < 2; ++n) _Pragma("unroll") for (int k = 0; k < 2; ++k) \
;         acc[ai][bj][m][n] = __builtin_amdgcn_mfma_f32_16x16x32_bf16(Bt[n][k], At[m][k], acc[ai][bj][m][n], 0, 0, 0); __builtin_amdgcn_s_setprio(0); } while (0)
; #define PG8_WAIT_V(n) asm volatile("s_waitcnt vmcnt(" #n ")" ::: "memory")
; #define PG8_WAIT_L(n) asm volatile("s_waitcnt lgkmcnt(" #n ")" ::: "memory")
; #define PG8_BAR __builtin_amdgcn_s_barrier()
; #define PG8_SCHED __builtin_amdgcn_sched_barrier(0)
; template <class Epi, class Sched, bool ALIGN_EPI = false, bool SP2 = false>
; __device__ __forceinline__ void gemm_phase(PG8_LAS unsigned char* lds, const Gemm g, const Sched& S, const Epi& E) {
;     ...
;             PG8_WAIT_V(8); PG8_WAIT_L(0); PG8_BAR; PG8_MMA(1, 0, At, B0); PG8_MMA(1, 1, At, B1); PG8_BAR; PG8_SCHED;
;             PG8_LDB(B0, 1, 0); PG8_LDB(B1, 1, 1); PG8_SCHED; PG8_LDA(At, 1, 0); PG8_STAGE(PG8_SA(0, 1), a2 + hstep, voffA);
;             PG8_WAIT_V(8); PG8_WAIT_L(0); PG8_BAR; PG8_MMA(0, 0, At, B0); PG8_MMA(0, 1, At, B1); PG8_BAR; PG8_SCHED;
	s_waitcnt lgkmcnt(0)
	v_mfma_f32_16x16x32_bf16 v[60:63], v[142:145], v[182:185], v[60:63]
	v_mfma_f32_16x16x32_bf16 v[56:59], v[150:153], v[182:185], v[56:59]
	v_mfma_f32_16x16x32_bf16 v[44:47], v[142:145], v[190:193], v[44:47]
	v_mfma_f32_16x16x32_bf16 v[40:43], v[150:153], v[190:193], v[40:43]
	v_mfma_f32_16x16x32_bf16 v[28:31], v[142:145], v[198:201], v[28:31]
	v_mfma_f32_16x16x32_bf16 v[24:27], v[150:153], v[198:201], v[24:27]
	v_mfma_f32_16x16x32_bf16 v[12:15], v[142:145], v[206:209], v[12:15]
	v_mfma_f32_16x16x32_bf16 v[8:11], v[150:153], v[206:209], v[8:11]
	v_mfma_f32_16x16x32_bf16 v[60:63], v[146:149], v[186:189], v[60:63]
	v_mfma_f32_16x16x32_bf16 v[56:59], v[154:157], v[186:189], v[56:59]
	v_mfma_f32_16x16x32_bf16 v[44:47], v[146:149], v[194:197], v[44:47]
	v_mfma_f32_16x16x32_bf16 v[40:43], v[154:157], v[194:197], v[40:43]
	v_mfma_f32_16x16x32_bf16 v[28:31], v[146:149], v[202:205], v[28:31]
	v_mfma_f32_16x16x32_bf16 v[24:27], v[154:157], v[202:205], v[24:27]
	v_mfma_f32_16x16x32_bf16 v[12:15], v[146:149], v[210:213], v[12:15]
	v_mfma_f32_16x16x32_bf16 v[8:11], v[154:157], v[210:213], v[8:11]
	v_mfma_f32_16x16x32_bf16 v[52:55], v[158:161], v[182:185], v[52:55]
	v_mfma_f32_16x16x32_bf16 v[48:51], v[166:169], v[182:185], v[48:51]
	v_mfma_f32_16x16x32_bf16 v[36:39], v[158:161], v[190:193], v[36:39]
	v_mfma_f32_16x16x32_bf16 v[32:35], v[166:169], v[190:193], v[32:35]
	v_mfma_f32_16x16x32_bf16 v[20:23], v[158:161], v[198:201], v[20:23]
	v_mfma_f32_16x16x32_bf16 v[16:19], v[166:169], v[198:201], v[16:19]
	v_mfma_f32_16x16x32_bf16 v[4:7], v[158:161], v[206:209], v[4:7]
	v_mfma_f32_16x16x32_bf16 v[0:3], v[166:169], v[206:209], v[0:3]
	v_mfma_f32_16x16x32_bf16 v[52:55], v[162:165], v[186:189], v[52:55]
	v_mfma_f32_16x16x32_bf16 v[48:51], v[170:173], v[186:189], v[48:51]
	v_mfma_f32_16x16x32_bf16 v[36:39], v[162:165], v[194:197], v[36:39]
	v_mfma_f32_16x16x32_bf16 v[32:35], v[170:173], v[194:197], v[32:35]
	v_mfma_f32_16x16x32_bf16 v[20:23], v[162:165], v[202:205], v[20:23]
	v_mfma_f32_16x16x32_bf16 v[16:19], v[170:173], v[202:205], v[16:19]
	v_mfma_f32_16x16x32_bf16 v[4:7], v[162:165], v[210:213], v[4:7]
	v_mfma_f32_16x16x32_bf16 v[0:3], v[170:173], v[210:213], v[0:3]
	s_barrier
	s_add_i32 s28, 0, 0x18000
	s_add_i32 s38, 0, 0x1c000
	v_add_u32_e32 v154, s28, v140
	v_add_u32_e32 v170, s38, v140
	ds_read_b128 v[142:145], v154
	ds_read_b128 v[146:149], v154 offset:1024
	ds_read_b128 v[150:153], v154 offset:2048
	ds_read_b128 v[154:157], v154 offset:3072
	ds_read_b128 v[158:161], v170
	ds_read_b128 v[162:165], v170 offset:1024
	ds_read_b128 v[166:169], v170 offset:2048
	ds_read_b128 v[170:173], v170 offset:3072
	s_add_u32 s4, s4, s0
	s_addc_u32 s5, s5, s1
	s_mov_b32 m0, s31
	v_lshl_add_u64 v[224:225], s[4:5], 0, v[132:133]
	ds_read_b128 v[182:185], v141 offset:32768
	ds_read_b128 v[186:189], v141 offset:33792
	ds_read_b128 v[190:193], v141 offset:34816
	ds_read_b128 v[194:197], v141 offset:35840
	ds_read_b128 v[198:201], v141 offset:36864
	ds_read_b128 v[202:205], v141 offset:37888
	ds_read_b128 v[206:209], v141 offset:38912
	ds_read_b128 v[210:213], v141 offset:39936
	global_load_lds_dwordx4 v[224:225], off
	v_lshl_add_u64 v[224:225], s[4:5], 0, v[130:131]
	s_mov_b32 m0, s46
	s_nop 0
	global_load_lds_dwordx4 v[224:225], off
	s_waitcnt vmcnt(8)
	s_waitcnt lgkmcnt(0)
	s_barrier
	s_waitcnt lgkmcnt(0)
	v_mfma_f32_16x16x32_bf16 v[124:127], v[142:145], v[182:185], v[124:127]
	v_mfma_f32_16x16x32_bf16 v[120:123], v[150:153], v[182:185], v[120:123]
	v_mfma_f32_16x16x32_bf16 v[108:111], v[142:145], v[190:193], v[108:111]
	v_mfma_f32_16x16x32_bf16 v[104:107], v[150:153], v[190:193], v[104:107]
	v_mfma_f32_16x16x32_bf16 v[92:95], v[142:145], v[198:201], v[92:95]
	v_mfma_f32_16x16x32_bf16 v[88:91], v[150:153], v[198:201], v[88:91]
	v_mfma_f32_16x16x32_bf16 v[76:79], v[142:145], v[206:209], v[76:79]
	v_mfma_f32_16x16x32_bf16 v[72:75], v[150:153], v[206:209], v[72:75]
	v_mfma_f32_16x16x32_bf16 v[124:127], v[146:149], v[186:189], v[124:127]
	v_mfma_f32_16x16x32_bf16 v[120:123], v[154:157], v[186:189], v[120:123]
	v_mfma_f32_16x16x32_bf16 v[108:111], v[146:149], v[194:197], v[108:111]
	v_mfma_f32_16x16x32_bf16 v[104:107], v[154:157], v[194:197], v[104:107]
	v_mfma_f32_16x16x32_bf16 v[92:95], v[146:149], v[202:205], v[92:95]
	v_mfma_f32_16x16x32_bf16 v[88:91], v[154:157], v[202:205], v[88:91]
	v_mfma_f32_16x16x32_bf16 v[76:79], v[146:149], v[210:213], v[76:79]
	v_mfma_f32_16x16x32_bf16 v[72:75], v[154:157], v[210:213], v[72:75]
	v_mfma_f32_16x16x32_bf16 v[116:119], v[158:161], v[182:185], v[116:119]
	v_mfma_f32_16x16x32_bf16 v[112:115], v[166:169], v[182:185], v[112:115]
	v_mfma_f32_16x16x32_bf16 v[100:103], v[158:161], v[190:193], v[100:103]
	v_mfma_f32_16x16x32_bf16 v[96:99], v[166:169], v[190:193], v[96:99]
	v_mfma_f32_16x16x32_bf16 v[84:87], v[158:161], v[198:201], v[84:87]
	v_mfma_f32_16x16x32_bf16 v[80:83], v[166:169], v[198:201], v[80:83]
	v_mfma_f32_16x16x32_bf16 v[68:71], v[158:161], v[206:209], v[68:71]
	v_mfma_f32_16x16x32_bf16 v[64:67], v[166:169], v[206:209], v[64:67]
	v_mfma_f32_16x16x32_bf16 v[116:119], v[162:165], v[186:189], v[116:119]
	v_mfma_f32_16x16x32_bf16 v[112:115], v[170:173], v[186:189], v[112:115]
	v_mfma_f32_16x16x32_bf16 v[100:103], v[162:165], v[194:197], v[100:103]
	v_mfma_f32_16x16x32_bf16 v[96:99], v[170:173], v[194:197], v[96:99]
	v_mfma_f32_16x16x32_bf16 v[84:87], v[162:165], v[202:205], v[84:87]
	v_mfma_f32_16x16x32_bf16 v[80:83], v[170:173], v[202:205], v[80:83]
	v_mfma_f32_16x16x32_bf16 v[68:71], v[162:165], v[210:213], v[68:71]
	v_mfma_f32_16x16x32_bf16 v[64:67], v[170:173], v[210:213], v[64:67]
	s_barrier
; #define PG8_STAGE(bufoff, gbase, voff) do { _Pragma("unroll") for (int _i = 0; _i < 2; ++_i) \
;         __builtin_amdgcn_global_load_lds((const unsigned*)((const char*)(gbase) + (voff)[_i]), (PG8_LAS unsigned*)(lds + (bufoff) + ldsw + _i * 8192), 16, 0, 0); } while (0)
; #define PG8_LDA(dst, b, h) do { _Pragma("unroll") for (int m = 0; m < 4; ++m) _Pragma("unroll") for (int k = 0; k < 2; ++k) dst[m][k] = *(const PG8_LAS bf16x8*)(lds + PG8_SA(b, h) + aoff + m * 2048 + k * 1024); } while (0)
; #define PG8_MMA(ai, bj, At, Bt) do { __builtin_amdgcn_s_setprio(1); _Pragma("unroll") for (int m = 0; m < 4; ++m) _Pragma("unroll") for (int n = 0; n < 2; ++n) _Pragma("unroll") for (int k = 0; k < 2; ++k) \
;         acc[ai][bj][m][n] = __builtin_amdgcn_mfma_f32_16x16x32_bf16(Bt[n][k], At[m][k], acc[ai][bj][m][n], 0, 0, 0); __builtin_amdgcn_s_setprio(0); } while (0)
; #define PG8_WAIT_V(n) asm volatile("s_waitcnt vmcnt(" #n ")" ::: "memory")
; #define PG8_WAIT_L(n) asm volatile("s_waitcnt lgkmcnt(" #n ")" ::: "memory")
; #define PG8_BAR __builtin_amdgcn_s_barrier()
; #define PG8_SCHED __builtin_amdgcn_sched_barrier(0)
; template <class Epi, class Sched, bool ALIGN_EPI = false, bool SP2 = false>
; __device__ __forceinline__ void gemm_phase(PG8_LAS unsigned char* lds, const Gemm g, const Sched& S, const Epi& E) {
;     ...
;             PG8_LDA(At, 1, 1); PG8_STAGE(PG8_SB(1, 0), b3, voffB); PG8_STAGE(PG8_SB(1, 1), b3 + hstep, voffB); PG8_STAGE(PG8_SA(1, 0), a3, voffA);
;             PG8_WAIT_V(8); PG8_WAIT_L(0); PG8_BAR; PG8_MMA(1, 0, At, B0); PG8_MMA(1, 1, At, B1); PG8_BAR; PG8_SCHED;
	s_add_i32 s4, s28, s24
	v_lshl_add_u64 v[174:175], v[174:175], 0, s[44:45]
	s_mov_b32 m0, s4
	ds_read_b128 v[182:185], v141 offset:49152
	ds_read_b128 v[186:189], v141 offset:50176
	ds_read_b128 v[190:193], v141 offset:51200
	ds_read_b128 v[194:197], v141 offset:52224
	ds_read_b128 v[198:201], v141 offset:53248
	ds_read_b128 v[202:205], v141 offset:54272
	ds_read_b128 v[206:209], v141 offset:55296
	ds_read_b128 v[210:213], v141 offset:56320
	global_load_lds_dwordx4 v[174:175], off
	v_lshl_add_u64 v[174:175], v[214:215], 0, s[44:45]
	s_add_i32 m0, s4, 0x2000
	s_add_i32 s4, s38, s24
	global_load_lds_dwordx4 v[174:175], off
	v_lshl_add_u64 v[174:175], v[216:217], 0, s[44:45]
	s_mov_b32 m0, s4
	s_nop 0
	global_load_lds_dwordx4 v[174:175], off
	v_lshl_add_u64 v[174:175], v[218:219], 0, s[44:45]
	s_add_i32 m0, s4, 0x2000
	s_nop 0
	global_load_lds_dwordx4 v[174:175], off
	v_lshl_add_u64 v[174:175], v[220:221], 0, s[44:45]
	s_mov_b32 m0, s69
	s_nop 0
	global_load_lds_dwordx4 v[174:175], off
	v_lshl_add_u64 v[174:175], v[222:223], 0, s[44:45]
	s_mov_b32 m0, s70
	s_nop 0
	global_load_lds_dwordx4 v[174:175], off
	s_waitcnt vmcnt(8)
	s_waitcnt lgkmcnt(0)
	s_barrier
	s_waitcnt lgkmcnt(0)
	v_mfma_f32_16x16x32_bf16 v[60:63], v[142:145], v[182:185], v[60:63]
	v_mfma_f32_16x16x32_bf16 v[56:59], v[150:153], v[182:185], v[56:59]
	v_mfma_f32_16x16x32_bf16 v[44:47], v[142:145], v[190:193], v[44:47]
	v_mfma_f32_16x16x32_bf16 v[40:43], v[150:153], v[190:193], v[40:43]
	v_mfma_f32_16x16x32_bf16 v[28:31], v[142:145], v[198:201], v[28:31]
	v_mfma_f32_16x16x32_bf16 v[24:27], v[150:153], v[198:201], v[24:27]
	v_mfma_f32_16x16x32_bf16 v[12:15], v[142:145], v[206:209], v[12:15]
	v_mfma_f32_16x16x32_bf16 v[8:11], v[150:153], v[206:209], v[8:11]
	v_mfma_f32_16x16x32_bf16 v[60:63], v[146:149], v[186:189], v[60:63]
	v_mfma_f32_16x16x32_bf16 v[56:59], v[154:157], v[186:189], v[56:59]
	v_mfma_f32_16x16x32_bf16 v[44:47], v[146:149], v[194:197], v[44:47]
	v_mfma_f32_16x16x32_bf16 v[40:43], v[154:157], v[194:197], v[40:43]
	v_mfma_f32_16x16x32_bf16 v[28:31], v[146:149], v[202:205], v[28:31]
	v_mfma_f32_16x16x32_bf16 v[24:27], v[154:157], v[202:205], v[24:27]
	v_mfma_f32_16x16x32_bf16 v[12:15], v[146:149], v[210:213], v[12:15]
	v_mfma_f32_16x16x32_bf16 v[8:11], v[154:157], v[210:213], v[8:11]
	v_mfma_f32_16x16x32_bf16 v[52:55], v[158:161], v[182:185], v[52:55]
	v_mfma_f32_16x16x32_bf16 v[48:51], v[166:169], v[182:185], v[48:51]
	v_mfma_f32_16x16x32_bf16 v[36:39], v[158:161], v[190:193], v[36:39]
	v_mfma_f32_16x16x32_bf16 v[32:35], v[166:169], v[190:193], v[32:35]
	v_mfma_f32_16x16x32_bf16 v[20:23], v[158:161], v[198:201], v[20:23]
	v_mfma_f32_16x16x32_bf16 v[16:19], v[166:169], v[198:201], v[16:19]
	v_mfma_f32_16x16x32_bf16 v[4:7], v[158:161], v[206:209], v[4:7]
	v_mfma_f32_16x16x32_bf16 v[0:3], v[166:169], v[206:209], v[0:3]
	v_mfma_f32_16x16x32_bf16 v[52:55], v[162:165], v[186:189], v[52:55]
	v_mfma_f32_16x16x32_bf16 v[48:51], v[170:173], v[186:189], v[48:51]
	s_add_u32 s64, s64, 0x100
	v_mfma_f32_16x16x32_bf16 v[36:39], v[162:165], v[194:197], v[36:39]
	s_addc_u32 s65, s65, 0
	v_mfma_f32_16x16x32_bf16 v[32:35], v[170:173], v[194:197], v[32:35]
	s_add_u32 s66, s66, 0x100
	v_mfma_f32_16x16x32_bf16 v[20:23], v[162:165], v[202:205], v[20:23]
	s_addc_u32 s67, s67, 0
	v_mfma_f32_16x16x32_bf16 v[16:19], v[170:173], v[202:205], v[16:19]
	s_cmp_ge_i32 s83, s63
	v_mfma_f32_16x16x32_bf16 v[4:7], v[162:165], v[210:213], v[4:7]
	s_mov_b32 s4, s83
	v_mfma_f32_16x16x32_bf16 v[0:3], v[170:173], v[210:213], v[0:3]
	s_barrier
	s_cbranch_scc0 .LBB0_812
